# v54 plus merging the adjacent vmcnt(8) and lgkmcnt(0) waits before each GEMM barrier into one s_waitcnt
# speedup vs baseline: 1.0029x; 1.0029x over previous
; #define PG8_STAGE(bufoff, gbase, voff) do { _Pragma("unroll") for (int _i = 0; _i < 2; ++_i) \
;         __builtin_amdgcn_global_load_lds((const unsigned*)((const char*)(gbase) + (voff)[_i]), (LAS unsigned*)(lds + (bufoff) + ldsw + _i * 8192), 16, 0, 0); } while (0)
; #define PG8_LDA(dst, b, h) do { _Pragma("unroll") for (int m = 0; m < 4; ++m) _Pragma("unroll") for (int k = 0; k < 2; ++k) dst[m][k] = *(const LAS bf16x8*)(lds + PG8_SA(b, h) + aoff + m * 2048 + k * 1024); } while (0)
; #define PG8_LDB(dst, b, h) do { _Pragma("unroll") for (int n = 0; n < 2; ++n) _Pragma("unroll") for (int k = 0; k < 2; ++k) dst[n][k] = *(const LAS bf16x8*)(lds + PG8_SB(b, h) + boff + n * 2048 + k * 1024); } while (0)
; #define PG8_MMA(ai, bj, At, Bt) do { __builtin_amdgcn_s_setprio(1); _Pragma("unroll") for (int m = 0; m < 4; ++m) _Pragma("unroll") for (int n = 0; n < 2; ++n) _Pragma("unroll") for (int k = 0; k < 2; ++k) \
;         acc[ai][bj][m][n] = __builtin_amdgcn_mfma_f32_16x16x32_bf16(Bt[n][k], At[m][k], acc[ai][bj][m][n], 0, 0, 0); __builtin_amdgcn_s_setprio(0); } while (0)
; #define PG8_WAIT_V(n) asm volatile("s_waitcnt vmcnt(" #n ")" ::: "memory")
; #define PG8_WAIT_L(n) asm volatile("s_waitcnt lgkmcnt(" #n ")" ::: "memory")
; #define PG8_BAR __builtin_amdgcn_s_barrier()
; #define PG8_SCHED __builtin_amdgcn_sched_barrier(0)
; template <class Epi>
; DI void gemm_phase(int wv, LAS unsigned char* lds, LAS unsigned char* scr, const Sched& S, const Epi& E) {
;     ...
;         const bool has_next = S.next(ui + 1, nxt);
;         const char* nA = has_next ? S.baseA(nxt) : cA; const char* nB = has_next ? S.baseB(nxt) : cB;
;         for (int t = 0; t < nt; t += 2) {
;             const bool last = (t == nt - 2);
;             const char* a1 = cA + (size_t)(t + 1) * kstep;
;             const char* a2 = last ? nA : cA + (size_t)(t + 2) * kstep; const char* b2 = last ? nB : cB + (size_t)(t + 2) * kstep;
;             const char* a3 = a2 + kstep; const char* b3 = b2 + kstep;
;             PG8_LDB(B0, 0, 0); PG8_LDB(B1, 0, 1); PG8_SCHED; PG8_LDA(At, 0, 0); PG8_STAGE(PG8_SA(1, 1), a1 + hstepA, voffA);
;             PG8_WAIT_V(8); PG8_WAIT_L(0); PG8_BAR; PG8_MMA(0, 0, At, B0); PG8_MMA(0, 1, At, B1); PG8_BAR; PG8_SCHED;
;             PG8_LDA(At, 0, 1); PG8_STAGE(PG8_SB(0, 0), b2, voffB); PG8_STAGE(PG8_SB(0, 1), b2 + hstepB, voffB); PG8_STAGE(PG8_SA(0, 0), a2, voffA);
.LBB0_43:
	s_add_u32 s22, s20, 0xfffc0080
	s_addc_u32 s23, s21, -1
	s_add_i32 s56, 0, 0x10000
	s_cmp_eq_u32 s53, 12
	s_cselect_b32 s25, s7, s23
	s_cselect_b32 s24, s9, s22
	s_cselect_b32 s23, s13, s52
	s_cselect_b32 s22, s15, s49
	s_add_i32 s58, 0, 0x14000
	v_add_u32_e32 v156, s56, v142
	v_add_u32_e32 v172, s58, v142
	ds_read_b128 v[144:147], v156
	ds_read_b128 v[148:151], v156 offset:1024
	ds_read_b128 v[152:155], v156 offset:2048
	ds_read_b128 v[156:159], v156 offset:3072
	ds_read_b128 v[160:163], v172
	ds_read_b128 v[164:167], v172 offset:1024
	ds_read_b128 v[168:171], v172 offset:2048
	ds_read_b128 v[172:175], v172 offset:3072
	v_lshl_add_u64 v[210:211], s[20:21], 0, v[140:141]
	s_add_i32 m0, s38, 0xc000
	ds_read_b128 v[176:179], v143
	ds_read_b128 v[180:183], v143 offset:1024
	ds_read_b128 v[184:187], v143 offset:2048
	ds_read_b128 v[188:191], v143 offset:3072
	ds_read_b128 v[194:197], v143 offset:4096
	ds_read_b128 v[198:201], v143 offset:5120
	ds_read_b128 v[202:205], v143 offset:6144
	ds_read_b128 v[206:209], v143 offset:7168
	global_load_lds_dwordx4 v[210:211], off
	v_lshl_add_u64 v[210:211], s[20:21], 0, v[138:139]
	s_add_i32 m0, s38, 0xe000
	s_nop 0
	global_load_lds_dwordx4 v[210:211], off
	s_waitcnt vmcnt(8) lgkmcnt(0)
	s_barrier
	v_mfma_f32_16x16x32_bf16 v[124:127], v[144:147], v[176:179], v[124:127]
	v_mfma_f32_16x16x32_bf16 v[120:123], v[152:155], v[176:179], v[120:123]
	v_mfma_f32_16x16x32_bf16 v[116:119], v[144:147], v[184:187], v[116:119]
	v_mfma_f32_16x16x32_bf16 v[112:115], v[152:155], v[184:187], v[112:115]
	v_mfma_f32_16x16x32_bf16 v[100:103], v[144:147], v[194:197], v[100:103]
	v_mfma_f32_16x16x32_bf16 v[96:99], v[152:155], v[194:197], v[96:99]
	v_mfma_f32_16x16x32_bf16 v[84:87], v[144:147], v[202:205], v[84:87]
	v_mfma_f32_16x16x32_bf16 v[80:83], v[152:155], v[202:205], v[80:83]
	v_mfma_f32_16x16x32_bf16 v[124:127], v[148:151], v[180:183], v[124:127]
	v_mfma_f32_16x16x32_bf16 v[120:123], v[156:159], v[180:183], v[120:123]
	v_mfma_f32_16x16x32_bf16 v[116:119], v[148:151], v[188:191], v[116:119]
	v_mfma_f32_16x16x32_bf16 v[112:115], v[156:159], v[188:191], v[112:115]
	v_mfma_f32_16x16x32_bf16 v[100:103], v[148:151], v[198:201], v[100:103]
	v_mfma_f32_16x16x32_bf16 v[96:99], v[156:159], v[198:201], v[96:99]
	v_mfma_f32_16x16x32_bf16 v[84:87], v[148:151], v[206:209], v[84:87]
	v_mfma_f32_16x16x32_bf16 v[80:83], v[156:159], v[206:209], v[80:83]
	v_mfma_f32_16x16x32_bf16 v[108:111], v[160:163], v[176:179], v[108:111]
	v_mfma_f32_16x16x32_bf16 v[104:107], v[168:171], v[176:179], v[104:107]
	v_mfma_f32_16x16x32_bf16 v[92:95], v[160:163], v[184:187], v[92:95]
	v_mfma_f32_16x16x32_bf16 v[88:91], v[168:171], v[184:187], v[88:91]
	v_mfma_f32_16x16x32_bf16 v[76:79], v[160:163], v[194:197], v[76:79]
	v_mfma_f32_16x16x32_bf16 v[72:75], v[168:171], v[194:197], v[72:75]
	v_mfma_f32_16x16x32_bf16 v[68:71], v[160:163], v[202:205], v[68:71]
	v_mfma_f32_16x16x32_bf16 v[64:67], v[168:171], v[202:205], v[64:67]
	v_mfma_f32_16x16x32_bf16 v[108:111], v[164:167], v[180:183], v[108:111]
	v_mfma_f32_16x16x32_bf16 v[104:107], v[172:175], v[180:183], v[104:107]
	v_mfma_f32_16x16x32_bf16 v[92:95], v[164:167], v[188:191], v[92:95]
	v_mfma_f32_16x16x32_bf16 v[88:91], v[172:175], v[188:191], v[88:91]
	v_mfma_f32_16x16x32_bf16 v[76:79], v[164:167], v[198:201], v[76:79]
	v_mfma_f32_16x16x32_bf16 v[72:75], v[172:175], v[198:201], v[72:75]
	v_mfma_f32_16x16x32_bf16 v[68:71], v[164:167], v[206:209], v[68:71]
	v_mfma_f32_16x16x32_bf16 v[64:67], v[172:175], v[206:209], v[64:67]
	s_barrier
	s_add_i32 s56, s56, s37
	v_lshl_add_u64 v[210:211], s[22:23], 0, v[130:131]
	s_mov_b32 m0, s56
	ds_read_b128 v[176:179], v143 offset:16384
	ds_read_b128 v[180:183], v143 offset:17408
	ds_read_b128 v[184:187], v143 offset:18432
	ds_read_b128 v[188:191], v143 offset:19456
	ds_read_b128 v[194:197], v143 offset:20480
	ds_read_b128 v[198:201], v143 offset:21504
	ds_read_b128 v[202:205], v143 offset:22528
	ds_read_b128 v[206:209], v143 offset:23552
	global_load_lds_dwordx4 v[210:211], off
	s_add_i32 m0, s56, 0x2000
	s_add_u32 s56, s22, 0x40000
	v_lshl_add_u64 v[212:213], s[22:23], 0, v[134:135]
	s_addc_u32 s57, s23, 0
	s_add_i32 s58, s58, s37
	global_load_lds_dwordx4 v[212:213], off
	v_lshl_add_u64 v[214:215], s[56:57], 0, v[130:131]
	s_mov_b32 m0, s58
	v_lshl_add_u64 v[216:217], s[24:25], 0, v[132:133]
	global_load_lds_dwordx4 v[214:215], off
	v_lshl_add_u64 v[214:215], s[56:57], 0, v[134:135]
	s_add_i32 m0, s58, 0x2000
	s_nop 0
	global_load_lds_dwordx4 v[214:215], off
	v_lshl_add_u64 v[214:215], s[24:25], 0, v[128:129]
	s_mov_b32 m0, s38
	s_nop 0
	global_load_lds_dwordx4 v[214:215], off
	s_mov_b32 m0, s39
	s_nop 0
	global_load_lds_dwordx4 v[216:217], off
	s_waitcnt vmcnt(8) lgkmcnt(0)
	s_barrier
; #define PG8_STAGE(bufoff, gbase, voff) do { _Pragma("unroll") for (int _i = 0; _i < 2; ++_i) \
;         __builtin_amdgcn_global_load_lds((const unsigned*)((const char*)(gbase) + (voff)[_i]), (LAS unsigned*)(lds + (bufoff) + ldsw + _i * 8192), 16, 0, 0); } while (0)
; #define PG8_LDA(dst, b, h) do { _Pragma("unroll") for (int m = 0; m < 4; ++m) _Pragma("unroll") for (int k = 0; k < 2; ++k) dst[m][k] = *(const LAS bf16x8*)(lds + PG8_SA(b, h) + aoff + m * 2048 + k * 1024); } while (0)
; #define PG8_LDB(dst, b, h) do { _Pragma("unroll") for (int n = 0; n < 2; ++n) _Pragma("unroll") for (int k = 0; k < 2; ++k) dst[n][k] = *(const LAS bf16x8*)(lds + PG8_SB(b, h) + boff + n * 2048 + k * 1024); } while (0)
; #define PG8_MMA(ai, bj, At, Bt) do { __builtin_amdgcn_s_setprio(1); _Pragma("unroll") for (int m = 0; m < 4; ++m) _Pragma("unroll") for (int n = 0; n < 2; ++n) _Pragma("unroll") for (int k = 0; k < 2; ++k) \
;         acc[ai][bj][m][n] = __builtin_amdgcn_mfma_f32_16x16x32_bf16(Bt[n][k], At[m][k], acc[ai][bj][m][n], 0, 0, 0); __builtin_amdgcn_s_setprio(0); } while (0)
; #define PG8_WAIT_V(n) asm volatile("s_waitcnt vmcnt(" #n ")" ::: "memory")
; #define PG8_WAIT_L(n) asm volatile("s_waitcnt lgkmcnt(" #n ")" ::: "memory")
; #define PG8_BAR __builtin_amdgcn_s_barrier()
; #define PG8_SCHED __builtin_amdgcn_sched_barrier(0)
; template <class Epi>
; DI void gemm_phase(int wv, LAS unsigned char* lds, LAS unsigned char* scr, const Sched& S, const Epi& E) {
;     ...
;             PG8_WAIT_V(8); PG8_WAIT_L(0); PG8_BAR; PG8_MMA(1, 0, At, B0); PG8_MMA(1, 1, At, B1); PG8_BAR; PG8_SCHED;
;             PG8_LDB(B0, 1, 0); PG8_LDB(B1, 1, 1); PG8_SCHED; PG8_LDA(At, 1, 0); PG8_STAGE(PG8_SA(0, 1), a2 + hstepA, voffA);
;             PG8_WAIT_V(8); PG8_WAIT_L(0); PG8_BAR; PG8_MMA(0, 0, At, B0); PG8_MMA(0, 1, At, B1); PG8_BAR; PG8_SCHED;
	v_mfma_f32_16x16x32_bf16 v[60:63], v[144:147], v[176:179], v[60:63]
	v_mfma_f32_16x16x32_bf16 v[56:59], v[152:155], v[176:179], v[56:59]
	v_mfma_f32_16x16x32_bf16 v[52:55], v[144:147], v[184:187], v[52:55]
	v_mfma_f32_16x16x32_bf16 v[48:51], v[152:155], v[184:187], v[48:51]
	v_mfma_f32_16x16x32_bf16 v[36:39], v[144:147], v[194:197], v[36:39]
	v_mfma_f32_16x16x32_bf16 v[32:35], v[152:155], v[194:197], v[32:35]
	v_mfma_f32_16x16x32_bf16 v[20:23], v[144:147], v[202:205], v[20:23]
	v_mfma_f32_16x16x32_bf16 v[16:19], v[152:155], v[202:205], v[16:19]
	v_mfma_f32_16x16x32_bf16 v[60:63], v[148:151], v[180:183], v[60:63]
	v_mfma_f32_16x16x32_bf16 v[56:59], v[156:159], v[180:183], v[56:59]
	v_mfma_f32_16x16x32_bf16 v[52:55], v[148:151], v[188:191], v[52:55]
	v_mfma_f32_16x16x32_bf16 v[48:51], v[156:159], v[188:191], v[48:51]
	v_mfma_f32_16x16x32_bf16 v[36:39], v[148:151], v[198:201], v[36:39]
	v_mfma_f32_16x16x32_bf16 v[32:35], v[156:159], v[198:201], v[32:35]
	v_mfma_f32_16x16x32_bf16 v[20:23], v[148:151], v[206:209], v[20:23]
	v_mfma_f32_16x16x32_bf16 v[16:19], v[156:159], v[206:209], v[16:19]
	v_mfma_f32_16x16x32_bf16 v[44:47], v[160:163], v[176:179], v[44:47]
	v_mfma_f32_16x16x32_bf16 v[40:43], v[168:171], v[176:179], v[40:43]
	v_mfma_f32_16x16x32_bf16 v[28:31], v[160:163], v[184:187], v[28:31]
	v_mfma_f32_16x16x32_bf16 v[24:27], v[168:171], v[184:187], v[24:27]
	v_mfma_f32_16x16x32_bf16 v[12:15], v[160:163], v[194:197], v[12:15]
	v_mfma_f32_16x16x32_bf16 v[8:11], v[168:171], v[194:197], v[8:11]
	v_mfma_f32_16x16x32_bf16 v[4:7], v[160:163], v[202:205], v[4:7]
	v_mfma_f32_16x16x32_bf16 v[0:3], v[168:171], v[202:205], v[0:3]
	v_mfma_f32_16x16x32_bf16 v[44:47], v[164:167], v[180:183], v[44:47]
	v_mfma_f32_16x16x32_bf16 v[40:43], v[172:175], v[180:183], v[40:43]
	v_mfma_f32_16x16x32_bf16 v[28:31], v[164:167], v[188:191], v[28:31]
	v_mfma_f32_16x16x32_bf16 v[24:27], v[172:175], v[188:191], v[24:27]
	v_mfma_f32_16x16x32_bf16 v[12:15], v[164:167], v[198:201], v[12:15]
	v_mfma_f32_16x16x32_bf16 v[8:11], v[172:175], v[198:201], v[8:11]
	v_mfma_f32_16x16x32_bf16 v[4:7], v[164:167], v[206:209], v[4:7]
	v_mfma_f32_16x16x32_bf16 v[0:3], v[172:175], v[206:209], v[0:3]
	s_barrier
	s_add_i32 s56, 0, 0x18000
	s_add_i32 s57, 0, 0x1c000
	v_add_u32_e32 v156, s56, v142
	v_add_u32_e32 v172, s57, v142
	ds_read_b128 v[144:147], v156
	ds_read_b128 v[148:151], v156 offset:1024
	ds_read_b128 v[152:155], v156 offset:2048
	ds_read_b128 v[156:159], v156 offset:3072
	ds_read_b128 v[160:163], v172
	ds_read_b128 v[164:167], v172 offset:1024
	ds_read_b128 v[168:171], v172 offset:2048
	ds_read_b128 v[172:175], v172 offset:3072
	s_add_u32 s24, s24, 0x40000
	s_addc_u32 s25, s25, 0
	s_mov_b32 m0, s42
	v_lshl_add_u64 v[218:219], s[24:25], 0, v[128:129]
	ds_read_b128 v[176:179], v143 offset:32768
	ds_read_b128 v[180:183], v143 offset:33792
	ds_read_b128 v[184:187], v143 offset:34816
	ds_read_b128 v[188:191], v143 offset:35840
	ds_read_b128 v[194:197], v143 offset:36864
	ds_read_b128 v[198:201], v143 offset:37888
	ds_read_b128 v[202:205], v143 offset:38912
	ds_read_b128 v[206:209], v143 offset:39936
	global_load_lds_dwordx4 v[218:219], off
	v_lshl_add_u64 v[218:219], s[24:25], 0, v[132:133]
	s_mov_b32 m0, s43
	s_nop 0
	global_load_lds_dwordx4 v[218:219], off
	s_waitcnt vmcnt(8) lgkmcnt(0)
	s_barrier
	v_mfma_f32_16x16x32_bf16 v[124:127], v[144:147], v[176:179], v[124:127]
	v_mfma_f32_16x16x32_bf16 v[120:123], v[152:155], v[176:179], v[120:123]
	v_mfma_f32_16x16x32_bf16 v[116:119], v[144:147], v[184:187], v[116:119]
	v_mfma_f32_16x16x32_bf16 v[112:115], v[152:155], v[184:187], v[112:115]
	v_mfma_f32_16x16x32_bf16 v[100:103], v[144:147], v[194:197], v[100:103]
	v_mfma_f32_16x16x32_bf16 v[96:99], v[152:155], v[194:197], v[96:99]
	v_mfma_f32_16x16x32_bf16 v[84:87], v[144:147], v[202:205], v[84:87]
	v_mfma_f32_16x16x32_bf16 v[80:83], v[152:155], v[202:205], v[80:83]
	v_mfma_f32_16x16x32_bf16 v[124:127], v[148:151], v[180:183], v[124:127]
	v_mfma_f32_16x16x32_bf16 v[120:123], v[156:159], v[180:183], v[120:123]
	v_mfma_f32_16x16x32_bf16 v[116:119], v[148:151], v[188:191], v[116:119]
	v_mfma_f32_16x16x32_bf16 v[112:115], v[156:159], v[188:191], v[112:115]
	v_mfma_f32_16x16x32_bf16 v[100:103], v[148:151], v[198:201], v[100:103]
	v_mfma_f32_16x16x32_bf16 v[96:99], v[156:159], v[198:201], v[96:99]
	v_mfma_f32_16x16x32_bf16 v[84:87], v[148:151], v[206:209], v[84:87]
	v_mfma_f32_16x16x32_bf16 v[80:83], v[156:159], v[206:209], v[80:83]
	v_mfma_f32_16x16x32_bf16 v[108:111], v[160:163], v[176:179], v[108:111]
	v_mfma_f32_16x16x32_bf16 v[104:107], v[168:171], v[176:179], v[104:107]
	v_mfma_f32_16x16x32_bf16 v[92:95], v[160:163], v[184:187], v[92:95]
	v_mfma_f32_16x16x32_bf16 v[88:91], v[168:171], v[184:187], v[88:91]
	v_mfma_f32_16x16x32_bf16 v[76:79], v[160:163], v[194:197], v[76:79]
	v_mfma_f32_16x16x32_bf16 v[72:75], v[168:171], v[194:197], v[72:75]
	v_mfma_f32_16x16x32_bf16 v[68:71], v[160:163], v[202:205], v[68:71]
	v_mfma_f32_16x16x32_bf16 v[64:67], v[168:171], v[202:205], v[64:67]
	v_mfma_f32_16x16x32_bf16 v[108:111], v[164:167], v[180:183], v[108:111]
	v_mfma_f32_16x16x32_bf16 v[104:107], v[172:175], v[180:183], v[104:107]
	v_mfma_f32_16x16x32_bf16 v[92:95], v[164:167], v[188:191], v[92:95]
	v_mfma_f32_16x16x32_bf16 v[88:91], v[172:175], v[188:191], v[88:91]
	v_mfma_f32_16x16x32_bf16 v[76:79], v[164:167], v[198:201], v[76:79]
	v_mfma_f32_16x16x32_bf16 v[72:75], v[172:175], v[198:201], v[72:75]
	v_mfma_f32_16x16x32_bf16 v[68:71], v[164:167], v[206:209], v[68:71]
	v_mfma_f32_16x16x32_bf16 v[64:67], v[172:175], v[206:209], v[64:67]
	s_barrier
; #define PG8_STAGE(bufoff, gbase, voff) do { _Pragma("unroll") for (int _i = 0; _i < 2; ++_i) \
;         __builtin_amdgcn_global_load_lds((const unsigned*)((const char*)(gbase) + (voff)[_i]), (LAS unsigned*)(lds + (bufoff) + ldsw + _i * 8192), 16, 0, 0); } while (0)
; #define PG8_LDA(dst, b, h) do { _Pragma("unroll") for (int m = 0; m < 4; ++m) _Pragma("unroll") for (int k = 0; k < 2; ++k) dst[m][k] = *(const LAS bf16x8*)(lds + PG8_SA(b, h) + aoff + m * 2048 + k * 1024); } while (0)
; #define PG8_MMA(ai, bj, At, Bt) do { __builtin_amdgcn_s_setprio(1); _Pragma("unroll") for (int m = 0; m < 4; ++m) _Pragma("unroll") for (int n = 0; n < 2; ++n) _Pragma("unroll") for (int k = 0; k < 2; ++k) \
;         acc[ai][bj][m][n] = __builtin_amdgcn_mfma_f32_16x16x32_bf16(Bt[n][k], At[m][k], acc[ai][bj][m][n], 0, 0, 0); __builtin_amdgcn_s_setprio(0); } while (0)
; #define PG8_WAIT_V(n) asm volatile("s_waitcnt vmcnt(" #n ")" ::: "memory")
; #define PG8_WAIT_L(n) asm volatile("s_waitcnt lgkmcnt(" #n ")" ::: "memory")
; #define PG8_BAR __builtin_amdgcn_s_barrier()
; #define PG8_SCHED __builtin_amdgcn_sched_barrier(0)
; template <class Epi>
; DI void gemm_phase(int wv, LAS unsigned char* lds, LAS unsigned char* scr, const Sched& S, const Epi& E) {
;     ...
;             PG8_LDA(At, 1, 1); PG8_STAGE(PG8_SB(1, 0), b3, voffB); PG8_STAGE(PG8_SB(1, 1), b3 + hstepB, voffB); PG8_STAGE(PG8_SA(1, 0), a3, voffA);
;             PG8_WAIT_V(8); PG8_WAIT_L(0); PG8_BAR; PG8_MMA(1, 0, At, B0); PG8_MMA(1, 1, At, B1); PG8_BAR; PG8_SCHED;
;         }
;         if (wr == 0) PG8_BAR;
	s_add_i32 s24, s56, s37
	v_lshl_add_u64 v[210:211], v[210:211], 0, s[2:3]
	s_mov_b32 m0, s24
	ds_read_b128 v[176:179], v143 offset:49152
	ds_read_b128 v[180:183], v143 offset:50176
	ds_read_b128 v[184:187], v143 offset:51200
	ds_read_b128 v[188:191], v143 offset:52224
	ds_read_b128 v[194:197], v143 offset:53248
	ds_read_b128 v[198:201], v143 offset:54272
	ds_read_b128 v[202:205], v143 offset:55296
	ds_read_b128 v[206:209], v143 offset:56320
	global_load_lds_dwordx4 v[210:211], off
	s_add_i32 m0, s24, 0x2000
	s_add_u32 s22, s22, 0x40080
	v_lshl_add_u64 v[210:211], v[212:213], 0, s[2:3]
	s_addc_u32 s23, s23, 0
	s_add_i32 s24, s57, s37
	global_load_lds_dwordx4 v[210:211], off
	v_lshl_add_u64 v[210:211], s[22:23], 0, v[130:131]
	s_mov_b32 m0, s24
	s_nop 0
	global_load_lds_dwordx4 v[210:211], off
	v_lshl_add_u64 v[210:211], s[22:23], 0, v[134:135]
	s_add_i32 m0, s24, 0x2000
	s_nop 0
	global_load_lds_dwordx4 v[210:211], off
	v_lshl_add_u64 v[210:211], v[214:215], 0, s[2:3]
	s_mov_b32 m0, s46
	s_nop 0
	global_load_lds_dwordx4 v[210:211], off
	v_lshl_add_u64 v[210:211], v[216:217], 0, s[2:3]
	s_mov_b32 m0, s47
	s_nop 0
	global_load_lds_dwordx4 v[210:211], off
	s_waitcnt vmcnt(8) lgkmcnt(0)
	s_barrier
	v_mfma_f32_16x16x32_bf16 v[60:63], v[144:147], v[176:179], v[60:63]
	v_mfma_f32_16x16x32_bf16 v[56:59], v[152:155], v[176:179], v[56:59]
	v_mfma_f32_16x16x32_bf16 v[52:55], v[144:147], v[184:187], v[52:55]
	v_mfma_f32_16x16x32_bf16 v[48:51], v[152:155], v[184:187], v[48:51]
	v_mfma_f32_16x16x32_bf16 v[36:39], v[144:147], v[194:197], v[36:39]
	v_mfma_f32_16x16x32_bf16 v[32:35], v[152:155], v[194:197], v[32:35]
	v_mfma_f32_16x16x32_bf16 v[20:23], v[144:147], v[202:205], v[20:23]
	v_mfma_f32_16x16x32_bf16 v[16:19], v[152:155], v[202:205], v[16:19]
	v_mfma_f32_16x16x32_bf16 v[60:63], v[148:151], v[180:183], v[60:63]
	v_mfma_f32_16x16x32_bf16 v[56:59], v[156:159], v[180:183], v[56:59]
	v_mfma_f32_16x16x32_bf16 v[52:55], v[148:151], v[188:191], v[52:55]
	v_mfma_f32_16x16x32_bf16 v[48:51], v[156:159], v[188:191], v[48:51]
	v_mfma_f32_16x16x32_bf16 v[36:39], v[148:151], v[198:201], v[36:39]
	v_mfma_f32_16x16x32_bf16 v[32:35], v[156:159], v[198:201], v[32:35]
	v_mfma_f32_16x16x32_bf16 v[20:23], v[148:151], v[206:209], v[20:23]
	v_mfma_f32_16x16x32_bf16 v[16:19], v[156:159], v[206:209], v[16:19]
	v_mfma_f32_16x16x32_bf16 v[44:47], v[160:163], v[176:179], v[44:47]
	v_mfma_f32_16x16x32_bf16 v[40:43], v[168:171], v[176:179], v[40:43]
	v_mfma_f32_16x16x32_bf16 v[28:31], v[160:163], v[184:187], v[28:31]
	v_mfma_f32_16x16x32_bf16 v[24:27], v[168:171], v[184:187], v[24:27]
	v_mfma_f32_16x16x32_bf16 v[12:15], v[160:163], v[194:197], v[12:15]
	v_mfma_f32_16x16x32_bf16 v[8:11], v[168:171], v[194:197], v[8:11]
	v_mfma_f32_16x16x32_bf16 v[4:7], v[160:163], v[202:205], v[4:7]
	v_mfma_f32_16x16x32_bf16 v[0:3], v[168:171], v[202:205], v[0:3]
	v_mfma_f32_16x16x32_bf16 v[44:47], v[164:167], v[180:183], v[44:47]
	v_mfma_f32_16x16x32_bf16 v[40:43], v[172:175], v[180:183], v[40:43]
	v_mfma_f32_16x16x32_bf16 v[28:31], v[164:167], v[188:191], v[28:31]
	v_mfma_f32_16x16x32_bf16 v[24:27], v[172:175], v[188:191], v[24:27]
	v_mfma_f32_16x16x32_bf16 v[12:15], v[164:167], v[198:201], v[12:15]
	v_mfma_f32_16x16x32_bf16 v[8:11], v[172:175], v[198:201], v[8:11]
	v_mfma_f32_16x16x32_bf16 v[4:7], v[164:167], v[206:209], v[4:7]
	v_mfma_f32_16x16x32_bf16 v[0:3], v[172:175], v[206:209], v[0:3]
	s_barrier
	s_add_i32 s53, s53, 2
	s_add_u32 s49, s49, 0x100
	s_addc_u32 s52, s52, 0
	s_add_u32 s20, s20, 0x100
	s_addc_u32 s21, s21, 0
	s_cmp_gt_u32 s53, 13
	s_cbranch_scc0 .LBB0_43
	s_and_b64 vcc, exec, s[4:5]
	s_cbranch_vccz .LBB0_46
	s_barrier

; #define PG8_STAGE(bufoff, gbase, voff) do { _Pragma("unroll") for (int _i = 0; _i < 2; ++_i) \
;         __builtin_amdgcn_global_load_lds((const unsigned*)((const char*)(gbase) + (voff)[_i]), (LAS unsigned*)(lds + (bufoff) + ldsw + _i * 8192), 16, 0, 0); } while (0)
; #define PG8_LDA(dst, b, h) do { _Pragma("unroll") for (int m = 0; m < 4; ++m) _Pragma("unroll") for (int k = 0; k < 2; ++k) dst[m][k] = *(const LAS bf16x8*)(lds + PG8_SA(b, h) + aoff + m * 2048 + k * 1024); } while (0)
; #define PG8_LDB(dst, b, h) do { _Pragma("unroll") for (int n = 0; n < 2; ++n) _Pragma("unroll") for (int k = 0; k < 2; ++k) dst[n][k] = *(const LAS bf16x8*)(lds + PG8_SB(b, h) + boff + n * 2048 + k * 1024); } while (0)
; #define PG8_MMA(ai, bj, At, Bt) do { __builtin_amdgcn_s_setprio(1); _Pragma("unroll") for (int m = 0; m < 4; ++m) _Pragma("unroll") for (int n = 0; n < 2; ++n) _Pragma("unroll") for (int k = 0; k < 2; ++k) \
;         acc[ai][bj][m][n] = __builtin_amdgcn_mfma_f32_16x16x32_bf16(Bt[n][k], At[m][k], acc[ai][bj][m][n], 0, 0, 0); __builtin_amdgcn_s_setprio(0); } while (0)
; #define PG8_WAIT_V(n) asm volatile("s_waitcnt vmcnt(" #n ")" ::: "memory")
; #define PG8_WAIT_L(n) asm volatile("s_waitcnt lgkmcnt(" #n ")" ::: "memory")
; #define PG8_BAR __builtin_amdgcn_s_barrier()
; #define PG8_SCHED __builtin_amdgcn_sched_barrier(0)
; template <class Epi>
; DI void gemm_phase(int wv, LAS unsigned char* lds, LAS unsigned char* scr, const Sched& S, const Epi& E) {
;     ...
;         const bool has_next = S.next(ui + 1, nxt);
;         const char* nA = has_next ? S.baseA(nxt) : cA; const char* nB = has_next ? S.baseB(nxt) : cB;
;         for (int t = 0; t < nt; t += 2) {
;             const bool last = (t == nt - 2);
;             const char* a1 = cA + (size_t)(t + 1) * kstep;
;             const char* a2 = last ? nA : cA + (size_t)(t + 2) * kstep; const char* b2 = last ? nB : cB + (size_t)(t + 2) * kstep;
;             const char* a3 = a2 + kstep; const char* b3 = b2 + kstep;
;             PG8_LDB(B0, 0, 0); PG8_LDB(B1, 0, 1); PG8_SCHED; PG8_LDA(At, 0, 0); PG8_STAGE(PG8_SA(1, 1), a1 + hstepA, voffA);
;             PG8_WAIT_V(8); PG8_WAIT_L(0); PG8_BAR; PG8_MMA(0, 0, At, B0); PG8_MMA(0, 1, At, B1); PG8_BAR; PG8_SCHED;
;             PG8_LDA(At, 0, 1); PG8_STAGE(PG8_SB(0, 0), b2, voffB); PG8_STAGE(PG8_SB(0, 1), b2 + hstepB, voffB); PG8_STAGE(PG8_SA(0, 0), a2, voffA);
.LBB0_89:
	s_add_u32 s24, s22, 0xfffc0080
	s_addc_u32 s25, s23, -1
	s_add_i32 s58, 0, 0x10000
	s_cmp_eq_u32 s57, 12
	s_cselect_b32 s27, s15, s25
	s_cselect_b32 s26, s33, s24
	v_add_u32_e32 v145, s58, v150
	s_cselect_b32 s25, s13, s49
	s_cselect_b32 s24, s47, s48
	s_add_i32 s62, 0, 0x14000
	ds_read_b128 v[152:155], v145
	ds_read_b128 v[156:159], v145 offset:1024
	ds_read_b128 v[160:163], v145 offset:2048
	ds_read_b128 v[164:167], v145 offset:3072
	v_add_u32_e32 v145, s62, v150
	ds_read_b128 v[168:171], v145
	ds_read_b128 v[172:175], v145 offset:1024
	ds_read_b128 v[176:179], v145 offset:2048
	ds_read_b128 v[180:183], v145 offset:3072
	v_lshl_add_u64 v[148:149], s[22:23], 0, v[142:143]
	s_add_i32 m0, s36, 0xc000
	ds_read_b128 v[184:187], v151
	ds_read_b128 v[188:191], v151 offset:1024
	ds_read_b128 v[194:197], v151 offset:2048
	ds_read_b128 v[198:201], v151 offset:3072
	ds_read_b128 v[202:205], v151 offset:4096
	ds_read_b128 v[206:209], v151 offset:5120
	ds_read_b128 v[210:213], v151 offset:6144
	ds_read_b128 v[214:217], v151 offset:7168
	global_load_lds_dwordx4 v[148:149], off
	v_lshl_add_u64 v[148:149], s[22:23], 0, v[140:141]
	s_add_i32 m0, s36, 0xe000
	s_nop 0
	global_load_lds_dwordx4 v[148:149], off
	s_waitcnt vmcnt(8) lgkmcnt(0)
	s_barrier
	v_mfma_f32_16x16x32_bf16 v[124:127], v[152:155], v[184:187], v[124:127]
	v_mfma_f32_16x16x32_bf16 v[120:123], v[160:163], v[184:187], v[120:123]
	v_mfma_f32_16x16x32_bf16 v[108:111], v[152:155], v[194:197], v[108:111]
	v_mfma_f32_16x16x32_bf16 v[104:107], v[160:163], v[194:197], v[104:107]
	v_mfma_f32_16x16x32_bf16 v[92:95], v[152:155], v[202:205], v[92:95]
	v_mfma_f32_16x16x32_bf16 v[88:91], v[160:163], v[202:205], v[88:91]
	v_mfma_f32_16x16x32_bf16 v[76:79], v[152:155], v[210:213], v[76:79]
	v_mfma_f32_16x16x32_bf16 v[72:75], v[160:163], v[210:213], v[72:75]
	v_mfma_f32_16x16x32_bf16 v[124:127], v[156:159], v[188:191], v[124:127]
	v_mfma_f32_16x16x32_bf16 v[120:123], v[164:167], v[188:191], v[120:123]
	v_mfma_f32_16x16x32_bf16 v[108:111], v[156:159], v[198:201], v[108:111]
	v_mfma_f32_16x16x32_bf16 v[104:107], v[164:167], v[198:201], v[104:107]
	v_mfma_f32_16x16x32_bf16 v[92:95], v[156:159], v[206:209], v[92:95]
	v_mfma_f32_16x16x32_bf16 v[88:91], v[164:167], v[206:209], v[88:91]
	v_mfma_f32_16x16x32_bf16 v[76:79], v[156:159], v[214:217], v[76:79]
	v_mfma_f32_16x16x32_bf16 v[72:75], v[164:167], v[214:217], v[72:75]
	v_mfma_f32_16x16x32_bf16 v[116:119], v[168:171], v[184:187], v[116:119]
	v_mfma_f32_16x16x32_bf16 v[112:115], v[176:179], v[184:187], v[112:115]
	v_mfma_f32_16x16x32_bf16 v[100:103], v[168:171], v[194:197], v[100:103]
	v_mfma_f32_16x16x32_bf16 v[96:99], v[176:179], v[194:197], v[96:99]
	v_mfma_f32_16x16x32_bf16 v[84:87], v[168:171], v[202:205], v[84:87]
	v_mfma_f32_16x16x32_bf16 v[80:83], v[176:179], v[202:205], v[80:83]
	v_mfma_f32_16x16x32_bf16 v[68:71], v[168:171], v[210:213], v[68:71]
	v_mfma_f32_16x16x32_bf16 v[64:67], v[176:179], v[210:213], v[64:67]
	v_mfma_f32_16x16x32_bf16 v[116:119], v[172:175], v[188:191], v[116:119]
	v_mfma_f32_16x16x32_bf16 v[112:115], v[180:183], v[188:191], v[112:115]
	v_mfma_f32_16x16x32_bf16 v[100:103], v[172:175], v[198:201], v[100:103]
	v_mfma_f32_16x16x32_bf16 v[96:99], v[180:183], v[198:201], v[96:99]
	v_mfma_f32_16x16x32_bf16 v[84:87], v[172:175], v[206:209], v[84:87]
	v_mfma_f32_16x16x32_bf16 v[80:83], v[180:183], v[206:209], v[80:83]
	v_mfma_f32_16x16x32_bf16 v[68:71], v[172:175], v[214:217], v[68:71]
	v_mfma_f32_16x16x32_bf16 v[64:67], v[180:183], v[214:217], v[64:67]
	s_barrier
	s_add_i32 s58, s58, s35
	v_lshl_add_u64 v[148:149], s[24:25], 0, v[130:131]
	s_mov_b32 m0, s58
	ds_read_b128 v[184:187], v151 offset:16384
	ds_read_b128 v[188:191], v151 offset:17408
	ds_read_b128 v[194:197], v151 offset:18432
	ds_read_b128 v[198:201], v151 offset:19456
	ds_read_b128 v[202:205], v151 offset:20480
	ds_read_b128 v[206:209], v151 offset:21504
	ds_read_b128 v[210:213], v151 offset:22528
	ds_read_b128 v[214:217], v151 offset:23552
	global_load_lds_dwordx4 v[148:149], off
	s_add_i32 m0, s58, 0x2000
	s_add_u32 s60, s24, 0x40000
	v_lshl_add_u64 v[218:219], s[24:25], 0, v[134:135]
	s_addc_u32 s61, s25, 0
	s_add_i32 s58, s62, s35
	global_load_lds_dwordx4 v[218:219], off
	v_lshl_add_u64 v[220:221], s[60:61], 0, v[130:131]
	s_mov_b32 m0, s58
	v_lshl_add_u64 v[222:223], s[26:27], 0, v[132:133]
	global_load_lds_dwordx4 v[220:221], off
	v_lshl_add_u64 v[220:221], s[60:61], 0, v[134:135]
	s_add_i32 m0, s58, 0x2000
	s_nop 0
	global_load_lds_dwordx4 v[220:221], off
	v_lshl_add_u64 v[220:221], s[26:27], 0, v[128:129]
	s_mov_b32 m0, s36
	s_nop 0
	global_load_lds_dwordx4 v[220:221], off
	s_mov_b32 m0, s37
	s_nop 0
	global_load_lds_dwordx4 v[222:223], off
	s_waitcnt vmcnt(8) lgkmcnt(0)
	s_barrier
; #define PG8_STAGE(bufoff, gbase, voff) do { _Pragma("unroll") for (int _i = 0; _i < 2; ++_i) \
;         __builtin_amdgcn_global_load_lds((const unsigned*)((const char*)(gbase) + (voff)[_i]), (LAS unsigned*)(lds + (bufoff) + ldsw + _i * 8192), 16, 0, 0); } while (0)
; #define PG8_LDA(dst, b, h) do { _Pragma("unroll") for (int m = 0; m < 4; ++m) _Pragma("unroll") for (int k = 0; k < 2; ++k) dst[m][k] = *(const LAS bf16x8*)(lds + PG8_SA(b, h) + aoff + m * 2048 + k * 1024); } while (0)
; #define PG8_LDB(dst, b, h) do { _Pragma("unroll") for (int n = 0; n < 2; ++n) _Pragma("unroll") for (int k = 0; k < 2; ++k) dst[n][k] = *(const LAS bf16x8*)(lds + PG8_SB(b, h) + boff + n * 2048 + k * 1024); } while (0)
; #define PG8_MMA(ai, bj, At, Bt) do { __builtin_amdgcn_s_setprio(1); _Pragma("unroll") for (int m = 0; m < 4; ++m) _Pragma("unroll") for (int n = 0; n < 2; ++n) _Pragma("unroll") for (int k = 0; k < 2; ++k) \
;         acc[ai][bj][m][n] = __builtin_amdgcn_mfma_f32_16x16x32_bf16(Bt[n][k], At[m][k], acc[ai][bj][m][n], 0, 0, 0); __builtin_amdgcn_s_setprio(0); } while (0)
; #define PG8_WAIT_V(n) asm volatile("s_waitcnt vmcnt(" #n ")" ::: "memory")
; #define PG8_WAIT_L(n) asm volatile("s_waitcnt lgkmcnt(" #n ")" ::: "memory")
; #define PG8_BAR __builtin_amdgcn_s_barrier()
; #define PG8_SCHED __builtin_amdgcn_sched_barrier(0)
; template <class Epi>
; DI void gemm_phase(int wv, LAS unsigned char* lds, LAS unsigned char* scr, const Sched& S, const Epi& E) {
;     ...
;             PG8_WAIT_V(8); PG8_WAIT_L(0); PG8_BAR; PG8_MMA(1, 0, At, B0); PG8_MMA(1, 1, At, B1); PG8_BAR; PG8_SCHED;
;             PG8_LDB(B0, 1, 0); PG8_LDB(B1, 1, 1); PG8_SCHED; PG8_LDA(At, 1, 0); PG8_STAGE(PG8_SA(0, 1), a2 + hstepA, voffA);
;             PG8_WAIT_V(8); PG8_WAIT_L(0); PG8_BAR; PG8_MMA(0, 0, At, B0); PG8_MMA(0, 1, At, B1); PG8_BAR; PG8_SCHED;
	v_mfma_f32_16x16x32_bf16 v[60:63], v[152:155], v[184:187], v[60:63]
	v_mfma_f32_16x16x32_bf16 v[56:59], v[160:163], v[184:187], v[56:59]
	v_mfma_f32_16x16x32_bf16 v[44:47], v[152:155], v[194:197], v[44:47]
	v_mfma_f32_16x16x32_bf16 v[40:43], v[160:163], v[194:197], v[40:43]
	v_mfma_f32_16x16x32_bf16 v[28:31], v[152:155], v[202:205], v[28:31]
	v_mfma_f32_16x16x32_bf16 v[24:27], v[160:163], v[202:205], v[24:27]
	v_mfma_f32_16x16x32_bf16 v[12:15], v[152:155], v[210:213], v[12:15]
	v_mfma_f32_16x16x32_bf16 v[8:11], v[160:163], v[210:213], v[8:11]
	v_mfma_f32_16x16x32_bf16 v[60:63], v[156:159], v[188:191], v[60:63]
	v_mfma_f32_16x16x32_bf16 v[56:59], v[164:167], v[188:191], v[56:59]
	v_mfma_f32_16x16x32_bf16 v[44:47], v[156:159], v[198:201], v[44:47]
	v_mfma_f32_16x16x32_bf16 v[40:43], v[164:167], v[198:201], v[40:43]
	v_mfma_f32_16x16x32_bf16 v[28:31], v[156:159], v[206:209], v[28:31]
	v_mfma_f32_16x16x32_bf16 v[24:27], v[164:167], v[206:209], v[24:27]
	v_mfma_f32_16x16x32_bf16 v[12:15], v[156:159], v[214:217], v[12:15]
	v_mfma_f32_16x16x32_bf16 v[8:11], v[164:167], v[214:217], v[8:11]
	v_mfma_f32_16x16x32_bf16 v[52:55], v[168:171], v[184:187], v[52:55]
	v_mfma_f32_16x16x32_bf16 v[48:51], v[176:179], v[184:187], v[48:51]
	v_mfma_f32_16x16x32_bf16 v[36:39], v[168:171], v[194:197], v[36:39]
	v_mfma_f32_16x16x32_bf16 v[32:35], v[176:179], v[194:197], v[32:35]
	v_mfma_f32_16x16x32_bf16 v[20:23], v[168:171], v[202:205], v[20:23]
	v_mfma_f32_16x16x32_bf16 v[16:19], v[176:179], v[202:205], v[16:19]
	v_mfma_f32_16x16x32_bf16 v[4:7], v[168:171], v[210:213], v[4:7]
	v_mfma_f32_16x16x32_bf16 v[0:3], v[176:179], v[210:213], v[0:3]
	v_mfma_f32_16x16x32_bf16 v[52:55], v[172:175], v[188:191], v[52:55]
	v_mfma_f32_16x16x32_bf16 v[48:51], v[180:183], v[188:191], v[48:51]
	v_mfma_f32_16x16x32_bf16 v[36:39], v[172:175], v[198:201], v[36:39]
	v_mfma_f32_16x16x32_bf16 v[32:35], v[180:183], v[198:201], v[32:35]
	v_mfma_f32_16x16x32_bf16 v[20:23], v[172:175], v[206:209], v[20:23]
	v_mfma_f32_16x16x32_bf16 v[16:19], v[180:183], v[206:209], v[16:19]
	v_mfma_f32_16x16x32_bf16 v[4:7], v[172:175], v[214:217], v[4:7]
	v_mfma_f32_16x16x32_bf16 v[0:3], v[180:183], v[214:217], v[0:3]
	s_barrier
	s_add_i32 s58, 0, 0x18000
	v_add_u32_e32 v145, s58, v150
	s_add_i32 s60, 0, 0x1c000
	ds_read_b128 v[152:155], v145
	ds_read_b128 v[156:159], v145 offset:1024
	ds_read_b128 v[160:163], v145 offset:2048
	ds_read_b128 v[164:167], v145 offset:3072
	v_add_u32_e32 v145, s60, v150
	ds_read_b128 v[168:171], v145
	ds_read_b128 v[172:175], v145 offset:1024
	ds_read_b128 v[176:179], v145 offset:2048
	ds_read_b128 v[180:183], v145 offset:3072
	s_add_u32 s26, s26, 0x40000
	s_addc_u32 s27, s27, 0
	s_mov_b32 m0, s38
	v_lshl_add_u64 v[224:225], s[26:27], 0, v[128:129]
	ds_read_b128 v[184:187], v151 offset:32768
	ds_read_b128 v[188:191], v151 offset:33792
	ds_read_b128 v[194:197], v151 offset:34816
	ds_read_b128 v[198:201], v151 offset:35840
	ds_read_b128 v[202:205], v151 offset:36864
	ds_read_b128 v[206:209], v151 offset:37888
	ds_read_b128 v[210:213], v151 offset:38912
	ds_read_b128 v[214:217], v151 offset:39936
	global_load_lds_dwordx4 v[224:225], off
	v_lshl_add_u64 v[224:225], s[26:27], 0, v[132:133]
	s_mov_b32 m0, s39
	s_nop 0
	global_load_lds_dwordx4 v[224:225], off
	s_waitcnt vmcnt(8) lgkmcnt(0)
	s_barrier
	v_mfma_f32_16x16x32_bf16 v[124:127], v[152:155], v[184:187], v[124:127]
	v_mfma_f32_16x16x32_bf16 v[120:123], v[160:163], v[184:187], v[120:123]
	v_mfma_f32_16x16x32_bf16 v[108:111], v[152:155], v[194:197], v[108:111]
	v_mfma_f32_16x16x32_bf16 v[104:107], v[160:163], v[194:197], v[104:107]
	v_mfma_f32_16x16x32_bf16 v[92:95], v[152:155], v[202:205], v[92:95]
	v_mfma_f32_16x16x32_bf16 v[88:91], v[160:163], v[202:205], v[88:91]
	v_mfma_f32_16x16x32_bf16 v[76:79], v[152:155], v[210:213], v[76:79]
	v_mfma_f32_16x16x32_bf16 v[72:75], v[160:163], v[210:213], v[72:75]
	v_mfma_f32_16x16x32_bf16 v[124:127], v[156:159], v[188:191], v[124:127]
	v_mfma_f32_16x16x32_bf16 v[120:123], v[164:167], v[188:191], v[120:123]
	v_mfma_f32_16x16x32_bf16 v[108:111], v[156:159], v[198:201], v[108:111]
	v_mfma_f32_16x16x32_bf16 v[104:107], v[164:167], v[198:201], v[104:107]
	v_mfma_f32_16x16x32_bf16 v[92:95], v[156:159], v[206:209], v[92:95]
	v_mfma_f32_16x16x32_bf16 v[88:91], v[164:167], v[206:209], v[88:91]
	v_mfma_f32_16x16x32_bf16 v[76:79], v[156:159], v[214:217], v[76:79]
	v_mfma_f32_16x16x32_bf16 v[72:75], v[164:167], v[214:217], v[72:75]
	v_mfma_f32_16x16x32_bf16 v[116:119], v[168:171], v[184:187], v[116:119]
	v_mfma_f32_16x16x32_bf16 v[112:115], v[176:179], v[184:187], v[112:115]
	v_mfma_f32_16x16x32_bf16 v[100:103], v[168:171], v[194:197], v[100:103]
	v_mfma_f32_16x16x32_bf16 v[96:99], v[176:179], v[194:197], v[96:99]
	v_mfma_f32_16x16x32_bf16 v[84:87], v[168:171], v[202:205], v[84:87]
	v_mfma_f32_16x16x32_bf16 v[80:83], v[176:179], v[202:205], v[80:83]
	v_mfma_f32_16x16x32_bf16 v[68:71], v[168:171], v[210:213], v[68:71]
	v_mfma_f32_16x16x32_bf16 v[64:67], v[176:179], v[210:213], v[64:67]
	v_mfma_f32_16x16x32_bf16 v[116:119], v[172:175], v[188:191], v[116:119]
	v_mfma_f32_16x16x32_bf16 v[112:115], v[180:183], v[188:191], v[112:115]
	v_mfma_f32_16x16x32_bf16 v[100:103], v[172:175], v[198:201], v[100:103]
	v_mfma_f32_16x16x32_bf16 v[96:99], v[180:183], v[198:201], v[96:99]
	v_mfma_f32_16x16x32_bf16 v[84:87], v[172:175], v[206:209], v[84:87]
	v_mfma_f32_16x16x32_bf16 v[80:83], v[180:183], v[206:209], v[80:83]
	v_mfma_f32_16x16x32_bf16 v[68:71], v[172:175], v[214:217], v[68:71]
	v_mfma_f32_16x16x32_bf16 v[64:67], v[180:183], v[214:217], v[64:67]
	s_barrier
; #define PG8_STAGE(bufoff, gbase, voff) do { _Pragma("unroll") for (int _i = 0; _i < 2; ++_i) \
;         __builtin_amdgcn_global_load_lds((const unsigned*)((const char*)(gbase) + (voff)[_i]), (LAS unsigned*)(lds + (bufoff) + ldsw + _i * 8192), 16, 0, 0); } while (0)
; #define PG8_LDA(dst, b, h) do { _Pragma("unroll") for (int m = 0; m < 4; ++m) _Pragma("unroll") for (int k = 0; k < 2; ++k) dst[m][k] = *(const LAS bf16x8*)(lds + PG8_SA(b, h) + aoff + m * 2048 + k * 1024); } while (0)
; #define PG8_MMA(ai, bj, At, Bt) do { __builtin_amdgcn_s_setprio(1); _Pragma("unroll") for (int m = 0; m < 4; ++m) _Pragma("unroll") for (int n = 0; n < 2; ++n) _Pragma("unroll") for (int k = 0; k < 2; ++k) \
;         acc[ai][bj][m][n] = __builtin_amdgcn_mfma_f32_16x16x32_bf16(Bt[n][k], At[m][k], acc[ai][bj][m][n], 0, 0, 0); __builtin_amdgcn_s_setprio(0); } while (0)
; #define PG8_WAIT_V(n) asm volatile("s_waitcnt vmcnt(" #n ")" ::: "memory")
; #define PG8_WAIT_L(n) asm volatile("s_waitcnt lgkmcnt(" #n ")" ::: "memory")
; #define PG8_BAR __builtin_amdgcn_s_barrier()
; #define PG8_SCHED __builtin_amdgcn_sched_barrier(0)
; template <class Epi>
; DI void gemm_phase(int wv, LAS unsigned char* lds, LAS unsigned char* scr, const Sched& S, const Epi& E) {
;     ...
;             PG8_LDA(At, 1, 1); PG8_STAGE(PG8_SB(1, 0), b3, voffB); PG8_STAGE(PG8_SB(1, 1), b3 + hstepB, voffB); PG8_STAGE(PG8_SA(1, 0), a3, voffA);
;             PG8_WAIT_V(8); PG8_WAIT_L(0); PG8_BAR; PG8_MMA(1, 0, At, B0); PG8_MMA(1, 1, At, B1); PG8_BAR; PG8_SCHED;
;         }
;         if (wr == 0) PG8_BAR;
	s_add_i32 s26, s58, s35
	v_lshl_add_u64 v[148:149], v[148:149], 0, s[2:3]
	s_mov_b32 m0, s26
	ds_read_b128 v[184:187], v151 offset:49152
	ds_read_b128 v[188:191], v151 offset:50176
	ds_read_b128 v[194:197], v151 offset:51200
	ds_read_b128 v[198:201], v151 offset:52224
	ds_read_b128 v[202:205], v151 offset:53248
	ds_read_b128 v[206:209], v151 offset:54272
	ds_read_b128 v[210:213], v151 offset:55296
	ds_read_b128 v[214:217], v151 offset:56320
	global_load_lds_dwordx4 v[148:149], off
	s_add_i32 m0, s26, 0x2000
	s_add_u32 s24, s24, 0x40080
	v_lshl_add_u64 v[148:149], v[218:219], 0, s[2:3]
	s_addc_u32 s25, s25, 0
	s_add_i32 s26, s60, s35
	global_load_lds_dwordx4 v[148:149], off
	v_lshl_add_u64 v[148:149], s[24:25], 0, v[130:131]
	s_mov_b32 m0, s26
	s_nop 0
	global_load_lds_dwordx4 v[148:149], off
	v_lshl_add_u64 v[148:149], s[24:25], 0, v[134:135]
	s_add_i32 m0, s26, 0x2000
	s_nop 0
	global_load_lds_dwordx4 v[148:149], off
	v_lshl_add_u64 v[148:149], v[220:221], 0, s[2:3]
	s_mov_b32 m0, s42
	s_nop 0
	global_load_lds_dwordx4 v[148:149], off
	v_lshl_add_u64 v[148:149], v[222:223], 0, s[2:3]
	s_mov_b32 m0, s43
	s_nop 0
	global_load_lds_dwordx4 v[148:149], off
	s_waitcnt vmcnt(8) lgkmcnt(0)
	s_barrier
	v_mfma_f32_16x16x32_bf16 v[60:63], v[152:155], v[184:187], v[60:63]
	v_mfma_f32_16x16x32_bf16 v[56:59], v[160:163], v[184:187], v[56:59]
	v_mfma_f32_16x16x32_bf16 v[44:47], v[152:155], v[194:197], v[44:47]
	v_mfma_f32_16x16x32_bf16 v[40:43], v[160:163], v[194:197], v[40:43]
	v_mfma_f32_16x16x32_bf16 v[28:31], v[152:155], v[202:205], v[28:31]
	v_mfma_f32_16x16x32_bf16 v[24:27], v[160:163], v[202:205], v[24:27]
	v_mfma_f32_16x16x32_bf16 v[12:15], v[152:155], v[210:213], v[12:15]
	v_mfma_f32_16x16x32_bf16 v[8:11], v[160:163], v[210:213], v[8:11]
	v_mfma_f32_16x16x32_bf16 v[60:63], v[156:159], v[188:191], v[60:63]
	v_mfma_f32_16x16x32_bf16 v[56:59], v[164:167], v[188:191], v[56:59]
	v_mfma_f32_16x16x32_bf16 v[44:47], v[156:159], v[198:201], v[44:47]
	v_mfma_f32_16x16x32_bf16 v[40:43], v[164:167], v[198:201], v[40:43]
	v_mfma_f32_16x16x32_bf16 v[28:31], v[156:159], v[206:209], v[28:31]
	v_mfma_f32_16x16x32_bf16 v[24:27], v[164:167], v[206:209], v[24:27]
	v_mfma_f32_16x16x32_bf16 v[12:15], v[156:159], v[214:217], v[12:15]
	v_mfma_f32_16x16x32_bf16 v[8:11], v[164:167], v[214:217], v[8:11]
	v_mfma_f32_16x16x32_bf16 v[52:55], v[168:171], v[184:187], v[52:55]
	v_mfma_f32_16x16x32_bf16 v[48:51], v[176:179], v[184:187], v[48:51]
	v_mfma_f32_16x16x32_bf16 v[36:39], v[168:171], v[194:197], v[36:39]
	v_mfma_f32_16x16x32_bf16 v[32:35], v[176:179], v[194:197], v[32:35]
	v_mfma_f32_16x16x32_bf16 v[20:23], v[168:171], v[202:205], v[20:23]
	v_mfma_f32_16x16x32_bf16 v[16:19], v[176:179], v[202:205], v[16:19]
	v_mfma_f32_16x16x32_bf16 v[4:7], v[168:171], v[210:213], v[4:7]
	v_mfma_f32_16x16x32_bf16 v[0:3], v[176:179], v[210:213], v[0:3]
	v_mfma_f32_16x16x32_bf16 v[52:55], v[172:175], v[188:191], v[52:55]
	v_mfma_f32_16x16x32_bf16 v[48:51], v[180:183], v[188:191], v[48:51]
	v_mfma_f32_16x16x32_bf16 v[36:39], v[172:175], v[198:201], v[36:39]
	v_mfma_f32_16x16x32_bf16 v[32:35], v[180:183], v[198:201], v[32:35]
	v_mfma_f32_16x16x32_bf16 v[20:23], v[172:175], v[206:209], v[20:23]
	v_mfma_f32_16x16x32_bf16 v[16:19], v[180:183], v[206:209], v[16:19]
	v_mfma_f32_16x16x32_bf16 v[4:7], v[172:175], v[214:217], v[4:7]
	v_mfma_f32_16x16x32_bf16 v[0:3], v[180:183], v[214:217], v[0:3]
	s_barrier
	s_add_i32 s57, s57, 2
	s_add_u32 s48, s48, 0x100
	s_addc_u32 s49, s49, 0
	s_add_u32 s22, s22, 0x100
	s_addc_u32 s23, s23, 0
	s_cmp_gt_u32 s57, 13
	s_cbranch_scc0 .LBB0_89
	s_and_b64 vcc, exec, s[10:11]
	s_cbranch_vccz .LBB0_92
	s_barrier

; #define PG8_STAGE(bufoff, gbase, voff) do { _Pragma("unroll") for (int _i = 0; _i < 2; ++_i) \
;         __builtin_amdgcn_global_load_lds((const unsigned*)((const char*)(gbase) + (voff)[_i]), (LAS unsigned*)(lds + (bufoff) + ldsw + _i * 8192), 16, 0, 0); } while (0)
; #define PG8_LDA(dst, b, h) do { _Pragma("unroll") for (int m = 0; m < 4; ++m) _Pragma("unroll") for (int k = 0; k < 2; ++k) dst[m][k] = *(const LAS bf16x8*)(lds + PG8_SA(b, h) + aoff + m * 2048 + k * 1024); } while (0)
; #define PG8_LDB(dst, b, h) do { _Pragma("unroll") for (int n = 0; n < 2; ++n) _Pragma("unroll") for (int k = 0; k < 2; ++k) dst[n][k] = *(const LAS bf16x8*)(lds + PG8_SB(b, h) + boff + n * 2048 + k * 1024); } while (0)
; #define PG8_MMA(ai, bj, At, Bt) do { __builtin_amdgcn_s_setprio(1); _Pragma("unroll") for (int m = 0; m < 4; ++m) _Pragma("unroll") for (int n = 0; n < 2; ++n) _Pragma("unroll") for (int k = 0; k < 2; ++k) \
;         acc[ai][bj][m][n] = __builtin_amdgcn_mfma_f32_16x16x32_bf16(Bt[n][k], At[m][k], acc[ai][bj][m][n], 0, 0, 0); __builtin_amdgcn_s_setprio(0); } while (0)
; #define PG8_WAIT_V(n) asm volatile("s_waitcnt vmcnt(" #n ")" ::: "memory")
; #define PG8_WAIT_L(n) asm volatile("s_waitcnt lgkmcnt(" #n ")" ::: "memory")
; #define PG8_BAR __builtin_amdgcn_s_barrier()
; #define PG8_SCHED __builtin_amdgcn_sched_barrier(0)
; template <class Epi>
; DI void gemm_phase(int wv, LAS unsigned char* lds, LAS unsigned char* scr, const Sched& S, const Epi& E) {
;     ...
;         const bool has_next = S.next(ui + 1, nxt);
;         const char* nA = has_next ? S.baseA(nxt) : cA; const char* nB = has_next ? S.baseB(nxt) : cB;
;         for (int t = 0; t < nt; t += 2) {
;             const bool last = (t == nt - 2);
;             const char* a1 = cA + (size_t)(t + 1) * kstep;
;             const char* a2 = last ? nA : cA + (size_t)(t + 2) * kstep; const char* b2 = last ? nB : cB + (size_t)(t + 2) * kstep;
;             const char* a3 = a2 + kstep; const char* b3 = b2 + kstep;
;             PG8_LDB(B0, 0, 0); PG8_LDB(B1, 0, 1); PG8_SCHED; PG8_LDA(At, 0, 0); PG8_STAGE(PG8_SA(1, 1), a1 + hstepA, voffA);
;             PG8_WAIT_V(8); PG8_WAIT_L(0); PG8_BAR; PG8_MMA(0, 0, At, B0); PG8_MMA(0, 1, At, B1); PG8_BAR; PG8_SCHED;
;             PG8_LDA(At, 0, 1); PG8_STAGE(PG8_SB(0, 0), b2, voffB); PG8_STAGE(PG8_SB(0, 1), b2 + hstepB, voffB); PG8_STAGE(PG8_SA(0, 0), a2, voffA);
.LBB0_113:
	s_add_u32 s46, s44, 0xfffc0080
	s_addc_u32 s47, s45, -1
	s_add_i32 s75, 0, 0x10000
	s_cmp_eq_u32 s74, 12
	s_cselect_b32 s49, s29, s47
	s_cselect_b32 s48, s31, s46
	s_cselect_b32 s47, s35, s73
	s_cselect_b32 s46, s37, s72
	s_add_i32 s78, 0, 0x14000
	v_add_u32_e32 v156, s75, v142
	v_add_u32_e32 v172, s78, v142
	ds_read_b128 v[144:147], v156
	ds_read_b128 v[148:151], v156 offset:1024
	ds_read_b128 v[152:155], v156 offset:2048
	ds_read_b128 v[156:159], v156 offset:3072
	ds_read_b128 v[160:163], v172
	ds_read_b128 v[164:167], v172 offset:1024
	ds_read_b128 v[168:171], v172 offset:2048
	ds_read_b128 v[172:175], v172 offset:3072
	v_lshl_add_u64 v[210:211], s[44:45], 0, v[140:141]
	s_add_i32 m0, s62, 0xc000
	ds_read_b128 v[176:179], v143
	ds_read_b128 v[180:183], v143 offset:1024
	ds_read_b128 v[184:187], v143 offset:2048
	ds_read_b128 v[188:191], v143 offset:3072
	ds_read_b128 v[194:197], v143 offset:4096
	ds_read_b128 v[198:201], v143 offset:5120
	ds_read_b128 v[202:205], v143 offset:6144
	ds_read_b128 v[206:209], v143 offset:7168
	global_load_lds_dwordx4 v[210:211], off
	v_lshl_add_u64 v[210:211], s[44:45], 0, v[138:139]
	s_add_i32 m0, s62, 0xe000
	s_nop 0
	global_load_lds_dwordx4 v[210:211], off
	s_waitcnt vmcnt(8) lgkmcnt(0)
	s_barrier
	v_mfma_f32_16x16x32_bf16 v[124:127], v[144:147], v[176:179], v[124:127]
	v_mfma_f32_16x16x32_bf16 v[120:123], v[152:155], v[176:179], v[120:123]
	v_mfma_f32_16x16x32_bf16 v[116:119], v[144:147], v[184:187], v[116:119]
	v_mfma_f32_16x16x32_bf16 v[112:115], v[152:155], v[184:187], v[112:115]
	v_mfma_f32_16x16x32_bf16 v[100:103], v[144:147], v[194:197], v[100:103]
	v_mfma_f32_16x16x32_bf16 v[96:99], v[152:155], v[194:197], v[96:99]
	v_mfma_f32_16x16x32_bf16 v[84:87], v[144:147], v[202:205], v[84:87]
	v_mfma_f32_16x16x32_bf16 v[80:83], v[152:155], v[202:205], v[80:83]
	v_mfma_f32_16x16x32_bf16 v[124:127], v[148:151], v[180:183], v[124:127]
	v_mfma_f32_16x16x32_bf16 v[120:123], v[156:159], v[180:183], v[120:123]
	v_mfma_f32_16x16x32_bf16 v[116:119], v[148:151], v[188:191], v[116:119]
	v_mfma_f32_16x16x32_bf16 v[112:115], v[156:159], v[188:191], v[112:115]
	v_mfma_f32_16x16x32_bf16 v[100:103], v[148:151], v[198:201], v[100:103]
	v_mfma_f32_16x16x32_bf16 v[96:99], v[156:159], v[198:201], v[96:99]
	v_mfma_f32_16x16x32_bf16 v[84:87], v[148:151], v[206:209], v[84:87]
	v_mfma_f32_16x16x32_bf16 v[80:83], v[156:159], v[206:209], v[80:83]
	v_mfma_f32_16x16x32_bf16 v[108:111], v[160:163], v[176:179], v[108:111]
	v_mfma_f32_16x16x32_bf16 v[104:107], v[168:171], v[176:179], v[104:107]
	v_mfma_f32_16x16x32_bf16 v[92:95], v[160:163], v[184:187], v[92:95]
	v_mfma_f32_16x16x32_bf16 v[88:91], v[168:171], v[184:187], v[88:91]
	v_mfma_f32_16x16x32_bf16 v[76:79], v[160:163], v[194:197], v[76:79]
	v_mfma_f32_16x16x32_bf16 v[72:75], v[168:171], v[194:197], v[72:75]
	v_mfma_f32_16x16x32_bf16 v[68:71], v[160:163], v[202:205], v[68:71]
	v_mfma_f32_16x16x32_bf16 v[64:67], v[168:171], v[202:205], v[64:67]
	v_mfma_f32_16x16x32_bf16 v[108:111], v[164:167], v[180:183], v[108:111]
	v_mfma_f32_16x16x32_bf16 v[104:107], v[172:175], v[180:183], v[104:107]
	v_mfma_f32_16x16x32_bf16 v[92:95], v[164:167], v[188:191], v[92:95]
	v_mfma_f32_16x16x32_bf16 v[88:91], v[172:175], v[188:191], v[88:91]
	v_mfma_f32_16x16x32_bf16 v[76:79], v[164:167], v[198:201], v[76:79]
	v_mfma_f32_16x16x32_bf16 v[72:75], v[172:175], v[198:201], v[72:75]
	v_mfma_f32_16x16x32_bf16 v[68:71], v[164:167], v[206:209], v[68:71]
	v_mfma_f32_16x16x32_bf16 v[64:67], v[172:175], v[206:209], v[64:67]
	s_barrier
	s_add_i32 s75, s75, s60
	v_lshl_add_u64 v[210:211], s[46:47], 0, v[130:131]
	s_mov_b32 m0, s75
	ds_read_b128 v[176:179], v143 offset:16384
	ds_read_b128 v[180:183], v143 offset:17408
	ds_read_b128 v[184:187], v143 offset:18432
	ds_read_b128 v[188:191], v143 offset:19456
	ds_read_b128 v[194:197], v143 offset:20480
	ds_read_b128 v[198:201], v143 offset:21504
	ds_read_b128 v[202:205], v143 offset:22528
	ds_read_b128 v[206:209], v143 offset:23552
	global_load_lds_dwordx4 v[210:211], off
	s_add_i32 m0, s75, 0x2000
	s_add_u32 s76, s46, 0x40000
	v_lshl_add_u64 v[212:213], s[46:47], 0, v[134:135]
	s_addc_u32 s77, s47, 0
	s_add_i32 s75, s78, s60
	global_load_lds_dwordx4 v[212:213], off
	v_lshl_add_u64 v[214:215], s[76:77], 0, v[130:131]
	s_mov_b32 m0, s75
	v_lshl_add_u64 v[216:217], s[48:49], 0, v[132:133]
	global_load_lds_dwordx4 v[214:215], off
	v_lshl_add_u64 v[214:215], s[76:77], 0, v[134:135]
	s_add_i32 m0, s75, 0x2000
	s_nop 0
	global_load_lds_dwordx4 v[214:215], off
	v_lshl_add_u64 v[214:215], s[48:49], 0, v[128:129]
	s_mov_b32 m0, s62
	s_nop 0
	global_load_lds_dwordx4 v[214:215], off
	s_mov_b32 m0, s63
	s_nop 0
	global_load_lds_dwordx4 v[216:217], off
	s_waitcnt vmcnt(8) lgkmcnt(0)
	s_barrier
; #define PG8_STAGE(bufoff, gbase, voff) do { _Pragma("unroll") for (int _i = 0; _i < 2; ++_i) \
;         __builtin_amdgcn_global_load_lds((const unsigned*)((const char*)(gbase) + (voff)[_i]), (LAS unsigned*)(lds + (bufoff) + ldsw + _i * 8192), 16, 0, 0); } while (0)
; #define PG8_LDA(dst, b, h) do { _Pragma("unroll") for (int m = 0; m < 4; ++m) _Pragma("unroll") for (int k = 0; k < 2; ++k) dst[m][k] = *(const LAS bf16x8*)(lds + PG8_SA(b, h) + aoff + m * 2048 + k * 1024); } while (0)
; #define PG8_LDB(dst, b, h) do { _Pragma("unroll") for (int n = 0; n < 2; ++n) _Pragma("unroll") for (int k = 0; k < 2; ++k) dst[n][k] = *(const LAS bf16x8*)(lds + PG8_SB(b, h) + boff + n * 2048 + k * 1024); } while (0)
; #define PG8_MMA(ai, bj, At, Bt) do { __builtin_amdgcn_s_setprio(1); _Pragma("unroll") for (int m = 0; m < 4; ++m) _Pragma("unroll") for (int n = 0; n < 2; ++n) _Pragma("unroll") for (int k = 0; k < 2; ++k) \
;         acc[ai][bj][m][n] = __builtin_amdgcn_mfma_f32_16x16x32_bf16(Bt[n][k], At[m][k], acc[ai][bj][m][n], 0, 0, 0); __builtin_amdgcn_s_setprio(0); } while (0)
; #define PG8_WAIT_V(n) asm volatile("s_waitcnt vmcnt(" #n ")" ::: "memory")
; #define PG8_WAIT_L(n) asm volatile("s_waitcnt lgkmcnt(" #n ")" ::: "memory")
; #define PG8_BAR __builtin_amdgcn_s_barrier()
; #define PG8_SCHED __builtin_amdgcn_sched_barrier(0)
; template <class Epi>
; DI void gemm_phase(int wv, LAS unsigned char* lds, LAS unsigned char* scr, const Sched& S, const Epi& E) {
;     ...
;             PG8_WAIT_V(8); PG8_WAIT_L(0); PG8_BAR; PG8_MMA(1, 0, At, B0); PG8_MMA(1, 1, At, B1); PG8_BAR; PG8_SCHED;
;             PG8_LDB(B0, 1, 0); PG8_LDB(B1, 1, 1); PG8_SCHED; PG8_LDA(At, 1, 0); PG8_STAGE(PG8_SA(0, 1), a2 + hstepA, voffA);
;             PG8_WAIT_V(8); PG8_WAIT_L(0); PG8_BAR; PG8_MMA(0, 0, At, B0); PG8_MMA(0, 1, At, B1); PG8_BAR; PG8_SCHED;
	v_mfma_f32_16x16x32_bf16 v[60:63], v[144:147], v[176:179], v[60:63]
	v_mfma_f32_16x16x32_bf16 v[56:59], v[152:155], v[176:179], v[56:59]
	v_mfma_f32_16x16x32_bf16 v[52:55], v[144:147], v[184:187], v[52:55]
	v_mfma_f32_16x16x32_bf16 v[48:51], v[152:155], v[184:187], v[48:51]
	v_mfma_f32_16x16x32_bf16 v[36:39], v[144:147], v[194:197], v[36:39]
	v_mfma_f32_16x16x32_bf16 v[32:35], v[152:155], v[194:197], v[32:35]
	v_mfma_f32_16x16x32_bf16 v[20:23], v[144:147], v[202:205], v[20:23]
	v_mfma_f32_16x16x32_bf16 v[16:19], v[152:155], v[202:205], v[16:19]
	v_mfma_f32_16x16x32_bf16 v[60:63], v[148:151], v[180:183], v[60:63]
	v_mfma_f32_16x16x32_bf16 v[56:59], v[156:159], v[180:183], v[56:59]
	v_mfma_f32_16x16x32_bf16 v[52:55], v[148:151], v[188:191], v[52:55]
	v_mfma_f32_16x16x32_bf16 v[48:51], v[156:159], v[188:191], v[48:51]
	v_mfma_f32_16x16x32_bf16 v[36:39], v[148:151], v[198:201], v[36:39]
	v_mfma_f32_16x16x32_bf16 v[32:35], v[156:159], v[198:201], v[32:35]
	v_mfma_f32_16x16x32_bf16 v[20:23], v[148:151], v[206:209], v[20:23]
	v_mfma_f32_16x16x32_bf16 v[16:19], v[156:159], v[206:209], v[16:19]
	v_mfma_f32_16x16x32_bf16 v[44:47], v[160:163], v[176:179], v[44:47]
	v_mfma_f32_16x16x32_bf16 v[40:43], v[168:171], v[176:179], v[40:43]
	v_mfma_f32_16x16x32_bf16 v[28:31], v[160:163], v[184:187], v[28:31]
	v_mfma_f32_16x16x32_bf16 v[24:27], v[168:171], v[184:187], v[24:27]
	v_mfma_f32_16x16x32_bf16 v[12:15], v[160:163], v[194:197], v[12:15]
	v_mfma_f32_16x16x32_bf16 v[8:11], v[168:171], v[194:197], v[8:11]
	v_mfma_f32_16x16x32_bf16 v[4:7], v[160:163], v[202:205], v[4:7]
	v_mfma_f32_16x16x32_bf16 v[0:3], v[168:171], v[202:205], v[0:3]
	v_mfma_f32_16x16x32_bf16 v[44:47], v[164:167], v[180:183], v[44:47]
	v_mfma_f32_16x16x32_bf16 v[40:43], v[172:175], v[180:183], v[40:43]
	v_mfma_f32_16x16x32_bf16 v[28:31], v[164:167], v[188:191], v[28:31]
	v_mfma_f32_16x16x32_bf16 v[24:27], v[172:175], v[188:191], v[24:27]
	v_mfma_f32_16x16x32_bf16 v[12:15], v[164:167], v[198:201], v[12:15]
	v_mfma_f32_16x16x32_bf16 v[8:11], v[172:175], v[198:201], v[8:11]
	v_mfma_f32_16x16x32_bf16 v[4:7], v[164:167], v[206:209], v[4:7]
	v_mfma_f32_16x16x32_bf16 v[0:3], v[172:175], v[206:209], v[0:3]
	s_barrier
	s_add_i32 s75, 0, 0x18000
	s_add_i32 s76, 0, 0x1c000
	v_add_u32_e32 v156, s75, v142
	v_add_u32_e32 v172, s76, v142
	ds_read_b128 v[144:147], v156
	ds_read_b128 v[148:151], v156 offset:1024
	ds_read_b128 v[152:155], v156 offset:2048
	ds_read_b128 v[156:159], v156 offset:3072
	ds_read_b128 v[160:163], v172
	ds_read_b128 v[164:167], v172 offset:1024
	ds_read_b128 v[168:171], v172 offset:2048
	ds_read_b128 v[172:175], v172 offset:3072
	s_add_u32 s48, s48, 0x40000
	s_addc_u32 s49, s49, 0
	s_mov_b32 m0, s64
	v_lshl_add_u64 v[218:219], s[48:49], 0, v[128:129]
	ds_read_b128 v[176:179], v143 offset:32768
	ds_read_b128 v[180:183], v143 offset:33792
	ds_read_b128 v[184:187], v143 offset:34816
	ds_read_b128 v[188:191], v143 offset:35840
	ds_read_b128 v[194:197], v143 offset:36864
	ds_read_b128 v[198:201], v143 offset:37888
	ds_read_b128 v[202:205], v143 offset:38912
	ds_read_b128 v[206:209], v143 offset:39936
	global_load_lds_dwordx4 v[218:219], off
	v_lshl_add_u64 v[218:219], s[48:49], 0, v[132:133]
	s_mov_b32 m0, s65
	s_nop 0
	global_load_lds_dwordx4 v[218:219], off
	s_waitcnt vmcnt(8) lgkmcnt(0)
	s_barrier
	v_mfma_f32_16x16x32_bf16 v[124:127], v[144:147], v[176:179], v[124:127]
	v_mfma_f32_16x16x32_bf16 v[120:123], v[152:155], v[176:179], v[120:123]
	v_mfma_f32_16x16x32_bf16 v[116:119], v[144:147], v[184:187], v[116:119]
	v_mfma_f32_16x16x32_bf16 v[112:115], v[152:155], v[184:187], v[112:115]
	v_mfma_f32_16x16x32_bf16 v[100:103], v[144:147], v[194:197], v[100:103]
	v_mfma_f32_16x16x32_bf16 v[96:99], v[152:155], v[194:197], v[96:99]
	v_mfma_f32_16x16x32_bf16 v[84:87], v[144:147], v[202:205], v[84:87]
	v_mfma_f32_16x16x32_bf16 v[80:83], v[152:155], v[202:205], v[80:83]
	v_mfma_f32_16x16x32_bf16 v[124:127], v[148:151], v[180:183], v[124:127]
	v_mfma_f32_16x16x32_bf16 v[120:123], v[156:159], v[180:183], v[120:123]
	v_mfma_f32_16x16x32_bf16 v[116:119], v[148:151], v[188:191], v[116:119]
	v_mfma_f32_16x16x32_bf16 v[112:115], v[156:159], v[188:191], v[112:115]
	v_mfma_f32_16x16x32_bf16 v[100:103], v[148:151], v[198:201], v[100:103]
	v_mfma_f32_16x16x32_bf16 v[96:99], v[156:159], v[198:201], v[96:99]
	v_mfma_f32_16x16x32_bf16 v[84:87], v[148:151], v[206:209], v[84:87]
	v_mfma_f32_16x16x32_bf16 v[80:83], v[156:159], v[206:209], v[80:83]
	v_mfma_f32_16x16x32_bf16 v[108:111], v[160:163], v[176:179], v[108:111]
	v_mfma_f32_16x16x32_bf16 v[104:107], v[168:171], v[176:179], v[104:107]
	v_mfma_f32_16x16x32_bf16 v[92:95], v[160:163], v[184:187], v[92:95]
	v_mfma_f32_16x16x32_bf16 v[88:91], v[168:171], v[184:187], v[88:91]
	v_mfma_f32_16x16x32_bf16 v[76:79], v[160:163], v[194:197], v[76:79]
	v_mfma_f32_16x16x32_bf16 v[72:75], v[168:171], v[194:197], v[72:75]
	v_mfma_f32_16x16x32_bf16 v[68:71], v[160:163], v[202:205], v[68:71]
	v_mfma_f32_16x16x32_bf16 v[64:67], v[168:171], v[202:205], v[64:67]
	v_mfma_f32_16x16x32_bf16 v[108:111], v[164:167], v[180:183], v[108:111]
	v_mfma_f32_16x16x32_bf16 v[104:107], v[172:175], v[180:183], v[104:107]
	v_mfma_f32_16x16x32_bf16 v[92:95], v[164:167], v[188:191], v[92:95]
	v_mfma_f32_16x16x32_bf16 v[88:91], v[172:175], v[188:191], v[88:91]
	v_mfma_f32_16x16x32_bf16 v[76:79], v[164:167], v[198:201], v[76:79]
	v_mfma_f32_16x16x32_bf16 v[72:75], v[172:175], v[198:201], v[72:75]
	v_mfma_f32_16x16x32_bf16 v[68:71], v[164:167], v[206:209], v[68:71]
	v_mfma_f32_16x16x32_bf16 v[64:67], v[172:175], v[206:209], v[64:67]
	s_barrier
; #define PG8_STAGE(bufoff, gbase, voff) do { _Pragma("unroll") for (int _i = 0; _i < 2; ++_i) \
;         __builtin_amdgcn_global_load_lds((const unsigned*)((const char*)(gbase) + (voff)[_i]), (LAS unsigned*)(lds + (bufoff) + ldsw + _i * 8192), 16, 0, 0); } while (0)
; #define PG8_LDA(dst, b, h) do { _Pragma("unroll") for (int m = 0; m < 4; ++m) _Pragma("unroll") for (int k = 0; k < 2; ++k) dst[m][k] = *(const LAS bf16x8*)(lds + PG8_SA(b, h) + aoff + m * 2048 + k * 1024); } while (0)
; #define PG8_MMA(ai, bj, At, Bt) do { __builtin_amdgcn_s_setprio(1); _Pragma("unroll") for (int m = 0; m < 4; ++m) _Pragma("unroll") for (int n = 0; n < 2; ++n) _Pragma("unroll") for (int k = 0; k < 2; ++k) \
;         acc[ai][bj][m][n] = __builtin_amdgcn_mfma_f32_16x16x32_bf16(Bt[n][k], At[m][k], acc[ai][bj][m][n], 0, 0, 0); __builtin_amdgcn_s_setprio(0); } while (0)
; #define PG8_WAIT_V(n) asm volatile("s_waitcnt vmcnt(" #n ")" ::: "memory")
; #define PG8_WAIT_L(n) asm volatile("s_waitcnt lgkmcnt(" #n ")" ::: "memory")
; #define PG8_BAR __builtin_amdgcn_s_barrier()
; #define PG8_SCHED __builtin_amdgcn_sched_barrier(0)
; template <class Epi>
; DI void gemm_phase(int wv, LAS unsigned char* lds, LAS unsigned char* scr, const Sched& S, const Epi& E) {
;     ...
;             PG8_LDA(At, 1, 1); PG8_STAGE(PG8_SB(1, 0), b3, voffB); PG8_STAGE(PG8_SB(1, 1), b3 + hstepB, voffB); PG8_STAGE(PG8_SA(1, 0), a3, voffA);
;             PG8_WAIT_V(8); PG8_WAIT_L(0); PG8_BAR; PG8_MMA(1, 0, At, B0); PG8_MMA(1, 1, At, B1); PG8_BAR; PG8_SCHED;
;         }
;         if (wr == 0) PG8_BAR;
	s_add_i32 s48, s75, s60
	v_lshl_add_u64 v[210:211], v[210:211], 0, s[2:3]
	s_mov_b32 m0, s48
	ds_read_b128 v[176:179], v143 offset:49152
	ds_read_b128 v[180:183], v143 offset:50176
	ds_read_b128 v[184:187], v143 offset:51200
	ds_read_b128 v[188:191], v143 offset:52224
	ds_read_b128 v[194:197], v143 offset:53248
	ds_read_b128 v[198:201], v143 offset:54272
	ds_read_b128 v[202:205], v143 offset:55296
	ds_read_b128 v[206:209], v143 offset:56320
	global_load_lds_dwordx4 v[210:211], off
	s_add_i32 m0, s48, 0x2000
	s_add_u32 s46, s46, 0x40080
	v_lshl_add_u64 v[210:211], v[212:213], 0, s[2:3]
	s_addc_u32 s47, s47, 0
	s_add_i32 s48, s76, s60
	global_load_lds_dwordx4 v[210:211], off
	v_lshl_add_u64 v[210:211], s[46:47], 0, v[130:131]
	s_mov_b32 m0, s48
	s_nop 0
	global_load_lds_dwordx4 v[210:211], off
	v_lshl_add_u64 v[210:211], s[46:47], 0, v[134:135]
	s_add_i32 m0, s48, 0x2000
	s_nop 0
	global_load_lds_dwordx4 v[210:211], off
	v_lshl_add_u64 v[210:211], v[214:215], 0, s[2:3]
	s_mov_b32 m0, s66
	s_nop 0
	global_load_lds_dwordx4 v[210:211], off
	v_lshl_add_u64 v[210:211], v[216:217], 0, s[2:3]
	s_mov_b32 m0, s67
	s_nop 0
	global_load_lds_dwordx4 v[210:211], off
	s_waitcnt vmcnt(8) lgkmcnt(0)
	s_barrier
	v_mfma_f32_16x16x32_bf16 v[60:63], v[144:147], v[176:179], v[60:63]
	v_mfma_f32_16x16x32_bf16 v[56:59], v[152:155], v[176:179], v[56:59]
	v_mfma_f32_16x16x32_bf16 v[52:55], v[144:147], v[184:187], v[52:55]
	v_mfma_f32_16x16x32_bf16 v[48:51], v[152:155], v[184:187], v[48:51]
	v_mfma_f32_16x16x32_bf16 v[36:39], v[144:147], v[194:197], v[36:39]
	v_mfma_f32_16x16x32_bf16 v[32:35], v[152:155], v[194:197], v[32:35]
	v_mfma_f32_16x16x32_bf16 v[20:23], v[144:147], v[202:205], v[20:23]
	v_mfma_f32_16x16x32_bf16 v[16:19], v[152:155], v[202:205], v[16:19]
	v_mfma_f32_16x16x32_bf16 v[60:63], v[148:151], v[180:183], v[60:63]
	v_mfma_f32_16x16x32_bf16 v[56:59], v[156:159], v[180:183], v[56:59]
	v_mfma_f32_16x16x32_bf16 v[52:55], v[148:151], v[188:191], v[52:55]
	v_mfma_f32_16x16x32_bf16 v[48:51], v[156:159], v[188:191], v[48:51]
	v_mfma_f32_16x16x32_bf16 v[36:39], v[148:151], v[198:201], v[36:39]
	v_mfma_f32_16x16x32_bf16 v[32:35], v[156:159], v[198:201], v[32:35]
	v_mfma_f32_16x16x32_bf16 v[20:23], v[148:151], v[206:209], v[20:23]
	v_mfma_f32_16x16x32_bf16 v[16:19], v[156:159], v[206:209], v[16:19]
	v_mfma_f32_16x16x32_bf16 v[44:47], v[160:163], v[176:179], v[44:47]
	v_mfma_f32_16x16x32_bf16 v[40:43], v[168:171], v[176:179], v[40:43]
	v_mfma_f32_16x16x32_bf16 v[28:31], v[160:163], v[184:187], v[28:31]
	v_mfma_f32_16x16x32_bf16 v[24:27], v[168:171], v[184:187], v[24:27]
	v_mfma_f32_16x16x32_bf16 v[12:15], v[160:163], v[194:197], v[12:15]
	v_mfma_f32_16x16x32_bf16 v[8:11], v[168:171], v[194:197], v[8:11]
	v_mfma_f32_16x16x32_bf16 v[4:7], v[160:163], v[202:205], v[4:7]
	v_mfma_f32_16x16x32_bf16 v[0:3], v[168:171], v[202:205], v[0:3]
	v_mfma_f32_16x16x32_bf16 v[44:47], v[164:167], v[180:183], v[44:47]
	v_mfma_f32_16x16x32_bf16 v[40:43], v[172:175], v[180:183], v[40:43]
	v_mfma_f32_16x16x32_bf16 v[28:31], v[164:167], v[188:191], v[28:31]
	v_mfma_f32_16x16x32_bf16 v[24:27], v[172:175], v[188:191], v[24:27]
	v_mfma_f32_16x16x32_bf16 v[12:15], v[164:167], v[198:201], v[12:15]
	v_mfma_f32_16x16x32_bf16 v[8:11], v[172:175], v[198:201], v[8:11]
	v_mfma_f32_16x16x32_bf16 v[4:7], v[164:167], v[206:209], v[4:7]
	v_mfma_f32_16x16x32_bf16 v[0:3], v[172:175], v[206:209], v[0:3]
	s_barrier
	s_add_i32 s74, s74, 2
	s_add_u32 s72, s72, 0x100
	s_addc_u32 s73, s73, 0
	s_add_u32 s44, s44, 0x100
	s_addc_u32 s45, s45, 0
	s_cmp_gt_u32 s74, 13
	s_cbranch_scc0 .LBB0_113
	s_and_b64 vcc, exec, s[14:15]
	s_movk_i32 s74, 0x4000
	s_mov_b64 s[72:73], s[92:93]
	s_cbranch_vccz .LBB0_116
	s_barrier

; #define PG8_STAGE(bufoff, gbase, voff) do { _Pragma("unroll") for (int _i = 0; _i < 2; ++_i) \
;         __builtin_amdgcn_global_load_lds((const unsigned*)((const char*)(gbase) + (voff)[_i]), (LAS unsigned*)(lds + (bufoff) + ldsw + _i * 8192), 16, 0, 0); } while (0)
; #define PG8_LDA(dst, b, h) do { _Pragma("unroll") for (int m = 0; m < 4; ++m) _Pragma("unroll") for (int k = 0; k < 2; ++k) dst[m][k] = *(const LAS bf16x8*)(lds + PG8_SA(b, h) + aoff + m * 2048 + k * 1024); } while (0)
; #define PG8_LDB(dst, b, h) do { _Pragma("unroll") for (int n = 0; n < 2; ++n) _Pragma("unroll") for (int k = 0; k < 2; ++k) dst[n][k] = *(const LAS bf16x8*)(lds + PG8_SB(b, h) + boff + n * 2048 + k * 1024); } while (0)
; #define PG8_MMA(ai, bj, At, Bt) do { __builtin_amdgcn_s_setprio(1); _Pragma("unroll") for (int m = 0; m < 4; ++m) _Pragma("unroll") for (int n = 0; n < 2; ++n) _Pragma("unroll") for (int k = 0; k < 2; ++k) \
;         acc[ai][bj][m][n] = __builtin_amdgcn_mfma_f32_16x16x32_bf16(Bt[n][k], At[m][k], acc[ai][bj][m][n], 0, 0, 0); __builtin_amdgcn_s_setprio(0); } while (0)
; #define PG8_WAIT_V(n) asm volatile("s_waitcnt vmcnt(" #n ")" ::: "memory")
; #define PG8_WAIT_L(n) asm volatile("s_waitcnt lgkmcnt(" #n ")" ::: "memory")
; #define PG8_BAR __builtin_amdgcn_s_barrier()
; #define PG8_SCHED __builtin_amdgcn_sched_barrier(0)
; template <class Epi>
; DI void gemm_phase(int wv, LAS unsigned char* lds, LAS unsigned char* scr, const Sched& S, const Epi& E) {
;     ...
;         const bool has_next = S.next(ui + 1, nxt);
;         const char* nA = has_next ? S.baseA(nxt) : cA; const char* nB = has_next ? S.baseB(nxt) : cB;
;         for (int t = 0; t < nt; t += 2) {
;             const bool last = (t == nt - 2);
;             const char* a1 = cA + (size_t)(t + 1) * kstep;
;             const char* a2 = last ? nA : cA + (size_t)(t + 2) * kstep; const char* b2 = last ? nB : cB + (size_t)(t + 2) * kstep;
;             const char* a3 = a2 + kstep; const char* b3 = b2 + kstep;
;             PG8_LDB(B0, 0, 0); PG8_LDB(B1, 0, 1); PG8_SCHED; PG8_LDA(At, 0, 0); PG8_STAGE(PG8_SA(1, 1), a1 + hstepA, voffA);
;             PG8_WAIT_V(8); PG8_WAIT_L(0); PG8_BAR; PG8_MMA(0, 0, At, B0); PG8_MMA(0, 1, At, B1); PG8_BAR; PG8_SCHED;
;             PG8_LDA(At, 0, 1); PG8_STAGE(PG8_SB(0, 0), b2, voffB); PG8_STAGE(PG8_SB(0, 1), b2 + hstepB, voffB); PG8_STAGE(PG8_SA(0, 0), a2, voffA);
.LBB0_137:
	s_add_u32 s34, s30, 0xfffc0080
	s_addc_u32 s35, s31, -1
	s_add_i32 s65, 0, 0x10000
	s_cmp_eq_u32 s64, 12
	s_cselect_b32 s37, s25, s35
	s_cselect_b32 s36, s60, s34
	v_add_u32_e32 v143, s65, v140
	s_cselect_b32 s35, s23, s63
	s_cselect_b32 s34, s61, s62
	s_add_i32 s68, 0, 0x14000
	ds_read_b128 v[144:147], v143
	ds_read_b128 v[148:151], v143 offset:1024
	ds_read_b128 v[152:155], v143 offset:2048
	ds_read_b128 v[156:159], v143 offset:3072
	v_add_u32_e32 v143, s68, v140
	ds_read_b128 v[160:163], v143
	ds_read_b128 v[164:167], v143 offset:1024
	ds_read_b128 v[168:171], v143 offset:2048
	ds_read_b128 v[172:175], v143 offset:3072
	v_lshl_add_u64 v[210:211], s[30:31], 0, v[138:139]
	s_add_i32 m0, s17, 0xc000
	ds_read_b128 v[176:179], v142
	ds_read_b128 v[180:183], v142 offset:1024
	ds_read_b128 v[184:187], v142 offset:2048
	ds_read_b128 v[188:191], v142 offset:3072
	ds_read_b128 v[194:197], v142 offset:4096
	ds_read_b128 v[198:201], v142 offset:5120
	ds_read_b128 v[202:205], v142 offset:6144
	ds_read_b128 v[206:209], v142 offset:7168
	global_load_lds_dwordx4 v[210:211], off
	v_lshl_add_u64 v[210:211], s[30:31], 0, v[136:137]
	s_add_i32 m0, s17, 0xe000
	s_nop 0
	global_load_lds_dwordx4 v[210:211], off
	s_waitcnt vmcnt(8) lgkmcnt(0)
	s_barrier
	v_mfma_f32_16x16x32_bf16 v[124:127], v[144:147], v[176:179], v[124:127]
	v_mfma_f32_16x16x32_bf16 v[120:123], v[152:155], v[176:179], v[120:123]
	v_mfma_f32_16x16x32_bf16 v[116:119], v[144:147], v[184:187], v[116:119]
	v_mfma_f32_16x16x32_bf16 v[112:115], v[152:155], v[184:187], v[112:115]
	v_mfma_f32_16x16x32_bf16 v[100:103], v[144:147], v[194:197], v[100:103]
	v_mfma_f32_16x16x32_bf16 v[96:99], v[152:155], v[194:197], v[96:99]
	v_mfma_f32_16x16x32_bf16 v[84:87], v[144:147], v[202:205], v[84:87]
	v_mfma_f32_16x16x32_bf16 v[80:83], v[152:155], v[202:205], v[80:83]
	v_mfma_f32_16x16x32_bf16 v[124:127], v[148:151], v[180:183], v[124:127]
	v_mfma_f32_16x16x32_bf16 v[120:123], v[156:159], v[180:183], v[120:123]
	v_mfma_f32_16x16x32_bf16 v[116:119], v[148:151], v[188:191], v[116:119]
	v_mfma_f32_16x16x32_bf16 v[112:115], v[156:159], v[188:191], v[112:115]
	v_mfma_f32_16x16x32_bf16 v[100:103], v[148:151], v[198:201], v[100:103]
	v_mfma_f32_16x16x32_bf16 v[96:99], v[156:159], v[198:201], v[96:99]
	v_mfma_f32_16x16x32_bf16 v[84:87], v[148:151], v[206:209], v[84:87]
	v_mfma_f32_16x16x32_bf16 v[80:83], v[156:159], v[206:209], v[80:83]
	v_mfma_f32_16x16x32_bf16 v[108:111], v[160:163], v[176:179], v[108:111]
	v_mfma_f32_16x16x32_bf16 v[104:107], v[168:171], v[176:179], v[104:107]
	v_mfma_f32_16x16x32_bf16 v[92:95], v[160:163], v[184:187], v[92:95]
	v_mfma_f32_16x16x32_bf16 v[88:91], v[168:171], v[184:187], v[88:91]
	v_mfma_f32_16x16x32_bf16 v[76:79], v[160:163], v[194:197], v[76:79]
	v_mfma_f32_16x16x32_bf16 v[72:75], v[168:171], v[194:197], v[72:75]
	v_mfma_f32_16x16x32_bf16 v[68:71], v[160:163], v[202:205], v[68:71]
	v_mfma_f32_16x16x32_bf16 v[64:67], v[168:171], v[202:205], v[64:67]
	v_mfma_f32_16x16x32_bf16 v[108:111], v[164:167], v[180:183], v[108:111]
	v_mfma_f32_16x16x32_bf16 v[104:107], v[172:175], v[180:183], v[104:107]
	v_mfma_f32_16x16x32_bf16 v[92:95], v[164:167], v[188:191], v[92:95]
	v_mfma_f32_16x16x32_bf16 v[88:91], v[172:175], v[188:191], v[88:91]
	v_mfma_f32_16x16x32_bf16 v[76:79], v[164:167], v[198:201], v[76:79]
	v_mfma_f32_16x16x32_bf16 v[72:75], v[172:175], v[198:201], v[72:75]
	v_mfma_f32_16x16x32_bf16 v[68:71], v[164:167], v[206:209], v[68:71]
	v_mfma_f32_16x16x32_bf16 v[64:67], v[172:175], v[206:209], v[64:67]
	s_barrier
	s_add_i32 s65, s65, s39
	v_lshl_add_u64 v[210:211], s[34:35], 0, v[192:193]
	s_mov_b32 m0, s65
	ds_read_b128 v[176:179], v142 offset:16384
	ds_read_b128 v[180:183], v142 offset:17408
	ds_read_b128 v[184:187], v142 offset:18432
	ds_read_b128 v[188:191], v142 offset:19456
	ds_read_b128 v[194:197], v142 offset:20480
	ds_read_b128 v[198:201], v142 offset:21504
	ds_read_b128 v[202:205], v142 offset:22528
	ds_read_b128 v[206:209], v142 offset:23552
	global_load_lds_dwordx4 v[210:211], off
	s_add_i32 m0, s65, 0x2000
	s_add_u32 s66, s34, 0x40000
	v_lshl_add_u64 v[212:213], s[34:35], 0, v[132:133]
	s_addc_u32 s67, s35, 0
	s_add_i32 s65, s68, s39
	global_load_lds_dwordx4 v[212:213], off
	v_lshl_add_u64 v[214:215], s[66:67], 0, v[192:193]
	s_mov_b32 m0, s65
	v_lshl_add_u64 v[216:217], s[36:37], 0, v[130:131]
	global_load_lds_dwordx4 v[214:215], off
	v_lshl_add_u64 v[214:215], s[66:67], 0, v[132:133]
	s_add_i32 m0, s65, 0x2000
	s_nop 0
	global_load_lds_dwordx4 v[214:215], off
	v_lshl_add_u64 v[214:215], s[36:37], 0, v[128:129]
	s_mov_b32 m0, s17
	s_nop 0
	global_load_lds_dwordx4 v[214:215], off
	s_mov_b32 m0, s21
	s_nop 0
	global_load_lds_dwordx4 v[216:217], off
	s_waitcnt vmcnt(8) lgkmcnt(0)
	s_barrier
; #define PG8_STAGE(bufoff, gbase, voff) do { _Pragma("unroll") for (int _i = 0; _i < 2; ++_i) \
;         __builtin_amdgcn_global_load_lds((const unsigned*)((const char*)(gbase) + (voff)[_i]), (LAS unsigned*)(lds + (bufoff) + ldsw + _i * 8192), 16, 0, 0); } while (0)
; #define PG8_LDA(dst, b, h) do { _Pragma("unroll") for (int m = 0; m < 4; ++m) _Pragma("unroll") for (int k = 0; k < 2; ++k) dst[m][k] = *(const LAS bf16x8*)(lds + PG8_SA(b, h) + aoff + m * 2048 + k * 1024); } while (0)
; #define PG8_LDB(dst, b, h) do { _Pragma("unroll") for (int n = 0; n < 2; ++n) _Pragma("unroll") for (int k = 0; k < 2; ++k) dst[n][k] = *(const LAS bf16x8*)(lds + PG8_SB(b, h) + boff + n * 2048 + k * 1024); } while (0)
; #define PG8_MMA(ai, bj, At, Bt) do { __builtin_amdgcn_s_setprio(1); _Pragma("unroll") for (int m = 0; m < 4; ++m) _Pragma("unroll") for (int n = 0; n < 2; ++n) _Pragma("unroll") for (int k = 0; k < 2; ++k) \
;         acc[ai][bj][m][n] = __builtin_amdgcn_mfma_f32_16x16x32_bf16(Bt[n][k], At[m][k], acc[ai][bj][m][n], 0, 0, 0); __builtin_amdgcn_s_setprio(0); } while (0)
; #define PG8_WAIT_V(n) asm volatile("s_waitcnt vmcnt(" #n ")" ::: "memory")
; #define PG8_WAIT_L(n) asm volatile("s_waitcnt lgkmcnt(" #n ")" ::: "memory")
; #define PG8_BAR __builtin_amdgcn_s_barrier()
; #define PG8_SCHED __builtin_amdgcn_sched_barrier(0)
; template <class Epi>
; DI void gemm_phase(int wv, LAS unsigned char* lds, LAS unsigned char* scr, const Sched& S, const Epi& E) {
;     ...
;             PG8_WAIT_V(8); PG8_WAIT_L(0); PG8_BAR; PG8_MMA(1, 0, At, B0); PG8_MMA(1, 1, At, B1); PG8_BAR; PG8_SCHED;
;             PG8_LDB(B0, 1, 0); PG8_LDB(B1, 1, 1); PG8_SCHED; PG8_LDA(At, 1, 0); PG8_STAGE(PG8_SA(0, 1), a2 + hstepA, voffA);
;             PG8_WAIT_V(8); PG8_WAIT_L(0); PG8_BAR; PG8_MMA(0, 0, At, B0); PG8_MMA(0, 1, At, B1); PG8_BAR; PG8_SCHED;
	v_mfma_f32_16x16x32_bf16 v[60:63], v[144:147], v[176:179], v[60:63]
	v_mfma_f32_16x16x32_bf16 v[56:59], v[152:155], v[176:179], v[56:59]
	v_mfma_f32_16x16x32_bf16 v[52:55], v[144:147], v[184:187], v[52:55]
	v_mfma_f32_16x16x32_bf16 v[48:51], v[152:155], v[184:187], v[48:51]
	v_mfma_f32_16x16x32_bf16 v[36:39], v[144:147], v[194:197], v[36:39]
	v_mfma_f32_16x16x32_bf16 v[32:35], v[152:155], v[194:197], v[32:35]
	v_mfma_f32_16x16x32_bf16 v[20:23], v[144:147], v[202:205], v[20:23]
	v_mfma_f32_16x16x32_bf16 v[16:19], v[152:155], v[202:205], v[16:19]
	v_mfma_f32_16x16x32_bf16 v[60:63], v[148:151], v[180:183], v[60:63]
	v_mfma_f32_16x16x32_bf16 v[56:59], v[156:159], v[180:183], v[56:59]
	v_mfma_f32_16x16x32_bf16 v[52:55], v[148:151], v[188:191], v[52:55]
	v_mfma_f32_16x16x32_bf16 v[48:51], v[156:159], v[188:191], v[48:51]
	v_mfma_f32_16x16x32_bf16 v[36:39], v[148:151], v[198:201], v[36:39]
	v_mfma_f32_16x16x32_bf16 v[32:35], v[156:159], v[198:201], v[32:35]
	v_mfma_f32_16x16x32_bf16 v[20:23], v[148:151], v[206:209], v[20:23]
	v_mfma_f32_16x16x32_bf16 v[16:19], v[156:159], v[206:209], v[16:19]
	v_mfma_f32_16x16x32_bf16 v[44:47], v[160:163], v[176:179], v[44:47]
	v_mfma_f32_16x16x32_bf16 v[40:43], v[168:171], v[176:179], v[40:43]
	v_mfma_f32_16x16x32_bf16 v[28:31], v[160:163], v[184:187], v[28:31]
	v_mfma_f32_16x16x32_bf16 v[24:27], v[168:171], v[184:187], v[24:27]
	v_mfma_f32_16x16x32_bf16 v[12:15], v[160:163], v[194:197], v[12:15]
	v_mfma_f32_16x16x32_bf16 v[8:11], v[168:171], v[194:197], v[8:11]
	v_mfma_f32_16x16x32_bf16 v[4:7], v[160:163], v[202:205], v[4:7]
	v_mfma_f32_16x16x32_bf16 v[0:3], v[168:171], v[202:205], v[0:3]
	v_mfma_f32_16x16x32_bf16 v[44:47], v[164:167], v[180:183], v[44:47]
	v_mfma_f32_16x16x32_bf16 v[40:43], v[172:175], v[180:183], v[40:43]
	v_mfma_f32_16x16x32_bf16 v[28:31], v[164:167], v[188:191], v[28:31]
	v_mfma_f32_16x16x32_bf16 v[24:27], v[172:175], v[188:191], v[24:27]
	v_mfma_f32_16x16x32_bf16 v[12:15], v[164:167], v[198:201], v[12:15]
	v_mfma_f32_16x16x32_bf16 v[8:11], v[172:175], v[198:201], v[8:11]
	v_mfma_f32_16x16x32_bf16 v[4:7], v[164:167], v[206:209], v[4:7]
	v_mfma_f32_16x16x32_bf16 v[0:3], v[172:175], v[206:209], v[0:3]
	s_barrier
	s_add_i32 s65, 0, 0x18000
	v_add_u32_e32 v143, s65, v140
	s_add_i32 s66, 0, 0x1c000
	ds_read_b128 v[144:147], v143
	ds_read_b128 v[148:151], v143 offset:1024
	ds_read_b128 v[152:155], v143 offset:2048
	ds_read_b128 v[156:159], v143 offset:3072
	v_add_u32_e32 v143, s66, v140
	ds_read_b128 v[160:163], v143
	ds_read_b128 v[164:167], v143 offset:1024
	ds_read_b128 v[168:171], v143 offset:2048
	ds_read_b128 v[172:175], v143 offset:3072
	s_add_u32 s36, s36, 0x40000
	s_addc_u32 s37, s37, 0
	s_mov_b32 m0, s42
	v_lshl_add_u64 v[218:219], s[36:37], 0, v[128:129]
	ds_read_b128 v[176:179], v142 offset:32768
	ds_read_b128 v[180:183], v142 offset:33792
	ds_read_b128 v[184:187], v142 offset:34816
	ds_read_b128 v[188:191], v142 offset:35840
	ds_read_b128 v[194:197], v142 offset:36864
	ds_read_b128 v[198:201], v142 offset:37888
	ds_read_b128 v[202:205], v142 offset:38912
	ds_read_b128 v[206:209], v142 offset:39936
	global_load_lds_dwordx4 v[218:219], off
	v_lshl_add_u64 v[218:219], s[36:37], 0, v[130:131]
	s_mov_b32 m0, s43
	s_nop 0
	global_load_lds_dwordx4 v[218:219], off
	s_waitcnt vmcnt(8) lgkmcnt(0)
	s_barrier
	v_mfma_f32_16x16x32_bf16 v[124:127], v[144:147], v[176:179], v[124:127]
	v_mfma_f32_16x16x32_bf16 v[120:123], v[152:155], v[176:179], v[120:123]
	v_mfma_f32_16x16x32_bf16 v[116:119], v[144:147], v[184:187], v[116:119]
	v_mfma_f32_16x16x32_bf16 v[112:115], v[152:155], v[184:187], v[112:115]
	v_mfma_f32_16x16x32_bf16 v[100:103], v[144:147], v[194:197], v[100:103]
	v_mfma_f32_16x16x32_bf16 v[96:99], v[152:155], v[194:197], v[96:99]
	v_mfma_f32_16x16x32_bf16 v[84:87], v[144:147], v[202:205], v[84:87]
	v_mfma_f32_16x16x32_bf16 v[80:83], v[152:155], v[202:205], v[80:83]
	v_mfma_f32_16x16x32_bf16 v[124:127], v[148:151], v[180:183], v[124:127]
	v_mfma_f32_16x16x32_bf16 v[120:123], v[156:159], v[180:183], v[120:123]
	v_mfma_f32_16x16x32_bf16 v[116:119], v[148:151], v[188:191], v[116:119]
	v_mfma_f32_16x16x32_bf16 v[112:115], v[156:159], v[188:191], v[112:115]
	v_mfma_f32_16x16x32_bf16 v[100:103], v[148:151], v[198:201], v[100:103]
	v_mfma_f32_16x16x32_bf16 v[96:99], v[156:159], v[198:201], v[96:99]
	v_mfma_f32_16x16x32_bf16 v[84:87], v[148:151], v[206:209], v[84:87]
	v_mfma_f32_16x16x32_bf16 v[80:83], v[156:159], v[206:209], v[80:83]
	v_mfma_f32_16x16x32_bf16 v[108:111], v[160:163], v[176:179], v[108:111]
	v_mfma_f32_16x16x32_bf16 v[104:107], v[168:171], v[176:179], v[104:107]
	v_mfma_f32_16x16x32_bf16 v[92:95], v[160:163], v[184:187], v[92:95]
	v_mfma_f32_16x16x32_bf16 v[88:91], v[168:171], v[184:187], v[88:91]
	v_mfma_f32_16x16x32_bf16 v[76:79], v[160:163], v[194:197], v[76:79]
	v_mfma_f32_16x16x32_bf16 v[72:75], v[168:171], v[194:197], v[72:75]
	v_mfma_f32_16x16x32_bf16 v[68:71], v[160:163], v[202:205], v[68:71]
	v_mfma_f32_16x16x32_bf16 v[64:67], v[168:171], v[202:205], v[64:67]
	v_mfma_f32_16x16x32_bf16 v[108:111], v[164:167], v[180:183], v[108:111]
	v_mfma_f32_16x16x32_bf16 v[104:107], v[172:175], v[180:183], v[104:107]
	v_mfma_f32_16x16x32_bf16 v[92:95], v[164:167], v[188:191], v[92:95]
	v_mfma_f32_16x16x32_bf16 v[88:91], v[172:175], v[188:191], v[88:91]
	v_mfma_f32_16x16x32_bf16 v[76:79], v[164:167], v[198:201], v[76:79]
	v_mfma_f32_16x16x32_bf16 v[72:75], v[172:175], v[198:201], v[72:75]
	v_mfma_f32_16x16x32_bf16 v[68:71], v[164:167], v[206:209], v[68:71]
	v_mfma_f32_16x16x32_bf16 v[64:67], v[172:175], v[206:209], v[64:67]
	s_barrier
; #define PG8_STAGE(bufoff, gbase, voff) do { _Pragma("unroll") for (int _i = 0; _i < 2; ++_i) \
;         __builtin_amdgcn_global_load_lds((const unsigned*)((const char*)(gbase) + (voff)[_i]), (LAS unsigned*)(lds + (bufoff) + ldsw + _i * 8192), 16, 0, 0); } while (0)
; #define PG8_LDA(dst, b, h) do { _Pragma("unroll") for (int m = 0; m < 4; ++m) _Pragma("unroll") for (int k = 0; k < 2; ++k) dst[m][k] = *(const LAS bf16x8*)(lds + PG8_SA(b, h) + aoff + m * 2048 + k * 1024); } while (0)
; #define PG8_MMA(ai, bj, At, Bt) do { __builtin_amdgcn_s_setprio(1); _Pragma("unroll") for (int m = 0; m < 4; ++m) _Pragma("unroll") for (int n = 0; n < 2; ++n) _Pragma("unroll") for (int k = 0; k < 2; ++k) \
;         acc[ai][bj][m][n] = __builtin_amdgcn_mfma_f32_16x16x32_bf16(Bt[n][k], At[m][k], acc[ai][bj][m][n], 0, 0, 0); __builtin_amdgcn_s_setprio(0); } while (0)
; #define PG8_WAIT_V(n) asm volatile("s_waitcnt vmcnt(" #n ")" ::: "memory")
; #define PG8_WAIT_L(n) asm volatile("s_waitcnt lgkmcnt(" #n ")" ::: "memory")
; #define PG8_BAR __builtin_amdgcn_s_barrier()
; #define PG8_SCHED __builtin_amdgcn_sched_barrier(0)
; template <class Epi>
; DI void gemm_phase(int wv, LAS unsigned char* lds, LAS unsigned char* scr, const Sched& S, const Epi& E) {
;     ...
;             PG8_LDA(At, 1, 1); PG8_STAGE(PG8_SB(1, 0), b3, voffB); PG8_STAGE(PG8_SB(1, 1), b3 + hstepB, voffB); PG8_STAGE(PG8_SA(1, 0), a3, voffA);
;             PG8_WAIT_V(8); PG8_WAIT_L(0); PG8_BAR; PG8_MMA(1, 0, At, B0); PG8_MMA(1, 1, At, B1); PG8_BAR; PG8_SCHED;
;         }
;         if (wr == 0) PG8_BAR;
	s_add_i32 s36, s65, s39
	v_lshl_add_u64 v[210:211], v[210:211], 0, s[2:3]
	s_mov_b32 m0, s36
	ds_read_b128 v[176:179], v142 offset:49152
	ds_read_b128 v[180:183], v142 offset:50176
	ds_read_b128 v[184:187], v142 offset:51200
	ds_read_b128 v[188:191], v142 offset:52224
	ds_read_b128 v[194:197], v142 offset:53248
	ds_read_b128 v[198:201], v142 offset:54272
	ds_read_b128 v[202:205], v142 offset:55296
	ds_read_b128 v[206:209], v142 offset:56320
	global_load_lds_dwordx4 v[210:211], off
	s_add_i32 m0, s36, 0x2000
	s_add_u32 s34, s34, 0x40080
	v_lshl_add_u64 v[210:211], v[212:213], 0, s[2:3]
	s_addc_u32 s35, s35, 0
	s_add_i32 s36, s66, s39
	global_load_lds_dwordx4 v[210:211], off
	v_lshl_add_u64 v[210:211], s[34:35], 0, v[192:193]
	s_mov_b32 m0, s36
	s_nop 0
	global_load_lds_dwordx4 v[210:211], off
	v_lshl_add_u64 v[210:211], s[34:35], 0, v[132:133]
	s_add_i32 m0, s36, 0x2000
	s_nop 0
	global_load_lds_dwordx4 v[210:211], off
	v_lshl_add_u64 v[210:211], v[214:215], 0, s[2:3]
	s_mov_b32 m0, s44
	s_nop 0
	global_load_lds_dwordx4 v[210:211], off
	v_lshl_add_u64 v[210:211], v[216:217], 0, s[2:3]
	s_mov_b32 m0, s45
	s_nop 0
	global_load_lds_dwordx4 v[210:211], off
	s_waitcnt vmcnt(8) lgkmcnt(0)
	s_barrier
	v_mfma_f32_16x16x32_bf16 v[60:63], v[144:147], v[176:179], v[60:63]
	v_mfma_f32_16x16x32_bf16 v[56:59], v[152:155], v[176:179], v[56:59]
	v_mfma_f32_16x16x32_bf16 v[52:55], v[144:147], v[184:187], v[52:55]
	v_mfma_f32_16x16x32_bf16 v[48:51], v[152:155], v[184:187], v[48:51]
	v_mfma_f32_16x16x32_bf16 v[36:39], v[144:147], v[194:197], v[36:39]
	v_mfma_f32_16x16x32_bf16 v[32:35], v[152:155], v[194:197], v[32:35]
	v_mfma_f32_16x16x32_bf16 v[20:23], v[144:147], v[202:205], v[20:23]
	v_mfma_f32_16x16x32_bf16 v[16:19], v[152:155], v[202:205], v[16:19]
	v_mfma_f32_16x16x32_bf16 v[60:63], v[148:151], v[180:183], v[60:63]
	v_mfma_f32_16x16x32_bf16 v[56:59], v[156:159], v[180:183], v[56:59]
	v_mfma_f32_16x16x32_bf16 v[52:55], v[148:151], v[188:191], v[52:55]
	v_mfma_f32_16x16x32_bf16 v[48:51], v[156:159], v[188:191], v[48:51]
	v_mfma_f32_16x16x32_bf16 v[36:39], v[148:151], v[198:201], v[36:39]
	v_mfma_f32_16x16x32_bf16 v[32:35], v[156:159], v[198:201], v[32:35]
	v_mfma_f32_16x16x32_bf16 v[20:23], v[148:151], v[206:209], v[20:23]
	v_mfma_f32_16x16x32_bf16 v[16:19], v[156:159], v[206:209], v[16:19]
	v_mfma_f32_16x16x32_bf16 v[44:47], v[160:163], v[176:179], v[44:47]
	v_mfma_f32_16x16x32_bf16 v[40:43], v[168:171], v[176:179], v[40:43]
	v_mfma_f32_16x16x32_bf16 v[28:31], v[160:163], v[184:187], v[28:31]
	v_mfma_f32_16x16x32_bf16 v[24:27], v[168:171], v[184:187], v[24:27]
	v_mfma_f32_16x16x32_bf16 v[12:15], v[160:163], v[194:197], v[12:15]
	v_mfma_f32_16x16x32_bf16 v[8:11], v[168:171], v[194:197], v[8:11]
	v_mfma_f32_16x16x32_bf16 v[4:7], v[160:163], v[202:205], v[4:7]
	v_mfma_f32_16x16x32_bf16 v[0:3], v[168:171], v[202:205], v[0:3]
	v_mfma_f32_16x16x32_bf16 v[44:47], v[164:167], v[180:183], v[44:47]
	v_mfma_f32_16x16x32_bf16 v[40:43], v[172:175], v[180:183], v[40:43]
	v_mfma_f32_16x16x32_bf16 v[28:31], v[164:167], v[188:191], v[28:31]
	v_mfma_f32_16x16x32_bf16 v[24:27], v[172:175], v[188:191], v[24:27]
	v_mfma_f32_16x16x32_bf16 v[12:15], v[164:167], v[198:201], v[12:15]
	v_mfma_f32_16x16x32_bf16 v[8:11], v[172:175], v[198:201], v[8:11]
	v_mfma_f32_16x16x32_bf16 v[4:7], v[164:167], v[206:209], v[4:7]
	v_mfma_f32_16x16x32_bf16 v[0:3], v[172:175], v[206:209], v[0:3]
	s_barrier
	s_add_i32 s64, s64, 2
	s_add_u32 s62, s62, 0x100
	s_addc_u32 s63, s63, 0
	s_add_u32 s30, s30, 0x100
	s_addc_u32 s31, s31, 0
	s_cmp_gt_u32 s64, 13
	s_cbranch_scc0 .LBB0_137
	s_and_b64 vcc, exec, s[18:19]
	s_cbranch_vccz .LBB0_140
	s_barrier

; #define PG8_STAGE(bufoff, gbase, voff) do { _Pragma("unroll") for (int _i = 0; _i < 2; ++_i) \
;         __builtin_amdgcn_global_load_lds((const unsigned*)((const char*)(gbase) + (voff)[_i]), (LAS unsigned*)(lds + (bufoff) + ldsw + _i * 8192), 16, 0, 0); } while (0)
; #define PG8_LDA(dst, b, h) do { _Pragma("unroll") for (int m = 0; m < 4; ++m) _Pragma("unroll") for (int k = 0; k < 2; ++k) dst[m][k] = *(const LAS bf16x8*)(lds + PG8_SA(b, h) + aoff + m * 2048 + k * 1024); } while (0)
; #define PG8_LDB(dst, b, h) do { _Pragma("unroll") for (int n = 0; n < 2; ++n) _Pragma("unroll") for (int k = 0; k < 2; ++k) dst[n][k] = *(const LAS bf16x8*)(lds + PG8_SB(b, h) + boff + n * 2048 + k * 1024); } while (0)
; #define PG8_MMA(ai, bj, At, Bt) do { __builtin_amdgcn_s_setprio(1); _Pragma("unroll") for (int m = 0; m < 4; ++m) _Pragma("unroll") for (int n = 0; n < 2; ++n) _Pragma("unroll") for (int k = 0; k < 2; ++k) \
;         acc[ai][bj][m][n] = __builtin_amdgcn_mfma_f32_16x16x32_bf16(Bt[n][k], At[m][k], acc[ai][bj][m][n], 0, 0, 0); __builtin_amdgcn_s_setprio(0); } while (0)
; #define PG8_WAIT_V(n) asm volatile("s_waitcnt vmcnt(" #n ")" ::: "memory")
; #define PG8_WAIT_L(n) asm volatile("s_waitcnt lgkmcnt(" #n ")" ::: "memory")
; #define PG8_BAR __builtin_amdgcn_s_barrier()
; #define PG8_SCHED __builtin_amdgcn_sched_barrier(0)
; template <class Epi>
; DI void gemm_phase(int wv, LAS unsigned char* lds, LAS unsigned char* scr, const Sched& S, const Epi& E) {
;     ...
;         const bool has_next = S.next(ui + 1, nxt);
;         const char* nA = has_next ? S.baseA(nxt) : cA; const char* nB = has_next ? S.baseB(nxt) : cB;
;         for (int t = 0; t < nt; t += 2) {
;             const bool last = (t == nt - 2);
;             const char* a1 = cA + (size_t)(t + 1) * kstep;
;             const char* a2 = last ? nA : cA + (size_t)(t + 2) * kstep; const char* b2 = last ? nB : cB + (size_t)(t + 2) * kstep;
;             const char* a3 = a2 + kstep; const char* b3 = b2 + kstep;
;             PG8_LDB(B0, 0, 0); PG8_LDB(B1, 0, 1); PG8_SCHED; PG8_LDA(At, 0, 0); PG8_STAGE(PG8_SA(1, 1), a1 + hstepA, voffA);
;             PG8_WAIT_V(8); PG8_WAIT_L(0); PG8_BAR; PG8_MMA(0, 0, At, B0); PG8_MMA(0, 1, At, B1); PG8_BAR; PG8_SCHED;
;             PG8_LDA(At, 0, 1); PG8_STAGE(PG8_SB(0, 0), b2, voffB); PG8_STAGE(PG8_SB(0, 1), b2 + hstepB, voffB); PG8_STAGE(PG8_SA(0, 0), a2, voffA);
.LBB0_163:
	s_add_u32 s26, s6, 0xfffc0080
	s_addc_u32 s27, s7, -1
	s_add_i32 s62, 0, 0x10000
	s_cmp_eq_u32 s61, 12
	s_cselect_b32 s29, s21, s27
	s_cselect_b32 s28, s40, s26
	v_add_u32_e32 v143, s62, v140
	s_cselect_b32 s27, s23, s60
	s_cselect_b32 s26, s22, s55
	s_add_i32 s64, 0, 0x14000
	ds_read_b128 v[144:147], v143
	ds_read_b128 v[148:151], v143 offset:1024
	ds_read_b128 v[152:155], v143 offset:2048
	ds_read_b128 v[156:159], v143 offset:3072
	v_add_u32_e32 v143, s64, v140
	ds_read_b128 v[160:163], v143
	ds_read_b128 v[164:167], v143 offset:1024
	ds_read_b128 v[168:171], v143 offset:2048
	ds_read_b128 v[172:175], v143 offset:3072
	v_lshl_add_u64 v[210:211], s[6:7], 0, v[138:139]
	s_add_i32 m0, s37, 0xc000
	ds_read_b128 v[176:179], v142
	ds_read_b128 v[180:183], v142 offset:1024
	ds_read_b128 v[184:187], v142 offset:2048
	ds_read_b128 v[188:191], v142 offset:3072
	ds_read_b128 v[194:197], v142 offset:4096
	ds_read_b128 v[198:201], v142 offset:5120
	ds_read_b128 v[202:205], v142 offset:6144
	ds_read_b128 v[206:209], v142 offset:7168
	global_load_lds_dwordx4 v[210:211], off
	v_lshl_add_u64 v[210:211], s[6:7], 0, v[136:137]
	s_add_i32 m0, s37, 0xe000
	s_nop 0
	global_load_lds_dwordx4 v[210:211], off
	s_waitcnt vmcnt(8) lgkmcnt(0)
	s_barrier
	v_mfma_f32_16x16x32_bf16 v[124:127], v[144:147], v[176:179], v[124:127]
	v_mfma_f32_16x16x32_bf16 v[120:123], v[152:155], v[176:179], v[120:123]
	v_mfma_f32_16x16x32_bf16 v[116:119], v[144:147], v[184:187], v[116:119]
	v_mfma_f32_16x16x32_bf16 v[112:115], v[152:155], v[184:187], v[112:115]
	v_mfma_f32_16x16x32_bf16 v[100:103], v[144:147], v[194:197], v[100:103]
	v_mfma_f32_16x16x32_bf16 v[96:99], v[152:155], v[194:197], v[96:99]
	v_mfma_f32_16x16x32_bf16 v[84:87], v[144:147], v[202:205], v[84:87]
	v_mfma_f32_16x16x32_bf16 v[80:83], v[152:155], v[202:205], v[80:83]
	v_mfma_f32_16x16x32_bf16 v[124:127], v[148:151], v[180:183], v[124:127]
	v_mfma_f32_16x16x32_bf16 v[120:123], v[156:159], v[180:183], v[120:123]
	v_mfma_f32_16x16x32_bf16 v[116:119], v[148:151], v[188:191], v[116:119]
	v_mfma_f32_16x16x32_bf16 v[112:115], v[156:159], v[188:191], v[112:115]
	v_mfma_f32_16x16x32_bf16 v[100:103], v[148:151], v[198:201], v[100:103]
	v_mfma_f32_16x16x32_bf16 v[96:99], v[156:159], v[198:201], v[96:99]
	v_mfma_f32_16x16x32_bf16 v[84:87], v[148:151], v[206:209], v[84:87]
	v_mfma_f32_16x16x32_bf16 v[80:83], v[156:159], v[206:209], v[80:83]
	v_mfma_f32_16x16x32_bf16 v[108:111], v[160:163], v[176:179], v[108:111]
	v_mfma_f32_16x16x32_bf16 v[104:107], v[168:171], v[176:179], v[104:107]
	v_mfma_f32_16x16x32_bf16 v[92:95], v[160:163], v[184:187], v[92:95]
	v_mfma_f32_16x16x32_bf16 v[88:91], v[168:171], v[184:187], v[88:91]
	v_mfma_f32_16x16x32_bf16 v[76:79], v[160:163], v[194:197], v[76:79]
	v_mfma_f32_16x16x32_bf16 v[72:75], v[168:171], v[194:197], v[72:75]
	v_mfma_f32_16x16x32_bf16 v[68:71], v[160:163], v[202:205], v[68:71]
	v_mfma_f32_16x16x32_bf16 v[64:67], v[168:171], v[202:205], v[64:67]
	v_mfma_f32_16x16x32_bf16 v[108:111], v[164:167], v[180:183], v[108:111]
	v_mfma_f32_16x16x32_bf16 v[104:107], v[172:175], v[180:183], v[104:107]
	v_mfma_f32_16x16x32_bf16 v[92:95], v[164:167], v[188:191], v[92:95]
	v_mfma_f32_16x16x32_bf16 v[88:91], v[172:175], v[188:191], v[88:91]
	v_mfma_f32_16x16x32_bf16 v[76:79], v[164:167], v[198:201], v[76:79]
	v_mfma_f32_16x16x32_bf16 v[72:75], v[172:175], v[198:201], v[72:75]
	v_mfma_f32_16x16x32_bf16 v[68:71], v[164:167], v[206:209], v[68:71]
	v_mfma_f32_16x16x32_bf16 v[64:67], v[172:175], v[206:209], v[64:67]
	s_barrier
	s_add_i32 s62, s62, s33
	v_lshl_add_u64 v[210:211], s[26:27], 0, v[192:193]
	s_mov_b32 m0, s62
	ds_read_b128 v[176:179], v142 offset:16384
	ds_read_b128 v[180:183], v142 offset:17408
	ds_read_b128 v[184:187], v142 offset:18432
	ds_read_b128 v[188:191], v142 offset:19456
	ds_read_b128 v[194:197], v142 offset:20480
	ds_read_b128 v[198:201], v142 offset:21504
	ds_read_b128 v[202:205], v142 offset:22528
	ds_read_b128 v[206:209], v142 offset:23552
	global_load_lds_dwordx4 v[210:211], off
	s_add_i32 m0, s62, 0x2000
	s_add_u32 s62, s26, 0x100000
	v_lshl_add_u64 v[212:213], s[26:27], 0, v[132:133]
	s_addc_u32 s63, s27, 0
	s_add_i32 s64, s64, s33
	global_load_lds_dwordx4 v[212:213], off
	v_lshl_add_u64 v[214:215], s[62:63], 0, v[192:193]
	s_mov_b32 m0, s64
	v_lshl_add_u64 v[216:217], s[28:29], 0, v[130:131]
	global_load_lds_dwordx4 v[214:215], off
	v_lshl_add_u64 v[214:215], s[62:63], 0, v[132:133]
	s_add_i32 m0, s64, 0x2000
	s_nop 0
	global_load_lds_dwordx4 v[214:215], off
	v_lshl_add_u64 v[214:215], s[28:29], 0, v[128:129]
	s_mov_b32 m0, s37
	s_nop 0
	global_load_lds_dwordx4 v[214:215], off
	s_mov_b32 m0, s38
	s_nop 0
	global_load_lds_dwordx4 v[216:217], off
	s_waitcnt vmcnt(8) lgkmcnt(0)
	s_barrier
; #define PG8_STAGE(bufoff, gbase, voff) do { _Pragma("unroll") for (int _i = 0; _i < 2; ++_i) \
;         __builtin_amdgcn_global_load_lds((const unsigned*)((const char*)(gbase) + (voff)[_i]), (LAS unsigned*)(lds + (bufoff) + ldsw + _i * 8192), 16, 0, 0); } while (0)
; #define PG8_LDA(dst, b, h) do { _Pragma("unroll") for (int m = 0; m < 4; ++m) _Pragma("unroll") for (int k = 0; k < 2; ++k) dst[m][k] = *(const LAS bf16x8*)(lds + PG8_SA(b, h) + aoff + m * 2048 + k * 1024); } while (0)
; #define PG8_LDB(dst, b, h) do { _Pragma("unroll") for (int n = 0; n < 2; ++n) _Pragma("unroll") for (int k = 0; k < 2; ++k) dst[n][k] = *(const LAS bf16x8*)(lds + PG8_SB(b, h) + boff + n * 2048 + k * 1024); } while (0)
; #define PG8_MMA(ai, bj, At, Bt) do { __builtin_amdgcn_s_setprio(1); _Pragma("unroll") for (int m = 0; m < 4; ++m) _Pragma("unroll") for (int n = 0; n < 2; ++n) _Pragma("unroll") for (int k = 0; k < 2; ++k) \
;         acc[ai][bj][m][n] = __builtin_amdgcn_mfma_f32_16x16x32_bf16(Bt[n][k], At[m][k], acc[ai][bj][m][n], 0, 0, 0); __builtin_amdgcn_s_setprio(0); } while (0)
; #define PG8_WAIT_V(n) asm volatile("s_waitcnt vmcnt(" #n ")" ::: "memory")
; #define PG8_WAIT_L(n) asm volatile("s_waitcnt lgkmcnt(" #n ")" ::: "memory")
; #define PG8_BAR __builtin_amdgcn_s_barrier()
; #define PG8_SCHED __builtin_amdgcn_sched_barrier(0)
; template <class Epi>
; DI void gemm_phase(int wv, LAS unsigned char* lds, LAS unsigned char* scr, const Sched& S, const Epi& E) {
;     ...
;             PG8_WAIT_V(8); PG8_WAIT_L(0); PG8_BAR; PG8_MMA(1, 0, At, B0); PG8_MMA(1, 1, At, B1); PG8_BAR; PG8_SCHED;
;             PG8_LDB(B0, 1, 0); PG8_LDB(B1, 1, 1); PG8_SCHED; PG8_LDA(At, 1, 0); PG8_STAGE(PG8_SA(0, 1), a2 + hstepA, voffA);
;             PG8_WAIT_V(8); PG8_WAIT_L(0); PG8_BAR; PG8_MMA(0, 0, At, B0); PG8_MMA(0, 1, At, B1); PG8_BAR; PG8_SCHED;
	v_mfma_f32_16x16x32_bf16 v[60:63], v[144:147], v[176:179], v[60:63]
	v_mfma_f32_16x16x32_bf16 v[56:59], v[152:155], v[176:179], v[56:59]
	v_mfma_f32_16x16x32_bf16 v[52:55], v[144:147], v[184:187], v[52:55]
	v_mfma_f32_16x16x32_bf16 v[48:51], v[152:155], v[184:187], v[48:51]
	v_mfma_f32_16x16x32_bf16 v[36:39], v[144:147], v[194:197], v[36:39]
	v_mfma_f32_16x16x32_bf16 v[32:35], v[152:155], v[194:197], v[32:35]
	v_mfma_f32_16x16x32_bf16 v[20:23], v[144:147], v[202:205], v[20:23]
	v_mfma_f32_16x16x32_bf16 v[16:19], v[152:155], v[202:205], v[16:19]
	v_mfma_f32_16x16x32_bf16 v[60:63], v[148:151], v[180:183], v[60:63]
	v_mfma_f32_16x16x32_bf16 v[56:59], v[156:159], v[180:183], v[56:59]
	v_mfma_f32_16x16x32_bf16 v[52:55], v[148:151], v[188:191], v[52:55]
	v_mfma_f32_16x16x32_bf16 v[48:51], v[156:159], v[188:191], v[48:51]
	v_mfma_f32_16x16x32_bf16 v[36:39], v[148:151], v[198:201], v[36:39]
	v_mfma_f32_16x16x32_bf16 v[32:35], v[156:159], v[198:201], v[32:35]
	v_mfma_f32_16x16x32_bf16 v[20:23], v[148:151], v[206:209], v[20:23]
	v_mfma_f32_16x16x32_bf16 v[16:19], v[156:159], v[206:209], v[16:19]
	v_mfma_f32_16x16x32_bf16 v[44:47], v[160:163], v[176:179], v[44:47]
	v_mfma_f32_16x16x32_bf16 v[40:43], v[168:171], v[176:179], v[40:43]
	v_mfma_f32_16x16x32_bf16 v[28:31], v[160:163], v[184:187], v[28:31]
	v_mfma_f32_16x16x32_bf16 v[24:27], v[168:171], v[184:187], v[24:27]
	v_mfma_f32_16x16x32_bf16 v[12:15], v[160:163], v[194:197], v[12:15]
	v_mfma_f32_16x16x32_bf16 v[8:11], v[168:171], v[194:197], v[8:11]
	v_mfma_f32_16x16x32_bf16 v[4:7], v[160:163], v[202:205], v[4:7]
	v_mfma_f32_16x16x32_bf16 v[0:3], v[168:171], v[202:205], v[0:3]
	v_mfma_f32_16x16x32_bf16 v[44:47], v[164:167], v[180:183], v[44:47]
	v_mfma_f32_16x16x32_bf16 v[40:43], v[172:175], v[180:183], v[40:43]
	v_mfma_f32_16x16x32_bf16 v[28:31], v[164:167], v[188:191], v[28:31]
	v_mfma_f32_16x16x32_bf16 v[24:27], v[172:175], v[188:191], v[24:27]
	v_mfma_f32_16x16x32_bf16 v[12:15], v[164:167], v[198:201], v[12:15]
	v_mfma_f32_16x16x32_bf16 v[8:11], v[172:175], v[198:201], v[8:11]
	v_mfma_f32_16x16x32_bf16 v[4:7], v[164:167], v[206:209], v[4:7]
	v_mfma_f32_16x16x32_bf16 v[0:3], v[172:175], v[206:209], v[0:3]
	s_barrier
	s_add_i32 s62, 0, 0x18000
	v_add_u32_e32 v143, s62, v140
	s_add_i32 s63, 0, 0x1c000
	ds_read_b128 v[144:147], v143
	ds_read_b128 v[148:151], v143 offset:1024
	ds_read_b128 v[152:155], v143 offset:2048
	ds_read_b128 v[156:159], v143 offset:3072
	v_add_u32_e32 v143, s63, v140
	ds_read_b128 v[160:163], v143
	ds_read_b128 v[164:167], v143 offset:1024
	ds_read_b128 v[168:171], v143 offset:2048
	ds_read_b128 v[172:175], v143 offset:3072
	s_add_u32 s28, s28, 0x40000
	s_addc_u32 s29, s29, 0
	s_mov_b32 m0, s39
	v_lshl_add_u64 v[218:219], s[28:29], 0, v[128:129]
	ds_read_b128 v[176:179], v142 offset:32768
	ds_read_b128 v[180:183], v142 offset:33792
	ds_read_b128 v[184:187], v142 offset:34816
	ds_read_b128 v[188:191], v142 offset:35840
	ds_read_b128 v[194:197], v142 offset:36864
	ds_read_b128 v[198:201], v142 offset:37888
	ds_read_b128 v[202:205], v142 offset:38912
	ds_read_b128 v[206:209], v142 offset:39936
	global_load_lds_dwordx4 v[218:219], off
	v_lshl_add_u64 v[218:219], s[28:29], 0, v[130:131]
	s_mov_b32 m0, s42
	s_nop 0
	global_load_lds_dwordx4 v[218:219], off
	s_waitcnt vmcnt(8) lgkmcnt(0)
	s_barrier
	v_mfma_f32_16x16x32_bf16 v[124:127], v[144:147], v[176:179], v[124:127]
	v_mfma_f32_16x16x32_bf16 v[120:123], v[152:155], v[176:179], v[120:123]
	v_mfma_f32_16x16x32_bf16 v[116:119], v[144:147], v[184:187], v[116:119]
	v_mfma_f32_16x16x32_bf16 v[112:115], v[152:155], v[184:187], v[112:115]
	v_mfma_f32_16x16x32_bf16 v[100:103], v[144:147], v[194:197], v[100:103]
	v_mfma_f32_16x16x32_bf16 v[96:99], v[152:155], v[194:197], v[96:99]
	v_mfma_f32_16x16x32_bf16 v[84:87], v[144:147], v[202:205], v[84:87]
	v_mfma_f32_16x16x32_bf16 v[80:83], v[152:155], v[202:205], v[80:83]
	v_mfma_f32_16x16x32_bf16 v[124:127], v[148:151], v[180:183], v[124:127]
	v_mfma_f32_16x16x32_bf16 v[120:123], v[156:159], v[180:183], v[120:123]
	v_mfma_f32_16x16x32_bf16 v[116:119], v[148:151], v[188:191], v[116:119]
	v_mfma_f32_16x16x32_bf16 v[112:115], v[156:159], v[188:191], v[112:115]
	v_mfma_f32_16x16x32_bf16 v[100:103], v[148:151], v[198:201], v[100:103]
	v_mfma_f32_16x16x32_bf16 v[96:99], v[156:159], v[198:201], v[96:99]
	v_mfma_f32_16x16x32_bf16 v[84:87], v[148:151], v[206:209], v[84:87]
	v_mfma_f32_16x16x32_bf16 v[80:83], v[156:159], v[206:209], v[80:83]
	v_mfma_f32_16x16x32_bf16 v[108:111], v[160:163], v[176:179], v[108:111]
	v_mfma_f32_16x16x32_bf16 v[104:107], v[168:171], v[176:179], v[104:107]
	v_mfma_f32_16x16x32_bf16 v[92:95], v[160:163], v[184:187], v[92:95]
	v_mfma_f32_16x16x32_bf16 v[88:91], v[168:171], v[184:187], v[88:91]
	v_mfma_f32_16x16x32_bf16 v[76:79], v[160:163], v[194:197], v[76:79]
	v_mfma_f32_16x16x32_bf16 v[72:75], v[168:171], v[194:197], v[72:75]
	v_mfma_f32_16x16x32_bf16 v[68:71], v[160:163], v[202:205], v[68:71]
	v_mfma_f32_16x16x32_bf16 v[64:67], v[168:171], v[202:205], v[64:67]
	v_mfma_f32_16x16x32_bf16 v[108:111], v[164:167], v[180:183], v[108:111]
	v_mfma_f32_16x16x32_bf16 v[104:107], v[172:175], v[180:183], v[104:107]
	v_mfma_f32_16x16x32_bf16 v[92:95], v[164:167], v[188:191], v[92:95]
	v_mfma_f32_16x16x32_bf16 v[88:91], v[172:175], v[188:191], v[88:91]
	v_mfma_f32_16x16x32_bf16 v[76:79], v[164:167], v[198:201], v[76:79]
	v_mfma_f32_16x16x32_bf16 v[72:75], v[172:175], v[198:201], v[72:75]
	v_mfma_f32_16x16x32_bf16 v[68:71], v[164:167], v[206:209], v[68:71]
	v_mfma_f32_16x16x32_bf16 v[64:67], v[172:175], v[206:209], v[64:67]
	s_barrier
; #define PG8_STAGE(bufoff, gbase, voff) do { _Pragma("unroll") for (int _i = 0; _i < 2; ++_i) \
;         __builtin_amdgcn_global_load_lds((const unsigned*)((const char*)(gbase) + (voff)[_i]), (LAS unsigned*)(lds + (bufoff) + ldsw + _i * 8192), 16, 0, 0); } while (0)
; #define PG8_LDA(dst, b, h) do { _Pragma("unroll") for (int m = 0; m < 4; ++m) _Pragma("unroll") for (int k = 0; k < 2; ++k) dst[m][k] = *(const LAS bf16x8*)(lds + PG8_SA(b, h) + aoff + m * 2048 + k * 1024); } while (0)
; #define PG8_MMA(ai, bj, At, Bt) do { __builtin_amdgcn_s_setprio(1); _Pragma("unroll") for (int m = 0; m < 4; ++m) _Pragma("unroll") for (int n = 0; n < 2; ++n) _Pragma("unroll") for (int k = 0; k < 2; ++k) \
;         acc[ai][bj][m][n] = __builtin_amdgcn_mfma_f32_16x16x32_bf16(Bt[n][k], At[m][k], acc[ai][bj][m][n], 0, 0, 0); __builtin_amdgcn_s_setprio(0); } while (0)
; #define PG8_WAIT_V(n) asm volatile("s_waitcnt vmcnt(" #n ")" ::: "memory")
; #define PG8_WAIT_L(n) asm volatile("s_waitcnt lgkmcnt(" #n ")" ::: "memory")
; #define PG8_BAR __builtin_amdgcn_s_barrier()
; #define PG8_SCHED __builtin_amdgcn_sched_barrier(0)
; template <class Epi>
; DI void gemm_phase(int wv, LAS unsigned char* lds, LAS unsigned char* scr, const Sched& S, const Epi& E) {
;     ...
;             PG8_LDA(At, 1, 1); PG8_STAGE(PG8_SB(1, 0), b3, voffB); PG8_STAGE(PG8_SB(1, 1), b3 + hstepB, voffB); PG8_STAGE(PG8_SA(1, 0), a3, voffA);
;             PG8_WAIT_V(8); PG8_WAIT_L(0); PG8_BAR; PG8_MMA(1, 0, At, B0); PG8_MMA(1, 1, At, B1); PG8_BAR; PG8_SCHED;
;         }
;         if (wr == 0) PG8_BAR;
	s_add_i32 s28, s62, s33
	v_lshl_add_u64 v[210:211], v[210:211], 0, s[2:3]
	s_mov_b32 m0, s28
	ds_read_b128 v[176:179], v142 offset:49152
	ds_read_b128 v[180:183], v142 offset:50176
	ds_read_b128 v[184:187], v142 offset:51200
	ds_read_b128 v[188:191], v142 offset:52224
	ds_read_b128 v[194:197], v142 offset:53248
	ds_read_b128 v[198:201], v142 offset:54272
	ds_read_b128 v[202:205], v142 offset:55296
	ds_read_b128 v[206:209], v142 offset:56320
	global_load_lds_dwordx4 v[210:211], off
	s_add_i32 m0, s28, 0x2000
	s_add_u32 s26, s26, 0x100080
	v_lshl_add_u64 v[210:211], v[212:213], 0, s[2:3]
	s_addc_u32 s27, s27, 0
	s_add_i32 s28, s63, s33
	global_load_lds_dwordx4 v[210:211], off
	v_lshl_add_u64 v[210:211], s[26:27], 0, v[192:193]
	s_mov_b32 m0, s28
	s_nop 0
	global_load_lds_dwordx4 v[210:211], off
	v_lshl_add_u64 v[210:211], s[26:27], 0, v[132:133]
	s_add_i32 m0, s28, 0x2000
	s_nop 0
	global_load_lds_dwordx4 v[210:211], off
	v_lshl_add_u64 v[210:211], v[214:215], 0, s[2:3]
	s_mov_b32 m0, s43
	s_nop 0
	global_load_lds_dwordx4 v[210:211], off
	v_lshl_add_u64 v[210:211], v[216:217], 0, s[2:3]
	s_mov_b32 m0, s44
	s_nop 0
	global_load_lds_dwordx4 v[210:211], off
	s_waitcnt vmcnt(8) lgkmcnt(0)
	s_barrier
	v_mfma_f32_16x16x32_bf16 v[60:63], v[144:147], v[176:179], v[60:63]
	v_mfma_f32_16x16x32_bf16 v[56:59], v[152:155], v[176:179], v[56:59]
	v_mfma_f32_16x16x32_bf16 v[52:55], v[144:147], v[184:187], v[52:55]
	v_mfma_f32_16x16x32_bf16 v[48:51], v[152:155], v[184:187], v[48:51]
	v_mfma_f32_16x16x32_bf16 v[36:39], v[144:147], v[194:197], v[36:39]
	v_mfma_f32_16x16x32_bf16 v[32:35], v[152:155], v[194:197], v[32:35]
	v_mfma_f32_16x16x32_bf16 v[20:23], v[144:147], v[202:205], v[20:23]
	v_mfma_f32_16x16x32_bf16 v[16:19], v[152:155], v[202:205], v[16:19]
	v_mfma_f32_16x16x32_bf16 v[60:63], v[148:151], v[180:183], v[60:63]
	v_mfma_f32_16x16x32_bf16 v[56:59], v[156:159], v[180:183], v[56:59]
	v_mfma_f32_16x16x32_bf16 v[52:55], v[148:151], v[188:191], v[52:55]
	v_mfma_f32_16x16x32_bf16 v[48:51], v[156:159], v[188:191], v[48:51]
	v_mfma_f32_16x16x32_bf16 v[36:39], v[148:151], v[198:201], v[36:39]
	v_mfma_f32_16x16x32_bf16 v[32:35], v[156:159], v[198:201], v[32:35]
	v_mfma_f32_16x16x32_bf16 v[20:23], v[148:151], v[206:209], v[20:23]
	v_mfma_f32_16x16x32_bf16 v[16:19], v[156:159], v[206:209], v[16:19]
	v_mfma_f32_16x16x32_bf16 v[44:47], v[160:163], v[176:179], v[44:47]
	v_mfma_f32_16x16x32_bf16 v[40:43], v[168:171], v[176:179], v[40:43]
	v_mfma_f32_16x16x32_bf16 v[28:31], v[160:163], v[184:187], v[28:31]
	v_mfma_f32_16x16x32_bf16 v[24:27], v[168:171], v[184:187], v[24:27]
	v_mfma_f32_16x16x32_bf16 v[12:15], v[160:163], v[194:197], v[12:15]
	v_mfma_f32_16x16x32_bf16 v[8:11], v[168:171], v[194:197], v[8:11]
	v_mfma_f32_16x16x32_bf16 v[4:7], v[160:163], v[202:205], v[4:7]
	v_mfma_f32_16x16x32_bf16 v[0:3], v[168:171], v[202:205], v[0:3]
	v_mfma_f32_16x16x32_bf16 v[44:47], v[164:167], v[180:183], v[44:47]
	v_mfma_f32_16x16x32_bf16 v[40:43], v[172:175], v[180:183], v[40:43]
	v_mfma_f32_16x16x32_bf16 v[28:31], v[164:167], v[188:191], v[28:31]
	v_mfma_f32_16x16x32_bf16 v[24:27], v[172:175], v[188:191], v[24:27]
	v_mfma_f32_16x16x32_bf16 v[12:15], v[164:167], v[198:201], v[12:15]
	v_mfma_f32_16x16x32_bf16 v[8:11], v[172:175], v[198:201], v[8:11]
	v_mfma_f32_16x16x32_bf16 v[4:7], v[164:167], v[206:209], v[4:7]
	v_mfma_f32_16x16x32_bf16 v[0:3], v[172:175], v[206:209], v[0:3]
	s_barrier
	s_add_i32 s61, s61, 2
	s_add_u32 s55, s55, 0x100
	s_addc_u32 s60, s60, 0
	s_add_u32 s6, s6, 0x100
	s_addc_u32 s7, s7, 0
	s_cmp_gt_u32 s61, 13
	s_cbranch_scc0 .LBB0_163
	s_and_b64 vcc, exec, s[18:19]
	s_cbranch_vccz .LBB0_166
	s_barrier

; #define PG8_STAGE(bufoff, gbase, voff) do { _Pragma("unroll") for (int _i = 0; _i < 2; ++_i) \
;         __builtin_amdgcn_global_load_lds((const unsigned*)((const char*)(gbase) + (voff)[_i]), (LAS unsigned*)(lds + (bufoff) + ldsw + _i * 8192), 16, 0, 0); } while (0)
; #define PG8_LDA(dst, b, h) do { _Pragma("unroll") for (int m = 0; m < 4; ++m) _Pragma("unroll") for (int k = 0; k < 2; ++k) dst[m][k] = *(const LAS bf16x8*)(lds + PG8_SA(b, h) + aoff + m * 2048 + k * 1024); } while (0)
; #define PG8_LDB(dst, b, h) do { _Pragma("unroll") for (int n = 0; n < 2; ++n) _Pragma("unroll") for (int k = 0; k < 2; ++k) dst[n][k] = *(const LAS bf16x8*)(lds + PG8_SB(b, h) + boff + n * 2048 + k * 1024); } while (0)
; #define PG8_MMA(ai, bj, At, Bt) do { __builtin_amdgcn_s_setprio(1); _Pragma("unroll") for (int m = 0; m < 4; ++m) _Pragma("unroll") for (int n = 0; n < 2; ++n) _Pragma("unroll") for (int k = 0; k < 2; ++k) \
;         acc[ai][bj][m][n] = __builtin_amdgcn_mfma_f32_16x16x32_bf16(Bt[n][k], At[m][k], acc[ai][bj][m][n], 0, 0, 0); __builtin_amdgcn_s_setprio(0); } while (0)
; #define PG8_WAIT_V(n) asm volatile("s_waitcnt vmcnt(" #n ")" ::: "memory")
; #define PG8_WAIT_L(n) asm volatile("s_waitcnt lgkmcnt(" #n ")" ::: "memory")
; #define PG8_BAR __builtin_amdgcn_s_barrier()
; #define PG8_SCHED __builtin_amdgcn_sched_barrier(0)
; template <class Epi>
; DI void gemm_phase(int wv, LAS unsigned char* lds, LAS unsigned char* scr, const Sched& S, const Epi& E) {
;     ...
;         const bool has_next = S.next(ui + 1, nxt);
;         const char* nA = has_next ? S.baseA(nxt) : cA; const char* nB = has_next ? S.baseB(nxt) : cB;
;         for (int t = 0; t < nt; t += 2) {
;             const bool last = (t == nt - 2);
;             const char* a1 = cA + (size_t)(t + 1) * kstep;
;             const char* a2 = last ? nA : cA + (size_t)(t + 2) * kstep; const char* b2 = last ? nB : cB + (size_t)(t + 2) * kstep;
;             const char* a3 = a2 + kstep; const char* b3 = b2 + kstep;
;             PG8_LDB(B0, 0, 0); PG8_LDB(B1, 0, 1); PG8_SCHED; PG8_LDA(At, 0, 0); PG8_STAGE(PG8_SA(1, 1), a1 + hstepA, voffA);
;             PG8_WAIT_V(8); PG8_WAIT_L(0); PG8_BAR; PG8_MMA(0, 0, At, B0); PG8_MMA(0, 1, At, B1); PG8_BAR; PG8_SCHED;
;             PG8_LDA(At, 0, 1); PG8_STAGE(PG8_SB(0, 0), b2, voffB); PG8_STAGE(PG8_SB(0, 1), b2 + hstepB, voffB); PG8_STAGE(PG8_SA(0, 0), a2, voffA);
.LBB0_189:
	s_add_u32 s26, s6, 0xfffc0080
	s_addc_u32 s27, s7, -1
	s_add_i32 s59, 0, 0x10000
	s_cmp_eq_u32 s55, 12
	s_cselect_b32 s29, s21, s27
	s_cselect_b32 s28, s40, s26
	v_add_u32_e32 v143, s59, v140
	s_cselect_b32 s27, s23, s54
	s_cselect_b32 s26, s22, s51
	s_add_i32 s62, 0, 0x14000
	ds_read_b128 v[144:147], v143
	ds_read_b128 v[148:151], v143 offset:1024
	ds_read_b128 v[152:155], v143 offset:2048
	ds_read_b128 v[156:159], v143 offset:3072
	v_add_u32_e32 v143, s62, v140
	ds_read_b128 v[160:163], v143
	ds_read_b128 v[164:167], v143 offset:1024
	ds_read_b128 v[168:171], v143 offset:2048
	ds_read_b128 v[172:175], v143 offset:3072
	v_lshl_add_u64 v[210:211], s[6:7], 0, v[138:139]
	s_add_i32 m0, s37, 0xc000
	ds_read_b128 v[176:179], v142
	ds_read_b128 v[180:183], v142 offset:1024
	ds_read_b128 v[184:187], v142 offset:2048
	ds_read_b128 v[188:191], v142 offset:3072
	ds_read_b128 v[194:197], v142 offset:4096
	ds_read_b128 v[198:201], v142 offset:5120
	ds_read_b128 v[202:205], v142 offset:6144
	ds_read_b128 v[206:209], v142 offset:7168
	global_load_lds_dwordx4 v[210:211], off
	v_lshl_add_u64 v[210:211], s[6:7], 0, v[136:137]
	s_add_i32 m0, s37, 0xe000
	s_nop 0
	global_load_lds_dwordx4 v[210:211], off
	s_waitcnt vmcnt(8) lgkmcnt(0)
	s_barrier
	v_mfma_f32_16x16x32_bf16 v[124:127], v[144:147], v[176:179], v[124:127]
	v_mfma_f32_16x16x32_bf16 v[120:123], v[152:155], v[176:179], v[120:123]
	v_mfma_f32_16x16x32_bf16 v[116:119], v[144:147], v[184:187], v[116:119]
	v_mfma_f32_16x16x32_bf16 v[112:115], v[152:155], v[184:187], v[112:115]
	v_mfma_f32_16x16x32_bf16 v[100:103], v[144:147], v[194:197], v[100:103]
	v_mfma_f32_16x16x32_bf16 v[96:99], v[152:155], v[194:197], v[96:99]
	v_mfma_f32_16x16x32_bf16 v[84:87], v[144:147], v[202:205], v[84:87]
	v_mfma_f32_16x16x32_bf16 v[80:83], v[152:155], v[202:205], v[80:83]
	v_mfma_f32_16x16x32_bf16 v[124:127], v[148:151], v[180:183], v[124:127]
	v_mfma_f32_16x16x32_bf16 v[120:123], v[156:159], v[180:183], v[120:123]
	v_mfma_f32_16x16x32_bf16 v[116:119], v[148:151], v[188:191], v[116:119]
	v_mfma_f32_16x16x32_bf16 v[112:115], v[156:159], v[188:191], v[112:115]
	v_mfma_f32_16x16x32_bf16 v[100:103], v[148:151], v[198:201], v[100:103]
	v_mfma_f32_16x16x32_bf16 v[96:99], v[156:159], v[198:201], v[96:99]
	v_mfma_f32_16x16x32_bf16 v[84:87], v[148:151], v[206:209], v[84:87]
	v_mfma_f32_16x16x32_bf16 v[80:83], v[156:159], v[206:209], v[80:83]
	v_mfma_f32_16x16x32_bf16 v[108:111], v[160:163], v[176:179], v[108:111]
	v_mfma_f32_16x16x32_bf16 v[104:107], v[168:171], v[176:179], v[104:107]
	v_mfma_f32_16x16x32_bf16 v[92:95], v[160:163], v[184:187], v[92:95]
	v_mfma_f32_16x16x32_bf16 v[88:91], v[168:171], v[184:187], v[88:91]
	v_mfma_f32_16x16x32_bf16 v[76:79], v[160:163], v[194:197], v[76:79]
	v_mfma_f32_16x16x32_bf16 v[72:75], v[168:171], v[194:197], v[72:75]
	v_mfma_f32_16x16x32_bf16 v[68:71], v[160:163], v[202:205], v[68:71]
	v_mfma_f32_16x16x32_bf16 v[64:67], v[168:171], v[202:205], v[64:67]
	v_mfma_f32_16x16x32_bf16 v[108:111], v[164:167], v[180:183], v[108:111]
	v_mfma_f32_16x16x32_bf16 v[104:107], v[172:175], v[180:183], v[104:107]
	v_mfma_f32_16x16x32_bf16 v[92:95], v[164:167], v[188:191], v[92:95]
	v_mfma_f32_16x16x32_bf16 v[88:91], v[172:175], v[188:191], v[88:91]
	v_mfma_f32_16x16x32_bf16 v[76:79], v[164:167], v[198:201], v[76:79]
	v_mfma_f32_16x16x32_bf16 v[72:75], v[172:175], v[198:201], v[72:75]
	v_mfma_f32_16x16x32_bf16 v[68:71], v[164:167], v[206:209], v[68:71]
	v_mfma_f32_16x16x32_bf16 v[64:67], v[172:175], v[206:209], v[64:67]
	s_barrier
	s_add_i32 s59, s59, s33
	v_lshl_add_u64 v[210:211], s[26:27], 0, v[192:193]
	s_mov_b32 m0, s59
	ds_read_b128 v[176:179], v142 offset:16384
	ds_read_b128 v[180:183], v142 offset:17408
	ds_read_b128 v[184:187], v142 offset:18432
	ds_read_b128 v[188:191], v142 offset:19456
	ds_read_b128 v[194:197], v142 offset:20480
	ds_read_b128 v[198:201], v142 offset:21504
	ds_read_b128 v[202:205], v142 offset:22528
	ds_read_b128 v[206:209], v142 offset:23552
	global_load_lds_dwordx4 v[210:211], off
	s_add_i32 m0, s59, 0x2000
	s_add_u32 s60, s26, 0x400000
	v_lshl_add_u64 v[212:213], s[26:27], 0, v[132:133]
	s_addc_u32 s61, s27, 0
	s_add_i32 s59, s62, s33
	global_load_lds_dwordx4 v[212:213], off
	v_lshl_add_u64 v[214:215], s[60:61], 0, v[192:193]
	s_mov_b32 m0, s59
	v_lshl_add_u64 v[216:217], s[28:29], 0, v[130:131]
	global_load_lds_dwordx4 v[214:215], off
	v_lshl_add_u64 v[214:215], s[60:61], 0, v[132:133]
	s_add_i32 m0, s59, 0x2000
	s_nop 0
	global_load_lds_dwordx4 v[214:215], off
	v_lshl_add_u64 v[214:215], s[28:29], 0, v[128:129]
	s_mov_b32 m0, s37
	s_nop 0
	global_load_lds_dwordx4 v[214:215], off
	s_mov_b32 m0, s38
	s_nop 0
	global_load_lds_dwordx4 v[216:217], off
	s_waitcnt vmcnt(8) lgkmcnt(0)
	s_barrier
; #define PG8_STAGE(bufoff, gbase, voff) do { _Pragma("unroll") for (int _i = 0; _i < 2; ++_i) \
;         __builtin_amdgcn_global_load_lds((const unsigned*)((const char*)(gbase) + (voff)[_i]), (LAS unsigned*)(lds + (bufoff) + ldsw + _i * 8192), 16, 0, 0); } while (0)
; #define PG8_LDA(dst, b, h) do { _Pragma("unroll") for (int m = 0; m < 4; ++m) _Pragma("unroll") for (int k = 0; k < 2; ++k) dst[m][k] = *(const LAS bf16x8*)(lds + PG8_SA(b, h) + aoff + m * 2048 + k * 1024); } while (0)
; #define PG8_LDB(dst, b, h) do { _Pragma("unroll") for (int n = 0; n < 2; ++n) _Pragma("unroll") for (int k = 0; k < 2; ++k) dst[n][k] = *(const LAS bf16x8*)(lds + PG8_SB(b, h) + boff + n * 2048 + k * 1024); } while (0)
; #define PG8_MMA(ai, bj, At, Bt) do { __builtin_amdgcn_s_setprio(1); _Pragma("unroll") for (int m = 0; m < 4; ++m) _Pragma("unroll") for (int n = 0; n < 2; ++n) _Pragma("unroll") for (int k = 0; k < 2; ++k) \
;         acc[ai][bj][m][n] = __builtin_amdgcn_mfma_f32_16x16x32_bf16(Bt[n][k], At[m][k], acc[ai][bj][m][n], 0, 0, 0); __builtin_amdgcn_s_setprio(0); } while (0)
; #define PG8_WAIT_V(n) asm volatile("s_waitcnt vmcnt(" #n ")" ::: "memory")
; #define PG8_WAIT_L(n) asm volatile("s_waitcnt lgkmcnt(" #n ")" ::: "memory")
; #define PG8_BAR __builtin_amdgcn_s_barrier()
; #define PG8_SCHED __builtin_amdgcn_sched_barrier(0)
; template <class Epi>
; DI void gemm_phase(int wv, LAS unsigned char* lds, LAS unsigned char* scr, const Sched& S, const Epi& E) {
;     ...
;             PG8_WAIT_V(8); PG8_WAIT_L(0); PG8_BAR; PG8_MMA(1, 0, At, B0); PG8_MMA(1, 1, At, B1); PG8_BAR; PG8_SCHED;
;             PG8_LDB(B0, 1, 0); PG8_LDB(B1, 1, 1); PG8_SCHED; PG8_LDA(At, 1, 0); PG8_STAGE(PG8_SA(0, 1), a2 + hstepA, voffA);
;             PG8_WAIT_V(8); PG8_WAIT_L(0); PG8_BAR; PG8_MMA(0, 0, At, B0); PG8_MMA(0, 1, At, B1); PG8_BAR; PG8_SCHED;
	v_mfma_f32_16x16x32_bf16 v[60:63], v[144:147], v[176:179], v[60:63]
	v_mfma_f32_16x16x32_bf16 v[56:59], v[152:155], v[176:179], v[56:59]
	v_mfma_f32_16x16x32_bf16 v[52:55], v[144:147], v[184:187], v[52:55]
	v_mfma_f32_16x16x32_bf16 v[48:51], v[152:155], v[184:187], v[48:51]
	v_mfma_f32_16x16x32_bf16 v[36:39], v[144:147], v[194:197], v[36:39]
	v_mfma_f32_16x16x32_bf16 v[32:35], v[152:155], v[194:197], v[32:35]
	v_mfma_f32_16x16x32_bf16 v[20:23], v[144:147], v[202:205], v[20:23]
	v_mfma_f32_16x16x32_bf16 v[16:19], v[152:155], v[202:205], v[16:19]
	v_mfma_f32_16x16x32_bf16 v[60:63], v[148:151], v[180:183], v[60:63]
	v_mfma_f32_16x16x32_bf16 v[56:59], v[156:159], v[180:183], v[56:59]
	v_mfma_f32_16x16x32_bf16 v[52:55], v[148:151], v[188:191], v[52:55]
	v_mfma_f32_16x16x32_bf16 v[48:51], v[156:159], v[188:191], v[48:51]
	v_mfma_f32_16x16x32_bf16 v[36:39], v[148:151], v[198:201], v[36:39]
	v_mfma_f32_16x16x32_bf16 v[32:35], v[156:159], v[198:201], v[32:35]
	v_mfma_f32_16x16x32_bf16 v[20:23], v[148:151], v[206:209], v[20:23]
	v_mfma_f32_16x16x32_bf16 v[16:19], v[156:159], v[206:209], v[16:19]
	v_mfma_f32_16x16x32_bf16 v[44:47], v[160:163], v[176:179], v[44:47]
	v_mfma_f32_16x16x32_bf16 v[40:43], v[168:171], v[176:179], v[40:43]
	v_mfma_f32_16x16x32_bf16 v[28:31], v[160:163], v[184:187], v[28:31]
	v_mfma_f32_16x16x32_bf16 v[24:27], v[168:171], v[184:187], v[24:27]
	v_mfma_f32_16x16x32_bf16 v[12:15], v[160:163], v[194:197], v[12:15]
	v_mfma_f32_16x16x32_bf16 v[8:11], v[168:171], v[194:197], v[8:11]
	v_mfma_f32_16x16x32_bf16 v[4:7], v[160:163], v[202:205], v[4:7]
	v_mfma_f32_16x16x32_bf16 v[0:3], v[168:171], v[202:205], v[0:3]
	v_mfma_f32_16x16x32_bf16 v[44:47], v[164:167], v[180:183], v[44:47]
	v_mfma_f32_16x16x32_bf16 v[40:43], v[172:175], v[180:183], v[40:43]
	v_mfma_f32_16x16x32_bf16 v[28:31], v[164:167], v[188:191], v[28:31]
	v_mfma_f32_16x16x32_bf16 v[24:27], v[172:175], v[188:191], v[24:27]
	v_mfma_f32_16x16x32_bf16 v[12:15], v[164:167], v[198:201], v[12:15]
	v_mfma_f32_16x16x32_bf16 v[8:11], v[172:175], v[198:201], v[8:11]
	v_mfma_f32_16x16x32_bf16 v[4:7], v[164:167], v[206:209], v[4:7]
	v_mfma_f32_16x16x32_bf16 v[0:3], v[172:175], v[206:209], v[0:3]
	s_barrier
	s_add_i32 s59, 0, 0x18000
	v_add_u32_e32 v143, s59, v140
	s_add_i32 s60, 0, 0x1c000
	ds_read_b128 v[144:147], v143
	ds_read_b128 v[148:151], v143 offset:1024
	ds_read_b128 v[152:155], v143 offset:2048
	ds_read_b128 v[156:159], v143 offset:3072
	v_add_u32_e32 v143, s60, v140
	ds_read_b128 v[160:163], v143
	ds_read_b128 v[164:167], v143 offset:1024
	ds_read_b128 v[168:171], v143 offset:2048
	ds_read_b128 v[172:175], v143 offset:3072
	s_add_u32 s28, s28, 0x40000
	s_addc_u32 s29, s29, 0
	s_mov_b32 m0, s39
	v_lshl_add_u64 v[218:219], s[28:29], 0, v[128:129]
	ds_read_b128 v[176:179], v142 offset:32768
	ds_read_b128 v[180:183], v142 offset:33792
	ds_read_b128 v[184:187], v142 offset:34816
	ds_read_b128 v[188:191], v142 offset:35840
	ds_read_b128 v[194:197], v142 offset:36864
	ds_read_b128 v[198:201], v142 offset:37888
	ds_read_b128 v[202:205], v142 offset:38912
	ds_read_b128 v[206:209], v142 offset:39936
	global_load_lds_dwordx4 v[218:219], off
	v_lshl_add_u64 v[218:219], s[28:29], 0, v[130:131]
	s_mov_b32 m0, s42
	s_nop 0
	global_load_lds_dwordx4 v[218:219], off
	s_waitcnt vmcnt(8) lgkmcnt(0)
	s_barrier
	v_mfma_f32_16x16x32_bf16 v[124:127], v[144:147], v[176:179], v[124:127]
	v_mfma_f32_16x16x32_bf16 v[120:123], v[152:155], v[176:179], v[120:123]
	v_mfma_f32_16x16x32_bf16 v[116:119], v[144:147], v[184:187], v[116:119]
	v_mfma_f32_16x16x32_bf16 v[112:115], v[152:155], v[184:187], v[112:115]
	v_mfma_f32_16x16x32_bf16 v[100:103], v[144:147], v[194:197], v[100:103]
	v_mfma_f32_16x16x32_bf16 v[96:99], v[152:155], v[194:197], v[96:99]
	v_mfma_f32_16x16x32_bf16 v[84:87], v[144:147], v[202:205], v[84:87]
	v_mfma_f32_16x16x32_bf16 v[80:83], v[152:155], v[202:205], v[80:83]
	v_mfma_f32_16x16x32_bf16 v[124:127], v[148:151], v[180:183], v[124:127]
	v_mfma_f32_16x16x32_bf16 v[120:123], v[156:159], v[180:183], v[120:123]
	v_mfma_f32_16x16x32_bf16 v[116:119], v[148:151], v[188:191], v[116:119]
	v_mfma_f32_16x16x32_bf16 v[112:115], v[156:159], v[188:191], v[112:115]
	v_mfma_f32_16x16x32_bf16 v[100:103], v[148:151], v[198:201], v[100:103]
	v_mfma_f32_16x16x32_bf16 v[96:99], v[156:159], v[198:201], v[96:99]
	v_mfma_f32_16x16x32_bf16 v[84:87], v[148:151], v[206:209], v[84:87]
	v_mfma_f32_16x16x32_bf16 v[80:83], v[156:159], v[206:209], v[80:83]
	v_mfma_f32_16x16x32_bf16 v[108:111], v[160:163], v[176:179], v[108:111]
	v_mfma_f32_16x16x32_bf16 v[104:107], v[168:171], v[176:179], v[104:107]
	v_mfma_f32_16x16x32_bf16 v[92:95], v[160:163], v[184:187], v[92:95]
	v_mfma_f32_16x16x32_bf16 v[88:91], v[168:171], v[184:187], v[88:91]
	v_mfma_f32_16x16x32_bf16 v[76:79], v[160:163], v[194:197], v[76:79]
	v_mfma_f32_16x16x32_bf16 v[72:75], v[168:171], v[194:197], v[72:75]
	v_mfma_f32_16x16x32_bf16 v[68:71], v[160:163], v[202:205], v[68:71]
	v_mfma_f32_16x16x32_bf16 v[64:67], v[168:171], v[202:205], v[64:67]
	v_mfma_f32_16x16x32_bf16 v[108:111], v[164:167], v[180:183], v[108:111]
	v_mfma_f32_16x16x32_bf16 v[104:107], v[172:175], v[180:183], v[104:107]
	v_mfma_f32_16x16x32_bf16 v[92:95], v[164:167], v[188:191], v[92:95]
	v_mfma_f32_16x16x32_bf16 v[88:91], v[172:175], v[188:191], v[88:91]
	v_mfma_f32_16x16x32_bf16 v[76:79], v[164:167], v[198:201], v[76:79]
	v_mfma_f32_16x16x32_bf16 v[72:75], v[172:175], v[198:201], v[72:75]
	v_mfma_f32_16x16x32_bf16 v[68:71], v[164:167], v[206:209], v[68:71]
	v_mfma_f32_16x16x32_bf16 v[64:67], v[172:175], v[206:209], v[64:67]
	s_barrier
; #define PG8_STAGE(bufoff, gbase, voff) do { _Pragma("unroll") for (int _i = 0; _i < 2; ++_i) \
;         __builtin_amdgcn_global_load_lds((const unsigned*)((const char*)(gbase) + (voff)[_i]), (LAS unsigned*)(lds + (bufoff) + ldsw + _i * 8192), 16, 0, 0); } while (0)
; #define PG8_LDA(dst, b, h) do { _Pragma("unroll") for (int m = 0; m < 4; ++m) _Pragma("unroll") for (int k = 0; k < 2; ++k) dst[m][k] = *(const LAS bf16x8*)(lds + PG8_SA(b, h) + aoff + m * 2048 + k * 1024); } while (0)
; #define PG8_MMA(ai, bj, At, Bt) do { __builtin_amdgcn_s_setprio(1); _Pragma("unroll") for (int m = 0; m < 4; ++m) _Pragma("unroll") for (int n = 0; n < 2; ++n) _Pragma("unroll") for (int k = 0; k < 2; ++k) \
;         acc[ai][bj][m][n] = __builtin_amdgcn_mfma_f32_16x16x32_bf16(Bt[n][k], At[m][k], acc[ai][bj][m][n], 0, 0, 0); __builtin_amdgcn_s_setprio(0); } while (0)
; #define PG8_WAIT_V(n) asm volatile("s_waitcnt vmcnt(" #n ")" ::: "memory")
; #define PG8_WAIT_L(n) asm volatile("s_waitcnt lgkmcnt(" #n ")" ::: "memory")
; #define PG8_BAR __builtin_amdgcn_s_barrier()
; #define PG8_SCHED __builtin_amdgcn_sched_barrier(0)
; template <class Epi>
; DI void gemm_phase(int wv, LAS unsigned char* lds, LAS unsigned char* scr, const Sched& S, const Epi& E) {
;     ...
;             PG8_LDA(At, 1, 1); PG8_STAGE(PG8_SB(1, 0), b3, voffB); PG8_STAGE(PG8_SB(1, 1), b3 + hstepB, voffB); PG8_STAGE(PG8_SA(1, 0), a3, voffA);
;             PG8_WAIT_V(8); PG8_WAIT_L(0); PG8_BAR; PG8_MMA(1, 0, At, B0); PG8_MMA(1, 1, At, B1); PG8_BAR; PG8_SCHED;
;         }
;         if (wr == 0) PG8_BAR;
	s_add_i32 s28, s59, s33
	v_lshl_add_u64 v[210:211], v[210:211], 0, s[2:3]
	s_mov_b32 m0, s28
	ds_read_b128 v[176:179], v142 offset:49152
	ds_read_b128 v[180:183], v142 offset:50176
	ds_read_b128 v[184:187], v142 offset:51200
	ds_read_b128 v[188:191], v142 offset:52224
	ds_read_b128 v[194:197], v142 offset:53248
	ds_read_b128 v[198:201], v142 offset:54272
	ds_read_b128 v[202:205], v142 offset:55296
	ds_read_b128 v[206:209], v142 offset:56320
	global_load_lds_dwordx4 v[210:211], off
	s_add_i32 m0, s28, 0x2000
	s_add_u32 s26, s26, 0x400080
	v_lshl_add_u64 v[210:211], v[212:213], 0, s[2:3]
	s_addc_u32 s27, s27, 0
	s_add_i32 s28, s60, s33
	global_load_lds_dwordx4 v[210:211], off
	v_lshl_add_u64 v[210:211], s[26:27], 0, v[192:193]
	s_mov_b32 m0, s28
	s_nop 0
	global_load_lds_dwordx4 v[210:211], off
	v_lshl_add_u64 v[210:211], s[26:27], 0, v[132:133]
	s_add_i32 m0, s28, 0x2000
	s_nop 0
	global_load_lds_dwordx4 v[210:211], off
	v_lshl_add_u64 v[210:211], v[214:215], 0, s[2:3]
	s_mov_b32 m0, s43
	s_nop 0
	global_load_lds_dwordx4 v[210:211], off
	v_lshl_add_u64 v[210:211], v[216:217], 0, s[2:3]
	s_mov_b32 m0, s44
	s_nop 0
	global_load_lds_dwordx4 v[210:211], off
	s_waitcnt vmcnt(8) lgkmcnt(0)
	s_barrier
	v_mfma_f32_16x16x32_bf16 v[60:63], v[144:147], v[176:179], v[60:63]
	v_mfma_f32_16x16x32_bf16 v[56:59], v[152:155], v[176:179], v[56:59]
	v_mfma_f32_16x16x32_bf16 v[52:55], v[144:147], v[184:187], v[52:55]
	v_mfma_f32_16x16x32_bf16 v[48:51], v[152:155], v[184:187], v[48:51]
	v_mfma_f32_16x16x32_bf16 v[36:39], v[144:147], v[194:197], v[36:39]
	v_mfma_f32_16x16x32_bf16 v[32:35], v[152:155], v[194:197], v[32:35]
	v_mfma_f32_16x16x32_bf16 v[20:23], v[144:147], v[202:205], v[20:23]
	v_mfma_f32_16x16x32_bf16 v[16:19], v[152:155], v[202:205], v[16:19]
	v_mfma_f32_16x16x32_bf16 v[60:63], v[148:151], v[180:183], v[60:63]
	v_mfma_f32_16x16x32_bf16 v[56:59], v[156:159], v[180:183], v[56:59]
	v_mfma_f32_16x16x32_bf16 v[52:55], v[148:151], v[188:191], v[52:55]
	v_mfma_f32_16x16x32_bf16 v[48:51], v[156:159], v[188:191], v[48:51]
	v_mfma_f32_16x16x32_bf16 v[36:39], v[148:151], v[198:201], v[36:39]
	v_mfma_f32_16x16x32_bf16 v[32:35], v[156:159], v[198:201], v[32:35]
	v_mfma_f32_16x16x32_bf16 v[20:23], v[148:151], v[206:209], v[20:23]
	v_mfma_f32_16x16x32_bf16 v[16:19], v[156:159], v[206:209], v[16:19]
	v_mfma_f32_16x16x32_bf16 v[44:47], v[160:163], v[176:179], v[44:47]
	v_mfma_f32_16x16x32_bf16 v[40:43], v[168:171], v[176:179], v[40:43]
	v_mfma_f32_16x16x32_bf16 v[28:31], v[160:163], v[184:187], v[28:31]
	v_mfma_f32_16x16x32_bf16 v[24:27], v[168:171], v[184:187], v[24:27]
	v_mfma_f32_16x16x32_bf16 v[12:15], v[160:163], v[194:197], v[12:15]
	v_mfma_f32_16x16x32_bf16 v[8:11], v[168:171], v[194:197], v[8:11]
	v_mfma_f32_16x16x32_bf16 v[4:7], v[160:163], v[202:205], v[4:7]
	v_mfma_f32_16x16x32_bf16 v[0:3], v[168:171], v[202:205], v[0:3]
	v_mfma_f32_16x16x32_bf16 v[44:47], v[164:167], v[180:183], v[44:47]
	v_mfma_f32_16x16x32_bf16 v[40:43], v[172:175], v[180:183], v[40:43]
	v_mfma_f32_16x16x32_bf16 v[28:31], v[164:167], v[188:191], v[28:31]
	v_mfma_f32_16x16x32_bf16 v[24:27], v[172:175], v[188:191], v[24:27]
	v_mfma_f32_16x16x32_bf16 v[12:15], v[164:167], v[198:201], v[12:15]
	v_mfma_f32_16x16x32_bf16 v[8:11], v[172:175], v[198:201], v[8:11]
	v_mfma_f32_16x16x32_bf16 v[4:7], v[164:167], v[206:209], v[4:7]
	v_mfma_f32_16x16x32_bf16 v[0:3], v[172:175], v[206:209], v[0:3]
	s_barrier
	s_add_i32 s55, s55, 2
	s_add_u32 s51, s51, 0x100
	s_addc_u32 s54, s54, 0
	s_add_u32 s6, s6, 0x100
	s_addc_u32 s7, s7, 0
	s_cmp_gt_u32 s55, 13
	s_cbranch_scc0 .LBB0_189
	s_and_b64 vcc, exec, s[18:19]
	s_cbranch_vccz .LBB0_192
	s_barrier

; #define PG8_STAGE(bufoff, gbase, voff) do { _Pragma("unroll") for (int _i = 0; _i < 2; ++_i) \
;         __builtin_amdgcn_global_load_lds((const unsigned*)((const char*)(gbase) + (voff)[_i]), (LAS unsigned*)(lds + (bufoff) + ldsw + _i * 8192), 16, 0, 0); } while (0)
; #define PG8_LDA(dst, b, h) do { _Pragma("unroll") for (int m = 0; m < 4; ++m) _Pragma("unroll") for (int k = 0; k < 2; ++k) dst[m][k] = *(const LAS bf16x8*)(lds + PG8_SA(b, h) + aoff + m * 2048 + k * 1024); } while (0)
; #define PG8_LDB(dst, b, h) do { _Pragma("unroll") for (int n = 0; n < 2; ++n) _Pragma("unroll") for (int k = 0; k < 2; ++k) dst[n][k] = *(const LAS bf16x8*)(lds + PG8_SB(b, h) + boff + n * 2048 + k * 1024); } while (0)
; #define PG8_MMA(ai, bj, At, Bt) do { __builtin_amdgcn_s_setprio(1); _Pragma("unroll") for (int m = 0; m < 4; ++m) _Pragma("unroll") for (int n = 0; n < 2; ++n) _Pragma("unroll") for (int k = 0; k < 2; ++k) \
;         acc[ai][bj][m][n] = __builtin_amdgcn_mfma_f32_16x16x32_bf16(Bt[n][k], At[m][k], acc[ai][bj][m][n], 0, 0, 0); __builtin_amdgcn_s_setprio(0); } while (0)
; #define PG8_WAIT_V(n) asm volatile("s_waitcnt vmcnt(" #n ")" ::: "memory")
; #define PG8_WAIT_L(n) asm volatile("s_waitcnt lgkmcnt(" #n ")" ::: "memory")
; #define PG8_BAR __builtin_amdgcn_s_barrier()
; #define PG8_SCHED __builtin_amdgcn_sched_barrier(0)
; template <class Epi>
; DI void gemm_phase(int wv, LAS unsigned char* lds, LAS unsigned char* scr, const Sched& S, const Epi& E) {
;     ...
;         const bool has_next = S.next(ui + 1, nxt);
;         const char* nA = has_next ? S.baseA(nxt) : cA; const char* nB = has_next ? S.baseB(nxt) : cB;
;         for (int t = 0; t < nt; t += 2) {
;             const bool last = (t == nt - 2);
;             const char* a1 = cA + (size_t)(t + 1) * kstep;
;             const char* a2 = last ? nA : cA + (size_t)(t + 2) * kstep; const char* b2 = last ? nB : cB + (size_t)(t + 2) * kstep;
;             const char* a3 = a2 + kstep; const char* b3 = b2 + kstep;
;             PG8_LDB(B0, 0, 0); PG8_LDB(B1, 0, 1); PG8_SCHED; PG8_LDA(At, 0, 0); PG8_STAGE(PG8_SA(1, 1), a1 + hstepA, voffA);
;             PG8_WAIT_V(8); PG8_WAIT_L(0); PG8_BAR; PG8_MMA(0, 0, At, B0); PG8_MMA(0, 1, At, B1); PG8_BAR; PG8_SCHED;
;             PG8_LDA(At, 0, 1); PG8_STAGE(PG8_SB(0, 0), b2, voffB); PG8_STAGE(PG8_SB(0, 1), b2 + hstepB, voffB); PG8_STAGE(PG8_SA(0, 0), a2, voffA);
.LBB0_256:
	s_add_u32 s21, s16, s13
	s_addc_u32 s23, s17, 0
	s_add_u32 s30, s21, 0x100
	s_addc_u32 s31, s23, 0
	s_and_b64 s[28:29], s[26:27], exec
	s_cselect_b32 s31, s9, s31
	s_cselect_b32 s30, s8, s30
	s_add_u32 s13, s18, s13
	s_addc_u32 s28, s19, 0
	s_add_u32 s13, s13, 0x100
	s_addc_u32 s28, s28, 0
	s_add_i32 s64, 0, 0x10000
	s_and_b64 s[26:27], s[26:27], exec
	s_cselect_b32 s35, s15, s28
	s_cselect_b32 s34, s14, s13
	s_add_i32 s27, 0, 0x14000
	s_add_u32 s38, s21, 0x40080
	s_addc_u32 s39, s23, 0
	s_add_i32 s63, s64, s45
	s_add_i32 m0, s46, 0xc000
	s_add_i32 s66, s46, 0xe000
	s_add_i32 s60, s63, 0x2000
	v_add_u32_e32 v138, s64, v140
	s_add_u32 s36, s34, 0x40000
	ds_read_b128 v[142:145], v138
	ds_read_b128 v[146:149], v138 offset:1024
	ds_read_b128 v[150:153], v138 offset:2048
	ds_read_b128 v[154:157], v138 offset:3072
	v_add_u32_e32 v138, s27, v140
	s_addc_u32 s37, s35, 0
	s_add_i32 s62, s27, s45
	ds_read_b128 v[158:161], v138
	ds_read_b128 v[162:165], v138 offset:1024
	ds_read_b128 v[166:169], v138 offset:2048
	ds_read_b128 v[170:173], v138 offset:3072
	s_add_i32 s61, s62, 0x2000
	s_add_i32 s59, 0, 0x18000
	s_add_i32 s23, 0, 0x1c000
	s_add_u32 s28, s30, 0x40000
	s_addc_u32 s29, s31, 0
	s_add_i32 s21, s59, s45
	s_add_i32 s13, s21, 0x2000
	s_add_u32 s26, s34, 0x40080
	s_addc_u32 s27, s35, 0
	s_add_i32 s65, s23, s45
	s_add_i32 s64, s65, 0x2000
	v_lshl_add_u64 v[138:139], s[38:39], 0, v[134:135]
	ds_read_b128 v[174:177], v141
	ds_read_b128 v[178:181], v141 offset:1024
	ds_read_b128 v[182:185], v141 offset:2048
	ds_read_b128 v[186:189], v141 offset:3072
	ds_read_b128 v[194:197], v141 offset:4096
	ds_read_b128 v[198:201], v141 offset:5120
	ds_read_b128 v[202:205], v141 offset:6144
	ds_read_b128 v[206:209], v141 offset:7168
	global_load_lds_dwordx4 v[138:139], off
	v_lshl_add_u64 v[138:139], s[38:39], 0, v[130:131]
	s_mov_b32 m0, s66
	s_nop 0
	global_load_lds_dwordx4 v[138:139], off
	s_waitcnt vmcnt(8) lgkmcnt(0)
	s_barrier
	v_mfma_f32_16x16x32_bf16 v[124:127], v[142:145], v[174:177], v[124:127]
	v_mfma_f32_16x16x32_bf16 v[120:123], v[150:153], v[174:177], v[120:123]
	v_mfma_f32_16x16x32_bf16 v[116:119], v[142:145], v[182:185], v[116:119]
	v_mfma_f32_16x16x32_bf16 v[108:111], v[150:153], v[182:185], v[108:111]
	v_mfma_f32_16x16x32_bf16 v[100:103], v[142:145], v[194:197], v[100:103]
	v_mfma_f32_16x16x32_bf16 v[92:95], v[150:153], v[194:197], v[92:95]
	v_mfma_f32_16x16x32_bf16 v[84:87], v[142:145], v[202:205], v[84:87]
	v_mfma_f32_16x16x32_bf16 v[76:79], v[150:153], v[202:205], v[76:79]
	v_mfma_f32_16x16x32_bf16 v[124:127], v[146:149], v[178:181], v[124:127]
	v_mfma_f32_16x16x32_bf16 v[120:123], v[154:157], v[178:181], v[120:123]
	v_mfma_f32_16x16x32_bf16 v[116:119], v[146:149], v[186:189], v[116:119]
	v_mfma_f32_16x16x32_bf16 v[108:111], v[154:157], v[186:189], v[108:111]
	v_mfma_f32_16x16x32_bf16 v[100:103], v[146:149], v[198:201], v[100:103]
	v_mfma_f32_16x16x32_bf16 v[92:95], v[154:157], v[198:201], v[92:95]
	v_mfma_f32_16x16x32_bf16 v[84:87], v[146:149], v[206:209], v[84:87]
	v_mfma_f32_16x16x32_bf16 v[76:79], v[154:157], v[206:209], v[76:79]
	v_mfma_f32_16x16x32_bf16 v[112:115], v[158:161], v[174:177], v[112:115]
	v_mfma_f32_16x16x32_bf16 v[104:107], v[166:169], v[174:177], v[104:107]
	v_mfma_f32_16x16x32_bf16 v[96:99], v[158:161], v[182:185], v[96:99]
	v_mfma_f32_16x16x32_bf16 v[88:91], v[166:169], v[182:185], v[88:91]
	v_mfma_f32_16x16x32_bf16 v[80:83], v[158:161], v[194:197], v[80:83]
	v_mfma_f32_16x16x32_bf16 v[72:75], v[166:169], v[194:197], v[72:75]
	v_mfma_f32_16x16x32_bf16 v[68:71], v[158:161], v[202:205], v[68:71]
	v_mfma_f32_16x16x32_bf16 v[64:67], v[166:169], v[202:205], v[64:67]
	v_mfma_f32_16x16x32_bf16 v[112:115], v[162:165], v[178:181], v[112:115]
	v_mfma_f32_16x16x32_bf16 v[104:107], v[170:173], v[178:181], v[104:107]
	v_mfma_f32_16x16x32_bf16 v[96:99], v[162:165], v[186:189], v[96:99]
	v_mfma_f32_16x16x32_bf16 v[88:91], v[170:173], v[186:189], v[88:91]
	v_mfma_f32_16x16x32_bf16 v[80:83], v[162:165], v[198:201], v[80:83]
	v_mfma_f32_16x16x32_bf16 v[72:75], v[170:173], v[198:201], v[72:75]
	v_mfma_f32_16x16x32_bf16 v[68:71], v[162:165], v[206:209], v[68:71]
	v_mfma_f32_16x16x32_bf16 v[64:67], v[170:173], v[206:209], v[64:67]
	s_barrier
	s_mov_b32 m0, s63
	v_lshl_add_u64 v[138:139], s[34:35], 0, v[132:133]
	ds_read_b128 v[174:177], v141 offset:16384
	ds_read_b128 v[178:181], v141 offset:17408
	ds_read_b128 v[182:185], v141 offset:18432
	ds_read_b128 v[186:189], v141 offset:19456
	ds_read_b128 v[194:197], v141 offset:20480
	ds_read_b128 v[198:201], v141 offset:21504
	ds_read_b128 v[202:205], v141 offset:22528
	ds_read_b128 v[206:209], v141 offset:23552
	global_load_lds_dwordx4 v[138:139], off
	v_lshl_add_u64 v[190:191], s[34:35], 0, v[128:129]
	s_mov_b32 m0, s60
	v_lshl_add_u64 v[210:211], s[36:37], 0, v[132:133]
	global_load_lds_dwordx4 v[190:191], off
	s_mov_b32 m0, s62
	v_lshl_add_u64 v[212:213], s[30:31], 0, v[130:131]
	global_load_lds_dwordx4 v[210:211], off
	v_lshl_add_u64 v[210:211], s[36:37], 0, v[128:129]
	s_mov_b32 m0, s61
	s_nop 0
	global_load_lds_dwordx4 v[210:211], off
	v_lshl_add_u64 v[210:211], s[30:31], 0, v[134:135]
	s_mov_b32 m0, s46
	s_nop 0
	global_load_lds_dwordx4 v[210:211], off
	s_mov_b32 m0, s47
	s_nop 0
	global_load_lds_dwordx4 v[212:213], off
	s_waitcnt vmcnt(8) lgkmcnt(0)
	s_barrier
; #define PG8_STAGE(bufoff, gbase, voff) do { _Pragma("unroll") for (int _i = 0; _i < 2; ++_i) \
;         __builtin_amdgcn_global_load_lds((const unsigned*)((const char*)(gbase) + (voff)[_i]), (LAS unsigned*)(lds + (bufoff) + ldsw + _i * 8192), 16, 0, 0); } while (0)
; #define PG8_LDA(dst, b, h) do { _Pragma("unroll") for (int m = 0; m < 4; ++m) _Pragma("unroll") for (int k = 0; k < 2; ++k) dst[m][k] = *(const LAS bf16x8*)(lds + PG8_SA(b, h) + aoff + m * 2048 + k * 1024); } while (0)
; #define PG8_LDB(dst, b, h) do { _Pragma("unroll") for (int n = 0; n < 2; ++n) _Pragma("unroll") for (int k = 0; k < 2; ++k) dst[n][k] = *(const LAS bf16x8*)(lds + PG8_SB(b, h) + boff + n * 2048 + k * 1024); } while (0)
; #define PG8_MMA(ai, bj, At, Bt) do { __builtin_amdgcn_s_setprio(1); _Pragma("unroll") for (int m = 0; m < 4; ++m) _Pragma("unroll") for (int n = 0; n < 2; ++n) _Pragma("unroll") for (int k = 0; k < 2; ++k) \
;         acc[ai][bj][m][n] = __builtin_amdgcn_mfma_f32_16x16x32_bf16(Bt[n][k], At[m][k], acc[ai][bj][m][n], 0, 0, 0); __builtin_amdgcn_s_setprio(0); } while (0)
; #define PG8_WAIT_V(n) asm volatile("s_waitcnt vmcnt(" #n ")" ::: "memory")
; #define PG8_WAIT_L(n) asm volatile("s_waitcnt lgkmcnt(" #n ")" ::: "memory")
; #define PG8_BAR __builtin_amdgcn_s_barrier()
; #define PG8_SCHED __builtin_amdgcn_sched_barrier(0)
; template <class Epi>
; DI void gemm_phase(int wv, LAS unsigned char* lds, LAS unsigned char* scr, const Sched& S, const Epi& E) {
;     ...
;             PG8_WAIT_V(8); PG8_WAIT_L(0); PG8_BAR; PG8_MMA(1, 0, At, B0); PG8_MMA(1, 1, At, B1); PG8_BAR; PG8_SCHED;
;             PG8_LDB(B0, 1, 0); PG8_LDB(B1, 1, 1); PG8_SCHED; PG8_LDA(At, 1, 0); PG8_STAGE(PG8_SA(0, 1), a2 + hstepA, voffA);
;             PG8_WAIT_V(8); PG8_WAIT_L(0); PG8_BAR; PG8_MMA(0, 0, At, B0); PG8_MMA(0, 1, At, B1); PG8_BAR; PG8_SCHED;
	v_mfma_f32_16x16x32_bf16 v[60:63], v[142:145], v[174:177], v[60:63]
	v_mfma_f32_16x16x32_bf16 v[56:59], v[150:153], v[174:177], v[56:59]
	v_mfma_f32_16x16x32_bf16 v[52:55], v[142:145], v[182:185], v[52:55]
	v_mfma_f32_16x16x32_bf16 v[44:47], v[150:153], v[182:185], v[44:47]
	v_mfma_f32_16x16x32_bf16 v[36:39], v[142:145], v[194:197], v[36:39]
	v_mfma_f32_16x16x32_bf16 v[28:31], v[150:153], v[194:197], v[28:31]
	v_mfma_f32_16x16x32_bf16 v[20:23], v[142:145], v[202:205], v[20:23]
	v_mfma_f32_16x16x32_bf16 v[12:15], v[150:153], v[202:205], v[12:15]
	v_mfma_f32_16x16x32_bf16 v[60:63], v[146:149], v[178:181], v[60:63]
	v_mfma_f32_16x16x32_bf16 v[56:59], v[154:157], v[178:181], v[56:59]
	v_mfma_f32_16x16x32_bf16 v[52:55], v[146:149], v[186:189], v[52:55]
	v_mfma_f32_16x16x32_bf16 v[44:47], v[154:157], v[186:189], v[44:47]
	v_mfma_f32_16x16x32_bf16 v[36:39], v[146:149], v[198:201], v[36:39]
	v_mfma_f32_16x16x32_bf16 v[28:31], v[154:157], v[198:201], v[28:31]
	v_mfma_f32_16x16x32_bf16 v[20:23], v[146:149], v[206:209], v[20:23]
	v_mfma_f32_16x16x32_bf16 v[12:15], v[154:157], v[206:209], v[12:15]
	v_mfma_f32_16x16x32_bf16 v[48:51], v[158:161], v[174:177], v[48:51]
	v_mfma_f32_16x16x32_bf16 v[40:43], v[166:169], v[174:177], v[40:43]
	v_mfma_f32_16x16x32_bf16 v[32:35], v[158:161], v[182:185], v[32:35]
	v_mfma_f32_16x16x32_bf16 v[24:27], v[166:169], v[182:185], v[24:27]
	v_mfma_f32_16x16x32_bf16 v[16:19], v[158:161], v[194:197], v[16:19]
	v_mfma_f32_16x16x32_bf16 v[8:11], v[166:169], v[194:197], v[8:11]
	v_mfma_f32_16x16x32_bf16 v[4:7], v[158:161], v[202:205], v[4:7]
	v_mfma_f32_16x16x32_bf16 v[0:3], v[166:169], v[202:205], v[0:3]
	v_mfma_f32_16x16x32_bf16 v[48:51], v[162:165], v[178:181], v[48:51]
	v_mfma_f32_16x16x32_bf16 v[40:43], v[170:173], v[178:181], v[40:43]
	v_mfma_f32_16x16x32_bf16 v[32:35], v[162:165], v[186:189], v[32:35]
	v_mfma_f32_16x16x32_bf16 v[24:27], v[170:173], v[186:189], v[24:27]
	v_mfma_f32_16x16x32_bf16 v[16:19], v[162:165], v[198:201], v[16:19]
	v_mfma_f32_16x16x32_bf16 v[8:11], v[170:173], v[198:201], v[8:11]
	v_mfma_f32_16x16x32_bf16 v[4:7], v[162:165], v[206:209], v[4:7]
	v_mfma_f32_16x16x32_bf16 v[0:3], v[170:173], v[206:209], v[0:3]
	s_barrier
	v_add_u32_e32 v154, s59, v140
	v_add_u32_e32 v170, s23, v140
	ds_read_b128 v[142:145], v154
	ds_read_b128 v[146:149], v154 offset:1024
	ds_read_b128 v[150:153], v154 offset:2048
	ds_read_b128 v[154:157], v154 offset:3072
	ds_read_b128 v[158:161], v170
	ds_read_b128 v[162:165], v170 offset:1024
	ds_read_b128 v[166:169], v170 offset:2048
	ds_read_b128 v[170:173], v170 offset:3072
	s_mov_b32 m0, s48
	v_lshl_add_u64 v[214:215], s[28:29], 0, v[134:135]
	ds_read_b128 v[174:177], v141 offset:32768
	ds_read_b128 v[178:181], v141 offset:33792
	ds_read_b128 v[182:185], v141 offset:34816
	ds_read_b128 v[186:189], v141 offset:35840
	ds_read_b128 v[194:197], v141 offset:36864
	ds_read_b128 v[198:201], v141 offset:37888
	ds_read_b128 v[202:205], v141 offset:38912
	ds_read_b128 v[206:209], v141 offset:39936
	global_load_lds_dwordx4 v[214:215], off
	v_lshl_add_u64 v[214:215], s[28:29], 0, v[130:131]
	s_mov_b32 m0, s49
	s_nop 0
	global_load_lds_dwordx4 v[214:215], off
	s_waitcnt vmcnt(8) lgkmcnt(0)
	s_barrier
	v_mfma_f32_16x16x32_bf16 v[124:127], v[142:145], v[174:177], v[124:127]
	v_mfma_f32_16x16x32_bf16 v[120:123], v[150:153], v[174:177], v[120:123]
	v_mfma_f32_16x16x32_bf16 v[116:119], v[142:145], v[182:185], v[116:119]
	v_mfma_f32_16x16x32_bf16 v[108:111], v[150:153], v[182:185], v[108:111]
	v_mfma_f32_16x16x32_bf16 v[100:103], v[142:145], v[194:197], v[100:103]
	v_mfma_f32_16x16x32_bf16 v[92:95], v[150:153], v[194:197], v[92:95]
	v_mfma_f32_16x16x32_bf16 v[84:87], v[142:145], v[202:205], v[84:87]
	v_mfma_f32_16x16x32_bf16 v[76:79], v[150:153], v[202:205], v[76:79]
	v_mfma_f32_16x16x32_bf16 v[124:127], v[146:149], v[178:181], v[124:127]
	v_mfma_f32_16x16x32_bf16 v[120:123], v[154:157], v[178:181], v[120:123]
	v_mfma_f32_16x16x32_bf16 v[116:119], v[146:149], v[186:189], v[116:119]
	v_mfma_f32_16x16x32_bf16 v[108:111], v[154:157], v[186:189], v[108:111]
	v_mfma_f32_16x16x32_bf16 v[100:103], v[146:149], v[198:201], v[100:103]
	v_mfma_f32_16x16x32_bf16 v[92:95], v[154:157], v[198:201], v[92:95]
	v_mfma_f32_16x16x32_bf16 v[84:87], v[146:149], v[206:209], v[84:87]
	v_mfma_f32_16x16x32_bf16 v[76:79], v[154:157], v[206:209], v[76:79]
	v_mfma_f32_16x16x32_bf16 v[112:115], v[158:161], v[174:177], v[112:115]
	v_mfma_f32_16x16x32_bf16 v[104:107], v[166:169], v[174:177], v[104:107]
	v_mfma_f32_16x16x32_bf16 v[96:99], v[158:161], v[182:185], v[96:99]
	v_mfma_f32_16x16x32_bf16 v[88:91], v[166:169], v[182:185], v[88:91]
	v_mfma_f32_16x16x32_bf16 v[80:83], v[158:161], v[194:197], v[80:83]
	v_mfma_f32_16x16x32_bf16 v[72:75], v[166:169], v[194:197], v[72:75]
	v_mfma_f32_16x16x32_bf16 v[68:71], v[158:161], v[202:205], v[68:71]
	v_mfma_f32_16x16x32_bf16 v[64:67], v[166:169], v[202:205], v[64:67]
	v_mfma_f32_16x16x32_bf16 v[112:115], v[162:165], v[178:181], v[112:115]
	v_mfma_f32_16x16x32_bf16 v[104:107], v[170:173], v[178:181], v[104:107]
	v_mfma_f32_16x16x32_bf16 v[96:99], v[162:165], v[186:189], v[96:99]
	v_mfma_f32_16x16x32_bf16 v[88:91], v[170:173], v[186:189], v[88:91]
	v_mfma_f32_16x16x32_bf16 v[80:83], v[162:165], v[198:201], v[80:83]
	v_mfma_f32_16x16x32_bf16 v[72:75], v[170:173], v[198:201], v[72:75]
	v_mfma_f32_16x16x32_bf16 v[68:71], v[162:165], v[206:209], v[68:71]
	v_mfma_f32_16x16x32_bf16 v[64:67], v[170:173], v[206:209], v[64:67]
	s_barrier
; #define PG8_STAGE(bufoff, gbase, voff) do { _Pragma("unroll") for (int _i = 0; _i < 2; ++_i) \
;         __builtin_amdgcn_global_load_lds((const unsigned*)((const char*)(gbase) + (voff)[_i]), (LAS unsigned*)(lds + (bufoff) + ldsw + _i * 8192), 16, 0, 0); } while (0)
; #define PG8_LDA(dst, b, h) do { _Pragma("unroll") for (int m = 0; m < 4; ++m) _Pragma("unroll") for (int k = 0; k < 2; ++k) dst[m][k] = *(const LAS bf16x8*)(lds + PG8_SA(b, h) + aoff + m * 2048 + k * 1024); } while (0)
; #define PG8_MMA(ai, bj, At, Bt) do { __builtin_amdgcn_s_setprio(1); _Pragma("unroll") for (int m = 0; m < 4; ++m) _Pragma("unroll") for (int n = 0; n < 2; ++n) _Pragma("unroll") for (int k = 0; k < 2; ++k) \
;         acc[ai][bj][m][n] = __builtin_amdgcn_mfma_f32_16x16x32_bf16(Bt[n][k], At[m][k], acc[ai][bj][m][n], 0, 0, 0); __builtin_amdgcn_s_setprio(0); } while (0)
; #define PG8_WAIT_V(n) asm volatile("s_waitcnt vmcnt(" #n ")" ::: "memory")
; #define PG8_WAIT_L(n) asm volatile("s_waitcnt lgkmcnt(" #n ")" ::: "memory")
; #define PG8_BAR __builtin_amdgcn_s_barrier()
; #define PG8_SCHED __builtin_amdgcn_sched_barrier(0)
; template <class Epi>
; DI void gemm_phase(int wv, LAS unsigned char* lds, LAS unsigned char* scr, const Sched& S, const Epi& E) {
;     ...
;             PG8_LDA(At, 1, 1); PG8_STAGE(PG8_SB(1, 0), b3, voffB); PG8_STAGE(PG8_SB(1, 1), b3 + hstepB, voffB); PG8_STAGE(PG8_SA(1, 0), a3, voffA);
;             PG8_WAIT_V(8); PG8_WAIT_L(0); PG8_BAR; PG8_MMA(1, 0, At, B0); PG8_MMA(1, 1, At, B1); PG8_BAR; PG8_SCHED;
;         }
;         if (wr == 0) PG8_BAR;
	s_mov_b32 m0, s21
	v_lshl_add_u64 v[138:139], v[138:139], 0, s[2:3]
	ds_read_b128 v[174:177], v141 offset:49152
	ds_read_b128 v[178:181], v141 offset:50176
	ds_read_b128 v[182:185], v141 offset:51200
	ds_read_b128 v[186:189], v141 offset:52224
	ds_read_b128 v[194:197], v141 offset:53248
	ds_read_b128 v[198:201], v141 offset:54272
	ds_read_b128 v[202:205], v141 offset:55296
	ds_read_b128 v[206:209], v141 offset:56320
	global_load_lds_dwordx4 v[138:139], off
	v_lshl_add_u64 v[138:139], v[190:191], 0, s[2:3]
	s_mov_b32 m0, s13
	s_nop 0
	global_load_lds_dwordx4 v[138:139], off
	v_lshl_add_u64 v[138:139], s[26:27], 0, v[132:133]
	s_mov_b32 m0, s65
	s_nop 0
	global_load_lds_dwordx4 v[138:139], off
	v_lshl_add_u64 v[138:139], s[26:27], 0, v[128:129]
	s_mov_b32 m0, s64
	s_nop 0
	global_load_lds_dwordx4 v[138:139], off
	v_lshl_add_u64 v[138:139], v[210:211], 0, s[2:3]
	s_mov_b32 m0, s52
	s_nop 0
	global_load_lds_dwordx4 v[138:139], off
	v_lshl_add_u64 v[138:139], v[212:213], 0, s[2:3]
	s_mov_b32 m0, s53
	s_nop 0
	global_load_lds_dwordx4 v[138:139], off
	s_waitcnt vmcnt(8) lgkmcnt(0)
	s_barrier
	v_mfma_f32_16x16x32_bf16 v[60:63], v[142:145], v[174:177], v[60:63]
	v_mfma_f32_16x16x32_bf16 v[56:59], v[150:153], v[174:177], v[56:59]
	v_mfma_f32_16x16x32_bf16 v[52:55], v[142:145], v[182:185], v[52:55]
	v_mfma_f32_16x16x32_bf16 v[44:47], v[150:153], v[182:185], v[44:47]
	v_mfma_f32_16x16x32_bf16 v[36:39], v[142:145], v[194:197], v[36:39]
	v_mfma_f32_16x16x32_bf16 v[28:31], v[150:153], v[194:197], v[28:31]
	v_mfma_f32_16x16x32_bf16 v[20:23], v[142:145], v[202:205], v[20:23]
	v_mfma_f32_16x16x32_bf16 v[12:15], v[150:153], v[202:205], v[12:15]
	v_mfma_f32_16x16x32_bf16 v[60:63], v[146:149], v[178:181], v[60:63]
	v_mfma_f32_16x16x32_bf16 v[56:59], v[154:157], v[178:181], v[56:59]
	v_mfma_f32_16x16x32_bf16 v[52:55], v[146:149], v[186:189], v[52:55]
	v_mfma_f32_16x16x32_bf16 v[44:47], v[154:157], v[186:189], v[44:47]
	v_mfma_f32_16x16x32_bf16 v[36:39], v[146:149], v[198:201], v[36:39]
	v_mfma_f32_16x16x32_bf16 v[28:31], v[154:157], v[198:201], v[28:31]
	v_mfma_f32_16x16x32_bf16 v[20:23], v[146:149], v[206:209], v[20:23]
	v_mfma_f32_16x16x32_bf16 v[12:15], v[154:157], v[206:209], v[12:15]
	v_mfma_f32_16x16x32_bf16 v[48:51], v[158:161], v[174:177], v[48:51]
	v_mfma_f32_16x16x32_bf16 v[40:43], v[166:169], v[174:177], v[40:43]
	v_mfma_f32_16x16x32_bf16 v[32:35], v[158:161], v[182:185], v[32:35]
	v_mfma_f32_16x16x32_bf16 v[24:27], v[166:169], v[182:185], v[24:27]
	v_mfma_f32_16x16x32_bf16 v[16:19], v[158:161], v[194:197], v[16:19]
	v_mfma_f32_16x16x32_bf16 v[8:11], v[166:169], v[194:197], v[8:11]
	v_mfma_f32_16x16x32_bf16 v[4:7], v[158:161], v[202:205], v[4:7]
	v_mfma_f32_16x16x32_bf16 v[0:3], v[166:169], v[202:205], v[0:3]
	v_mfma_f32_16x16x32_bf16 v[48:51], v[162:165], v[178:181], v[48:51]
	v_mfma_f32_16x16x32_bf16 v[40:43], v[170:173], v[178:181], v[40:43]
	v_mfma_f32_16x16x32_bf16 v[32:35], v[162:165], v[186:189], v[32:35]
	v_mfma_f32_16x16x32_bf16 v[24:27], v[170:173], v[186:189], v[24:27]
	v_mfma_f32_16x16x32_bf16 v[16:19], v[162:165], v[198:201], v[16:19]
	v_mfma_f32_16x16x32_bf16 v[8:11], v[170:173], v[198:201], v[8:11]
	v_mfma_f32_16x16x32_bf16 v[4:7], v[162:165], v[206:209], v[4:7]
	v_mfma_f32_16x16x32_bf16 v[0:3], v[170:173], v[206:209], v[0:3]
	s_barrier
	s_movk_i32 s13, 0x100
	s_andn2_b64 vcc, exec, s[24:25]
	s_mov_b64 s[26:27], -1
	s_mov_b64 s[24:25], 0
	s_cbranch_vccz .LBB0_256
	s_and_b64 vcc, exec, s[10:11]
	s_cbranch_vccz .LBB0_259
	s_barrier

; #define PG8_STAGE(bufoff, gbase, voff) do { _Pragma("unroll") for (int _i = 0; _i < 2; ++_i) \
;         __builtin_amdgcn_global_load_lds((const unsigned*)((const char*)(gbase) + (voff)[_i]), (LAS unsigned*)(lds + (bufoff) + ldsw + _i * 8192), 16, 0, 0); } while (0)
; #define PG8_LDA(dst, b, h) do { _Pragma("unroll") for (int m = 0; m < 4; ++m) _Pragma("unroll") for (int k = 0; k < 2; ++k) dst[m][k] = *(const LAS bf16x8*)(lds + PG8_SA(b, h) + aoff + m * 2048 + k * 1024); } while (0)
; #define PG8_LDB(dst, b, h) do { _Pragma("unroll") for (int n = 0; n < 2; ++n) _Pragma("unroll") for (int k = 0; k < 2; ++k) dst[n][k] = *(const LAS bf16x8*)(lds + PG8_SB(b, h) + boff + n * 2048 + k * 1024); } while (0)
; #define PG8_MMA(ai, bj, At, Bt) do { __builtin_amdgcn_s_setprio(1); _Pragma("unroll") for (int m = 0; m < 4; ++m) _Pragma("unroll") for (int n = 0; n < 2; ++n) _Pragma("unroll") for (int k = 0; k < 2; ++k) \
;         acc[ai][bj][m][n] = __builtin_amdgcn_mfma_f32_16x16x32_bf16(Bt[n][k], At[m][k], acc[ai][bj][m][n], 0, 0, 0); __builtin_amdgcn_s_setprio(0); } while (0)
; #define PG8_WAIT_V(n) asm volatile("s_waitcnt vmcnt(" #n ")" ::: "memory")
; #define PG8_WAIT_L(n) asm volatile("s_waitcnt lgkmcnt(" #n ")" ::: "memory")
; #define PG8_BAR __builtin_amdgcn_s_barrier()
; #define PG8_SCHED __builtin_amdgcn_sched_barrier(0)
; template <class Epi>
; DI void gemm_phase(int wv, LAS unsigned char* lds, LAS unsigned char* scr, const Sched& S, const Epi& E) {
;     ...
;         const bool has_next = S.next(ui + 1, nxt);
;         const char* nA = has_next ? S.baseA(nxt) : cA; const char* nB = has_next ? S.baseB(nxt) : cB;
;         for (int t = 0; t < nt; t += 2) {
;             const bool last = (t == nt - 2);
;             const char* a1 = cA + (size_t)(t + 1) * kstep;
;             const char* a2 = last ? nA : cA + (size_t)(t + 2) * kstep; const char* b2 = last ? nB : cB + (size_t)(t + 2) * kstep;
;             const char* a3 = a2 + kstep; const char* b3 = b2 + kstep;
;             PG8_LDB(B0, 0, 0); PG8_LDB(B1, 0, 1); PG8_SCHED; PG8_LDA(At, 0, 0); PG8_STAGE(PG8_SA(1, 1), a1 + hstepA, voffA);
;             PG8_WAIT_V(8); PG8_WAIT_L(0); PG8_BAR; PG8_MMA(0, 0, At, B0); PG8_MMA(0, 1, At, B1); PG8_BAR; PG8_SCHED;
;             PG8_LDA(At, 0, 1); PG8_STAGE(PG8_SB(0, 0), b2, voffB); PG8_STAGE(PG8_SB(0, 1), b2 + hstepB, voffB); PG8_STAGE(PG8_SA(0, 0), a2, voffA);
.LBB0_277:
	s_add_u32 s21, s14, s13
	s_addc_u32 s34, s15, 0
	s_add_u32 s28, s21, 0x100
	s_addc_u32 s29, s34, 0
	s_and_b64 s[26:27], s[24:25], exec
	s_cselect_b32 s29, s9, s29
	s_cselect_b32 s28, s8, s28
	s_add_u32 s13, s16, s13
	s_addc_u32 s26, s17, 0
	s_add_u32 s13, s13, 0x100
	s_addc_u32 s26, s26, 0
	s_add_i32 s64, 0, 0x10000
	s_and_b64 s[24:25], s[24:25], exec
	s_cselect_b32 s31, s19, s26
	s_cselect_b32 s30, s18, s13
	s_add_i32 s25, 0, 0x14000
	s_add_u32 s36, s21, 0x40080
	s_addc_u32 s37, s34, 0
	s_add_i32 s63, s64, s43
	s_add_i32 m0, s44, 0xc000
	s_add_i32 s66, s44, 0xe000
	s_add_i32 s60, s63, 0x2000
	s_add_u32 s34, s30, 0x40000
	v_add_u32_e32 v152, s64, v138
	v_add_u32_e32 v168, s25, v138
	s_addc_u32 s35, s31, 0
	s_add_i32 s62, s25, s43
	ds_read_b128 v[140:143], v152
	ds_read_b128 v[144:147], v152 offset:1024
	ds_read_b128 v[148:151], v152 offset:2048
	ds_read_b128 v[152:155], v152 offset:3072
	ds_read_b128 v[156:159], v168
	ds_read_b128 v[160:163], v168 offset:1024
	ds_read_b128 v[164:167], v168 offset:2048
	ds_read_b128 v[168:171], v168 offset:3072
	s_add_i32 s61, s62, 0x2000
	s_add_i32 s59, 0, 0x18000
	s_add_i32 s55, 0, 0x1c000
	s_add_u32 s26, s28, 0x40000
	s_addc_u32 s27, s29, 0
	s_add_i32 s21, s59, s43
	s_add_i32 s13, s21, 0x2000
	s_add_u32 s24, s30, 0x40080
	s_addc_u32 s25, s31, 0
	s_add_i32 s65, s55, s43
	s_add_i32 s64, s65, 0x2000
	v_lshl_add_u64 v[206:207], s[36:37], 0, v[134:135]
	ds_read_b128 v[172:175], v139
	ds_read_b128 v[176:179], v139 offset:1024
	ds_read_b128 v[180:183], v139 offset:2048
	ds_read_b128 v[184:187], v139 offset:3072
	ds_read_b128 v[188:191], v139 offset:4096
	ds_read_b128 v[194:197], v139 offset:5120
	ds_read_b128 v[198:201], v139 offset:6144
	ds_read_b128 v[202:205], v139 offset:7168
	global_load_lds_dwordx4 v[206:207], off
	v_lshl_add_u64 v[206:207], s[36:37], 0, v[130:131]
	s_mov_b32 m0, s66
	s_nop 0
	global_load_lds_dwordx4 v[206:207], off
	s_waitcnt vmcnt(8) lgkmcnt(0)
	s_barrier
	v_mfma_f32_16x16x32_bf16 v[124:127], v[140:143], v[172:175], v[124:127]
	v_mfma_f32_16x16x32_bf16 v[120:123], v[148:151], v[172:175], v[120:123]
	v_mfma_f32_16x16x32_bf16 v[116:119], v[140:143], v[180:183], v[116:119]
	v_mfma_f32_16x16x32_bf16 v[112:115], v[148:151], v[180:183], v[112:115]
	v_mfma_f32_16x16x32_bf16 v[100:103], v[140:143], v[188:191], v[100:103]
	v_mfma_f32_16x16x32_bf16 v[96:99], v[148:151], v[188:191], v[96:99]
	v_mfma_f32_16x16x32_bf16 v[84:87], v[140:143], v[198:201], v[84:87]
	v_mfma_f32_16x16x32_bf16 v[80:83], v[148:151], v[198:201], v[80:83]
	v_mfma_f32_16x16x32_bf16 v[124:127], v[144:147], v[176:179], v[124:127]
	v_mfma_f32_16x16x32_bf16 v[120:123], v[152:155], v[176:179], v[120:123]
	v_mfma_f32_16x16x32_bf16 v[116:119], v[144:147], v[184:187], v[116:119]
	v_mfma_f32_16x16x32_bf16 v[112:115], v[152:155], v[184:187], v[112:115]
	v_mfma_f32_16x16x32_bf16 v[100:103], v[144:147], v[194:197], v[100:103]
	v_mfma_f32_16x16x32_bf16 v[96:99], v[152:155], v[194:197], v[96:99]
	v_mfma_f32_16x16x32_bf16 v[84:87], v[144:147], v[202:205], v[84:87]
	v_mfma_f32_16x16x32_bf16 v[80:83], v[152:155], v[202:205], v[80:83]
	v_mfma_f32_16x16x32_bf16 v[108:111], v[156:159], v[172:175], v[108:111]
	v_mfma_f32_16x16x32_bf16 v[104:107], v[164:167], v[172:175], v[104:107]
	v_mfma_f32_16x16x32_bf16 v[92:95], v[156:159], v[180:183], v[92:95]
	v_mfma_f32_16x16x32_bf16 v[88:91], v[164:167], v[180:183], v[88:91]
	v_mfma_f32_16x16x32_bf16 v[76:79], v[156:159], v[188:191], v[76:79]
	v_mfma_f32_16x16x32_bf16 v[72:75], v[164:167], v[188:191], v[72:75]
	v_mfma_f32_16x16x32_bf16 v[68:71], v[156:159], v[198:201], v[68:71]
	v_mfma_f32_16x16x32_bf16 v[64:67], v[164:167], v[198:201], v[64:67]
	v_mfma_f32_16x16x32_bf16 v[108:111], v[160:163], v[176:179], v[108:111]
	v_mfma_f32_16x16x32_bf16 v[104:107], v[168:171], v[176:179], v[104:107]
	v_mfma_f32_16x16x32_bf16 v[92:95], v[160:163], v[184:187], v[92:95]
	v_mfma_f32_16x16x32_bf16 v[88:91], v[168:171], v[184:187], v[88:91]
	v_mfma_f32_16x16x32_bf16 v[76:79], v[160:163], v[194:197], v[76:79]
	v_mfma_f32_16x16x32_bf16 v[72:75], v[168:171], v[194:197], v[72:75]
	v_mfma_f32_16x16x32_bf16 v[68:71], v[160:163], v[202:205], v[68:71]
	v_mfma_f32_16x16x32_bf16 v[64:67], v[168:171], v[202:205], v[64:67]
	s_barrier
	s_mov_b32 m0, s63
	v_lshl_add_u64 v[206:207], s[30:31], 0, v[132:133]
	ds_read_b128 v[172:175], v139 offset:16384
	ds_read_b128 v[176:179], v139 offset:17408
	ds_read_b128 v[180:183], v139 offset:18432
	ds_read_b128 v[184:187], v139 offset:19456
	ds_read_b128 v[188:191], v139 offset:20480
	ds_read_b128 v[194:197], v139 offset:21504
	ds_read_b128 v[198:201], v139 offset:22528
	ds_read_b128 v[202:205], v139 offset:23552
	global_load_lds_dwordx4 v[206:207], off
	v_lshl_add_u64 v[208:209], s[30:31], 0, v[128:129]
	s_mov_b32 m0, s60
	v_lshl_add_u64 v[210:211], s[34:35], 0, v[132:133]
	global_load_lds_dwordx4 v[208:209], off
	s_mov_b32 m0, s62
	v_lshl_add_u64 v[212:213], s[28:29], 0, v[130:131]
	global_load_lds_dwordx4 v[210:211], off
	v_lshl_add_u64 v[210:211], s[34:35], 0, v[128:129]
	s_mov_b32 m0, s61
	s_nop 0
	global_load_lds_dwordx4 v[210:211], off
	v_lshl_add_u64 v[210:211], s[28:29], 0, v[134:135]
	s_mov_b32 m0, s44
	s_nop 0
	global_load_lds_dwordx4 v[210:211], off
	s_mov_b32 m0, s45
	s_nop 0
	global_load_lds_dwordx4 v[212:213], off
	s_waitcnt vmcnt(8) lgkmcnt(0)
	s_barrier
; #define PG8_STAGE(bufoff, gbase, voff) do { _Pragma("unroll") for (int _i = 0; _i < 2; ++_i) \
;         __builtin_amdgcn_global_load_lds((const unsigned*)((const char*)(gbase) + (voff)[_i]), (LAS unsigned*)(lds + (bufoff) + ldsw + _i * 8192), 16, 0, 0); } while (0)
; #define PG8_LDA(dst, b, h) do { _Pragma("unroll") for (int m = 0; m < 4; ++m) _Pragma("unroll") for (int k = 0; k < 2; ++k) dst[m][k] = *(const LAS bf16x8*)(lds + PG8_SA(b, h) + aoff + m * 2048 + k * 1024); } while (0)
; #define PG8_LDB(dst, b, h) do { _Pragma("unroll") for (int n = 0; n < 2; ++n) _Pragma("unroll") for (int k = 0; k < 2; ++k) dst[n][k] = *(const LAS bf16x8*)(lds + PG8_SB(b, h) + boff + n * 2048 + k * 1024); } while (0)
; #define PG8_MMA(ai, bj, At, Bt) do { __builtin_amdgcn_s_setprio(1); _Pragma("unroll") for (int m = 0; m < 4; ++m) _Pragma("unroll") for (int n = 0; n < 2; ++n) _Pragma("unroll") for (int k = 0; k < 2; ++k) \
;         acc[ai][bj][m][n] = __builtin_amdgcn_mfma_f32_16x16x32_bf16(Bt[n][k], At[m][k], acc[ai][bj][m][n], 0, 0, 0); __builtin_amdgcn_s_setprio(0); } while (0)
; #define PG8_WAIT_V(n) asm volatile("s_waitcnt vmcnt(" #n ")" ::: "memory")
; #define PG8_WAIT_L(n) asm volatile("s_waitcnt lgkmcnt(" #n ")" ::: "memory")
; #define PG8_BAR __builtin_amdgcn_s_barrier()
; #define PG8_SCHED __builtin_amdgcn_sched_barrier(0)
; template <class Epi>
; DI void gemm_phase(int wv, LAS unsigned char* lds, LAS unsigned char* scr, const Sched& S, const Epi& E) {
;     ...
;             PG8_WAIT_V(8); PG8_WAIT_L(0); PG8_BAR; PG8_MMA(1, 0, At, B0); PG8_MMA(1, 1, At, B1); PG8_BAR; PG8_SCHED;
;             PG8_LDB(B0, 1, 0); PG8_LDB(B1, 1, 1); PG8_SCHED; PG8_LDA(At, 1, 0); PG8_STAGE(PG8_SA(0, 1), a2 + hstepA, voffA);
;             PG8_WAIT_V(8); PG8_WAIT_L(0); PG8_BAR; PG8_MMA(0, 0, At, B0); PG8_MMA(0, 1, At, B1); PG8_BAR; PG8_SCHED;
	v_mfma_f32_16x16x32_bf16 v[60:63], v[140:143], v[172:175], v[60:63]
	v_mfma_f32_16x16x32_bf16 v[56:59], v[148:151], v[172:175], v[56:59]
	v_mfma_f32_16x16x32_bf16 v[52:55], v[140:143], v[180:183], v[52:55]
	v_mfma_f32_16x16x32_bf16 v[48:51], v[148:151], v[180:183], v[48:51]
	v_mfma_f32_16x16x32_bf16 v[36:39], v[140:143], v[188:191], v[36:39]
	v_mfma_f32_16x16x32_bf16 v[32:35], v[148:151], v[188:191], v[32:35]
	v_mfma_f32_16x16x32_bf16 v[20:23], v[140:143], v[198:201], v[20:23]
	v_mfma_f32_16x16x32_bf16 v[16:19], v[148:151], v[198:201], v[16:19]
	v_mfma_f32_16x16x32_bf16 v[60:63], v[144:147], v[176:179], v[60:63]
	v_mfma_f32_16x16x32_bf16 v[56:59], v[152:155], v[176:179], v[56:59]
	v_mfma_f32_16x16x32_bf16 v[52:55], v[144:147], v[184:187], v[52:55]
	v_mfma_f32_16x16x32_bf16 v[48:51], v[152:155], v[184:187], v[48:51]
	v_mfma_f32_16x16x32_bf16 v[36:39], v[144:147], v[194:197], v[36:39]
	v_mfma_f32_16x16x32_bf16 v[32:35], v[152:155], v[194:197], v[32:35]
	v_mfma_f32_16x16x32_bf16 v[20:23], v[144:147], v[202:205], v[20:23]
	v_mfma_f32_16x16x32_bf16 v[16:19], v[152:155], v[202:205], v[16:19]
	v_mfma_f32_16x16x32_bf16 v[44:47], v[156:159], v[172:175], v[44:47]
	v_mfma_f32_16x16x32_bf16 v[40:43], v[164:167], v[172:175], v[40:43]
	v_mfma_f32_16x16x32_bf16 v[28:31], v[156:159], v[180:183], v[28:31]
	v_mfma_f32_16x16x32_bf16 v[24:27], v[164:167], v[180:183], v[24:27]
	v_mfma_f32_16x16x32_bf16 v[12:15], v[156:159], v[188:191], v[12:15]
	v_mfma_f32_16x16x32_bf16 v[8:11], v[164:167], v[188:191], v[8:11]
	v_mfma_f32_16x16x32_bf16 v[4:7], v[156:159], v[198:201], v[4:7]
	v_mfma_f32_16x16x32_bf16 v[0:3], v[164:167], v[198:201], v[0:3]
	v_mfma_f32_16x16x32_bf16 v[44:47], v[160:163], v[176:179], v[44:47]
	v_mfma_f32_16x16x32_bf16 v[40:43], v[168:171], v[176:179], v[40:43]
	v_mfma_f32_16x16x32_bf16 v[28:31], v[160:163], v[184:187], v[28:31]
	v_mfma_f32_16x16x32_bf16 v[24:27], v[168:171], v[184:187], v[24:27]
	v_mfma_f32_16x16x32_bf16 v[12:15], v[160:163], v[194:197], v[12:15]
	v_mfma_f32_16x16x32_bf16 v[8:11], v[168:171], v[194:197], v[8:11]
	v_mfma_f32_16x16x32_bf16 v[4:7], v[160:163], v[202:205], v[4:7]
	v_mfma_f32_16x16x32_bf16 v[0:3], v[168:171], v[202:205], v[0:3]
	s_barrier
	v_add_u32_e32 v152, s59, v138
	v_add_u32_e32 v168, s55, v138
	ds_read_b128 v[140:143], v152
	ds_read_b128 v[144:147], v152 offset:1024
	ds_read_b128 v[148:151], v152 offset:2048
	ds_read_b128 v[152:155], v152 offset:3072
	ds_read_b128 v[156:159], v168
	ds_read_b128 v[160:163], v168 offset:1024
	ds_read_b128 v[164:167], v168 offset:2048
	ds_read_b128 v[168:171], v168 offset:3072
	s_mov_b32 m0, s46
	v_lshl_add_u64 v[214:215], s[26:27], 0, v[134:135]
	ds_read_b128 v[172:175], v139 offset:32768
	ds_read_b128 v[176:179], v139 offset:33792
	ds_read_b128 v[180:183], v139 offset:34816
	ds_read_b128 v[184:187], v139 offset:35840
	ds_read_b128 v[188:191], v139 offset:36864
	ds_read_b128 v[194:197], v139 offset:37888
	ds_read_b128 v[198:201], v139 offset:38912
	ds_read_b128 v[202:205], v139 offset:39936
	global_load_lds_dwordx4 v[214:215], off
	v_lshl_add_u64 v[214:215], s[26:27], 0, v[130:131]
	s_mov_b32 m0, s47
	s_nop 0
	global_load_lds_dwordx4 v[214:215], off
	s_waitcnt vmcnt(8) lgkmcnt(0)
	s_barrier
	v_mfma_f32_16x16x32_bf16 v[124:127], v[140:143], v[172:175], v[124:127]
	v_mfma_f32_16x16x32_bf16 v[120:123], v[148:151], v[172:175], v[120:123]
	v_mfma_f32_16x16x32_bf16 v[116:119], v[140:143], v[180:183], v[116:119]
	v_mfma_f32_16x16x32_bf16 v[112:115], v[148:151], v[180:183], v[112:115]
	v_mfma_f32_16x16x32_bf16 v[100:103], v[140:143], v[188:191], v[100:103]
	v_mfma_f32_16x16x32_bf16 v[96:99], v[148:151], v[188:191], v[96:99]
	v_mfma_f32_16x16x32_bf16 v[84:87], v[140:143], v[198:201], v[84:87]
	v_mfma_f32_16x16x32_bf16 v[80:83], v[148:151], v[198:201], v[80:83]
	v_mfma_f32_16x16x32_bf16 v[124:127], v[144:147], v[176:179], v[124:127]
	v_mfma_f32_16x16x32_bf16 v[120:123], v[152:155], v[176:179], v[120:123]
	v_mfma_f32_16x16x32_bf16 v[116:119], v[144:147], v[184:187], v[116:119]
	v_mfma_f32_16x16x32_bf16 v[112:115], v[152:155], v[184:187], v[112:115]
	v_mfma_f32_16x16x32_bf16 v[100:103], v[144:147], v[194:197], v[100:103]
	v_mfma_f32_16x16x32_bf16 v[96:99], v[152:155], v[194:197], v[96:99]
	v_mfma_f32_16x16x32_bf16 v[84:87], v[144:147], v[202:205], v[84:87]
	v_mfma_f32_16x16x32_bf16 v[80:83], v[152:155], v[202:205], v[80:83]
	v_mfma_f32_16x16x32_bf16 v[108:111], v[156:159], v[172:175], v[108:111]
	v_mfma_f32_16x16x32_bf16 v[104:107], v[164:167], v[172:175], v[104:107]
	v_mfma_f32_16x16x32_bf16 v[92:95], v[156:159], v[180:183], v[92:95]
	v_mfma_f32_16x16x32_bf16 v[88:91], v[164:167], v[180:183], v[88:91]
	v_mfma_f32_16x16x32_bf16 v[76:79], v[156:159], v[188:191], v[76:79]
	v_mfma_f32_16x16x32_bf16 v[72:75], v[164:167], v[188:191], v[72:75]
	v_mfma_f32_16x16x32_bf16 v[68:71], v[156:159], v[198:201], v[68:71]
	v_mfma_f32_16x16x32_bf16 v[64:67], v[164:167], v[198:201], v[64:67]
	v_mfma_f32_16x16x32_bf16 v[108:111], v[160:163], v[176:179], v[108:111]
	v_mfma_f32_16x16x32_bf16 v[104:107], v[168:171], v[176:179], v[104:107]
	v_mfma_f32_16x16x32_bf16 v[92:95], v[160:163], v[184:187], v[92:95]
	v_mfma_f32_16x16x32_bf16 v[88:91], v[168:171], v[184:187], v[88:91]
	v_mfma_f32_16x16x32_bf16 v[76:79], v[160:163], v[194:197], v[76:79]
	v_mfma_f32_16x16x32_bf16 v[72:75], v[168:171], v[194:197], v[72:75]
	v_mfma_f32_16x16x32_bf16 v[68:71], v[160:163], v[202:205], v[68:71]
	v_mfma_f32_16x16x32_bf16 v[64:67], v[168:171], v[202:205], v[64:67]
	s_barrier
; #define PG8_STAGE(bufoff, gbase, voff) do { _Pragma("unroll") for (int _i = 0; _i < 2; ++_i) \
;         __builtin_amdgcn_global_load_lds((const unsigned*)((const char*)(gbase) + (voff)[_i]), (LAS unsigned*)(lds + (bufoff) + ldsw + _i * 8192), 16, 0, 0); } while (0)
; #define PG8_LDA(dst, b, h) do { _Pragma("unroll") for (int m = 0; m < 4; ++m) _Pragma("unroll") for (int k = 0; k < 2; ++k) dst[m][k] = *(const LAS bf16x8*)(lds + PG8_SA(b, h) + aoff + m * 2048 + k * 1024); } while (0)
; #define PG8_MMA(ai, bj, At, Bt) do { __builtin_amdgcn_s_setprio(1); _Pragma("unroll") for (int m = 0; m < 4; ++m) _Pragma("unroll") for (int n = 0; n < 2; ++n) _Pragma("unroll") for (int k = 0; k < 2; ++k) \
;         acc[ai][bj][m][n] = __builtin_amdgcn_mfma_f32_16x16x32_bf16(Bt[n][k], At[m][k], acc[ai][bj][m][n], 0, 0, 0); __builtin_amdgcn_s_setprio(0); } while (0)
; #define PG8_WAIT_V(n) asm volatile("s_waitcnt vmcnt(" #n ")" ::: "memory")
; #define PG8_WAIT_L(n) asm volatile("s_waitcnt lgkmcnt(" #n ")" ::: "memory")
; #define PG8_BAR __builtin_amdgcn_s_barrier()
; #define PG8_SCHED __builtin_amdgcn_sched_barrier(0)
; template <class Epi>
; DI void gemm_phase(int wv, LAS unsigned char* lds, LAS unsigned char* scr, const Sched& S, const Epi& E) {
;     ...
;             PG8_LDA(At, 1, 1); PG8_STAGE(PG8_SB(1, 0), b3, voffB); PG8_STAGE(PG8_SB(1, 1), b3 + hstepB, voffB); PG8_STAGE(PG8_SA(1, 0), a3, voffA);
;             PG8_WAIT_V(8); PG8_WAIT_L(0); PG8_BAR; PG8_MMA(1, 0, At, B0); PG8_MMA(1, 1, At, B1); PG8_BAR; PG8_SCHED;
;         }
;         if (wr == 0) PG8_BAR;
	s_mov_b32 m0, s21
	v_lshl_add_u64 v[206:207], v[206:207], 0, s[2:3]
	ds_read_b128 v[172:175], v139 offset:49152
	ds_read_b128 v[176:179], v139 offset:50176
	ds_read_b128 v[180:183], v139 offset:51200
	ds_read_b128 v[184:187], v139 offset:52224
	ds_read_b128 v[188:191], v139 offset:53248
	ds_read_b128 v[194:197], v139 offset:54272
	ds_read_b128 v[198:201], v139 offset:55296
	ds_read_b128 v[202:205], v139 offset:56320
	global_load_lds_dwordx4 v[206:207], off
	v_lshl_add_u64 v[206:207], v[208:209], 0, s[2:3]
	s_mov_b32 m0, s13
	s_nop 0
	global_load_lds_dwordx4 v[206:207], off
	v_lshl_add_u64 v[206:207], s[24:25], 0, v[132:133]
	s_mov_b32 m0, s65
	s_nop 0
	global_load_lds_dwordx4 v[206:207], off
	v_lshl_add_u64 v[206:207], s[24:25], 0, v[128:129]
	s_mov_b32 m0, s64
	s_nop 0
	global_load_lds_dwordx4 v[206:207], off
	v_lshl_add_u64 v[206:207], v[210:211], 0, s[2:3]
	s_mov_b32 m0, s50
	s_nop 0
	global_load_lds_dwordx4 v[206:207], off
	v_lshl_add_u64 v[206:207], v[212:213], 0, s[2:3]
	s_mov_b32 m0, s51
	s_nop 0
	global_load_lds_dwordx4 v[206:207], off
	s_waitcnt vmcnt(8) lgkmcnt(0)
	s_barrier
	v_mfma_f32_16x16x32_bf16 v[60:63], v[140:143], v[172:175], v[60:63]
	v_mfma_f32_16x16x32_bf16 v[56:59], v[148:151], v[172:175], v[56:59]
	v_mfma_f32_16x16x32_bf16 v[52:55], v[140:143], v[180:183], v[52:55]
	v_mfma_f32_16x16x32_bf16 v[48:51], v[148:151], v[180:183], v[48:51]
	v_mfma_f32_16x16x32_bf16 v[36:39], v[140:143], v[188:191], v[36:39]
	v_mfma_f32_16x16x32_bf16 v[32:35], v[148:151], v[188:191], v[32:35]
	v_mfma_f32_16x16x32_bf16 v[20:23], v[140:143], v[198:201], v[20:23]
	v_mfma_f32_16x16x32_bf16 v[16:19], v[148:151], v[198:201], v[16:19]
	v_mfma_f32_16x16x32_bf16 v[60:63], v[144:147], v[176:179], v[60:63]
	v_mfma_f32_16x16x32_bf16 v[56:59], v[152:155], v[176:179], v[56:59]
	v_mfma_f32_16x16x32_bf16 v[52:55], v[144:147], v[184:187], v[52:55]
	v_mfma_f32_16x16x32_bf16 v[48:51], v[152:155], v[184:187], v[48:51]
	v_mfma_f32_16x16x32_bf16 v[36:39], v[144:147], v[194:197], v[36:39]
	v_mfma_f32_16x16x32_bf16 v[32:35], v[152:155], v[194:197], v[32:35]
	v_mfma_f32_16x16x32_bf16 v[20:23], v[144:147], v[202:205], v[20:23]
	v_mfma_f32_16x16x32_bf16 v[16:19], v[152:155], v[202:205], v[16:19]
	v_mfma_f32_16x16x32_bf16 v[44:47], v[156:159], v[172:175], v[44:47]
	v_mfma_f32_16x16x32_bf16 v[40:43], v[164:167], v[172:175], v[40:43]
	v_mfma_f32_16x16x32_bf16 v[28:31], v[156:159], v[180:183], v[28:31]
	v_mfma_f32_16x16x32_bf16 v[24:27], v[164:167], v[180:183], v[24:27]
	v_mfma_f32_16x16x32_bf16 v[12:15], v[156:159], v[188:191], v[12:15]
	v_mfma_f32_16x16x32_bf16 v[8:11], v[164:167], v[188:191], v[8:11]
	v_mfma_f32_16x16x32_bf16 v[4:7], v[156:159], v[198:201], v[4:7]
	v_mfma_f32_16x16x32_bf16 v[0:3], v[164:167], v[198:201], v[0:3]
	v_mfma_f32_16x16x32_bf16 v[44:47], v[160:163], v[176:179], v[44:47]
	v_mfma_f32_16x16x32_bf16 v[40:43], v[168:171], v[176:179], v[40:43]
	v_mfma_f32_16x16x32_bf16 v[28:31], v[160:163], v[184:187], v[28:31]
	v_mfma_f32_16x16x32_bf16 v[24:27], v[168:171], v[184:187], v[24:27]
	v_mfma_f32_16x16x32_bf16 v[12:15], v[160:163], v[194:197], v[12:15]
	v_mfma_f32_16x16x32_bf16 v[8:11], v[168:171], v[194:197], v[8:11]
	v_mfma_f32_16x16x32_bf16 v[4:7], v[160:163], v[202:205], v[4:7]
	v_mfma_f32_16x16x32_bf16 v[0:3], v[168:171], v[202:205], v[0:3]
	s_barrier
	s_movk_i32 s13, 0x100
	s_andn2_b64 vcc, exec, s[22:23]
	s_mov_b64 s[24:25], -1
	s_mov_b64 s[22:23], 0
	s_cbranch_vccz .LBB0_277
	s_and_b64 vcc, exec, s[10:11]
	s_cbranch_vccz .LBB0_280
	s_barrier

; #define PG8_STAGE(bufoff, gbase, voff) do { _Pragma("unroll") for (int _i = 0; _i < 2; ++_i) \
;         __builtin_amdgcn_global_load_lds((const unsigned*)((const char*)(gbase) + (voff)[_i]), (LAS unsigned*)(lds + (bufoff) + ldsw + _i * 8192), 16, 0, 0); } while (0)
; #define PG8_LDA(dst, b, h) do { _Pragma("unroll") for (int m = 0; m < 4; ++m) _Pragma("unroll") for (int k = 0; k < 2; ++k) dst[m][k] = *(const LAS bf16x8*)(lds + PG8_SA(b, h) + aoff + m * 2048 + k * 1024); } while (0)
; #define PG8_LDB(dst, b, h) do { _Pragma("unroll") for (int n = 0; n < 2; ++n) _Pragma("unroll") for (int k = 0; k < 2; ++k) dst[n][k] = *(const LAS bf16x8*)(lds + PG8_SB(b, h) + boff + n * 2048 + k * 1024); } while (0)
; #define PG8_MMA(ai, bj, At, Bt) do { __builtin_amdgcn_s_setprio(1); _Pragma("unroll") for (int m = 0; m < 4; ++m) _Pragma("unroll") for (int n = 0; n < 2; ++n) _Pragma("unroll") for (int k = 0; k < 2; ++k) \
;         acc[ai][bj][m][n] = __builtin_amdgcn_mfma_f32_16x16x32_bf16(Bt[n][k], At[m][k], acc[ai][bj][m][n], 0, 0, 0); __builtin_amdgcn_s_setprio(0); } while (0)
; #define PG8_WAIT_V(n) asm volatile("s_waitcnt vmcnt(" #n ")" ::: "memory")
; #define PG8_WAIT_L(n) asm volatile("s_waitcnt lgkmcnt(" #n ")" ::: "memory")
; #define PG8_BAR __builtin_amdgcn_s_barrier()
; #define PG8_SCHED __builtin_amdgcn_sched_barrier(0)
; template <class Epi>
; DI void gemm_phase(int wv, LAS unsigned char* lds, LAS unsigned char* scr, const Sched& S, const Epi& E) {
;     ...
;             const bool last = (t == nt - 2);
;             const char* a1 = cA + (size_t)(t + 1) * kstep;
;             const char* a2 = last ? nA : cA + (size_t)(t + 2) * kstep; const char* b2 = last ? nB : cB + (size_t)(t + 2) * kstep;
;             const char* a3 = a2 + kstep; const char* b3 = b2 + kstep;
;             PG8_LDB(B0, 0, 0); PG8_LDB(B1, 0, 1); PG8_SCHED; PG8_LDA(At, 0, 0); PG8_STAGE(PG8_SA(1, 1), a1 + hstepA, voffA);
;             PG8_WAIT_V(8); PG8_WAIT_L(0); PG8_BAR; PG8_MMA(0, 0, At, B0); PG8_MMA(0, 1, At, B1); PG8_BAR; PG8_SCHED;
;             PG8_LDA(At, 0, 1); PG8_STAGE(PG8_SB(0, 0), b2, voffB); PG8_STAGE(PG8_SB(0, 1), b2 + hstepB, voffB); PG8_STAGE(PG8_SA(0, 0), a2, voffA);
.LBB0_463:
	s_add_u32 s24, s22, 0xfffc0080
	s_addc_u32 s25, s23, -1
	s_add_i32 s48, 0, 0x10000
	s_cmp_eq_u32 s47, 12
	s_cselect_b32 s27, s11, s25
	s_cselect_b32 s26, s15, s24
	v_add_u32_e32 v143, s48, v144
	s_cselect_b32 s25, s13, s46
	s_cselect_b32 s24, s21, s45
	s_add_i32 s50, 0, 0x14000
	ds_read_b128 v[146:149], v143
	ds_read_b128 v[150:153], v143 offset:1024
	ds_read_b128 v[154:157], v143 offset:2048
	ds_read_b128 v[158:161], v143 offset:3072
	v_add_u32_e32 v143, s50, v144
	ds_read_b128 v[162:165], v143
	ds_read_b128 v[166:169], v143 offset:1024
	ds_read_b128 v[170:173], v143 offset:2048
	ds_read_b128 v[174:177], v143 offset:3072
	v_lshl_add_u64 v[190:191], s[22:23], 0, v[140:141]
	s_add_i32 m0, s34, 0xc000
	ds_read_b128 v[178:181], v145
	ds_read_b128 v[182:185], v145 offset:1024
	ds_read_b128 v[186:189], v145 offset:2048
	ds_read_b128 v[194:197], v145 offset:3072
	ds_read_b128 v[198:201], v145 offset:4096
	ds_read_b128 v[202:205], v145 offset:5120
	ds_read_b128 v[206:209], v145 offset:6144
	ds_read_b128 v[210:213], v145 offset:7168
	global_load_lds_dwordx4 v[190:191], off
	v_lshl_add_u64 v[190:191], s[22:23], 0, v[138:139]
	s_add_i32 m0, s34, 0xe000
	s_nop 0
	global_load_lds_dwordx4 v[190:191], off
	s_waitcnt vmcnt(8) lgkmcnt(0)
	s_barrier
	v_mfma_f32_16x16x32_bf16 v[124:127], v[146:149], v[178:181], v[124:127]
	v_mfma_f32_16x16x32_bf16 v[120:123], v[154:157], v[178:181], v[120:123]
	v_mfma_f32_16x16x32_bf16 v[116:119], v[146:149], v[186:189], v[116:119]
	v_mfma_f32_16x16x32_bf16 v[112:115], v[154:157], v[186:189], v[112:115]
	v_mfma_f32_16x16x32_bf16 v[100:103], v[146:149], v[198:201], v[100:103]
	v_mfma_f32_16x16x32_bf16 v[96:99], v[154:157], v[198:201], v[96:99]
	v_mfma_f32_16x16x32_bf16 v[84:87], v[146:149], v[206:209], v[84:87]
	v_mfma_f32_16x16x32_bf16 v[80:83], v[154:157], v[206:209], v[80:83]
	v_mfma_f32_16x16x32_bf16 v[124:127], v[150:153], v[182:185], v[124:127]
	v_mfma_f32_16x16x32_bf16 v[120:123], v[158:161], v[182:185], v[120:123]
	v_mfma_f32_16x16x32_bf16 v[116:119], v[150:153], v[194:197], v[116:119]
	v_mfma_f32_16x16x32_bf16 v[112:115], v[158:161], v[194:197], v[112:115]
	v_mfma_f32_16x16x32_bf16 v[100:103], v[150:153], v[202:205], v[100:103]
	v_mfma_f32_16x16x32_bf16 v[96:99], v[158:161], v[202:205], v[96:99]
	v_mfma_f32_16x16x32_bf16 v[84:87], v[150:153], v[210:213], v[84:87]
	v_mfma_f32_16x16x32_bf16 v[80:83], v[158:161], v[210:213], v[80:83]
	v_mfma_f32_16x16x32_bf16 v[108:111], v[162:165], v[178:181], v[108:111]
	v_mfma_f32_16x16x32_bf16 v[104:107], v[170:173], v[178:181], v[104:107]
	v_mfma_f32_16x16x32_bf16 v[92:95], v[162:165], v[186:189], v[92:95]
	v_mfma_f32_16x16x32_bf16 v[88:91], v[170:173], v[186:189], v[88:91]
	v_mfma_f32_16x16x32_bf16 v[76:79], v[162:165], v[198:201], v[76:79]
	v_mfma_f32_16x16x32_bf16 v[72:75], v[170:173], v[198:201], v[72:75]
	v_mfma_f32_16x16x32_bf16 v[68:71], v[162:165], v[206:209], v[68:71]
	v_mfma_f32_16x16x32_bf16 v[64:67], v[170:173], v[206:209], v[64:67]
	v_mfma_f32_16x16x32_bf16 v[108:111], v[166:169], v[182:185], v[108:111]
	v_mfma_f32_16x16x32_bf16 v[104:107], v[174:177], v[182:185], v[104:107]
	v_mfma_f32_16x16x32_bf16 v[92:95], v[166:169], v[194:197], v[92:95]
	v_mfma_f32_16x16x32_bf16 v[88:91], v[174:177], v[194:197], v[88:91]
	v_mfma_f32_16x16x32_bf16 v[76:79], v[166:169], v[202:205], v[76:79]
	v_mfma_f32_16x16x32_bf16 v[72:75], v[174:177], v[202:205], v[72:75]
	v_mfma_f32_16x16x32_bf16 v[68:71], v[166:169], v[210:213], v[68:71]
	v_mfma_f32_16x16x32_bf16 v[64:67], v[174:177], v[210:213], v[64:67]
	s_barrier
	s_add_i32 s48, s48, s33
	v_lshl_add_u64 v[190:191], s[24:25], 0, v[132:133]
	s_mov_b32 m0, s48
	ds_read_b128 v[178:181], v145 offset:16384
	ds_read_b128 v[182:185], v145 offset:17408
	ds_read_b128 v[186:189], v145 offset:18432
	ds_read_b128 v[194:197], v145 offset:19456
	ds_read_b128 v[198:201], v145 offset:20480
	ds_read_b128 v[202:205], v145 offset:21504
	ds_read_b128 v[206:209], v145 offset:22528
	ds_read_b128 v[210:213], v145 offset:23552
	global_load_lds_dwordx4 v[190:191], off
	s_add_i32 m0, s48, 0x2000
	s_add_u32 s48, s24, 0x40000
	v_lshl_add_u64 v[214:215], s[24:25], 0, v[128:129]
	s_addc_u32 s49, s25, 0
	s_add_i32 s50, s50, s33
	global_load_lds_dwordx4 v[214:215], off
	v_lshl_add_u64 v[216:217], s[48:49], 0, v[132:133]
	s_mov_b32 m0, s50
	v_lshl_add_u64 v[218:219], s[26:27], 0, v[130:131]
	global_load_lds_dwordx4 v[216:217], off
	v_lshl_add_u64 v[216:217], s[48:49], 0, v[128:129]
	s_add_i32 m0, s50, 0x2000
	s_nop 0
	global_load_lds_dwordx4 v[216:217], off
	v_lshl_add_u64 v[216:217], s[26:27], 0, v[134:135]
	s_mov_b32 m0, s34
	s_nop 0
	global_load_lds_dwordx4 v[216:217], off
	s_mov_b32 m0, s35
	s_nop 0
	global_load_lds_dwordx4 v[218:219], off
	s_waitcnt vmcnt(8) lgkmcnt(0)
	s_barrier
; #define PG8_STAGE(bufoff, gbase, voff) do { _Pragma("unroll") for (int _i = 0; _i < 2; ++_i) \
;         __builtin_amdgcn_global_load_lds((const unsigned*)((const char*)(gbase) + (voff)[_i]), (LAS unsigned*)(lds + (bufoff) + ldsw + _i * 8192), 16, 0, 0); } while (0)
; #define PG8_LDA(dst, b, h) do { _Pragma("unroll") for (int m = 0; m < 4; ++m) _Pragma("unroll") for (int k = 0; k < 2; ++k) dst[m][k] = *(const LAS bf16x8*)(lds + PG8_SA(b, h) + aoff + m * 2048 + k * 1024); } while (0)
; #define PG8_LDB(dst, b, h) do { _Pragma("unroll") for (int n = 0; n < 2; ++n) _Pragma("unroll") for (int k = 0; k < 2; ++k) dst[n][k] = *(const LAS bf16x8*)(lds + PG8_SB(b, h) + boff + n * 2048 + k * 1024); } while (0)
; #define PG8_MMA(ai, bj, At, Bt) do { __builtin_amdgcn_s_setprio(1); _Pragma("unroll") for (int m = 0; m < 4; ++m) _Pragma("unroll") for (int n = 0; n < 2; ++n) _Pragma("unroll") for (int k = 0; k < 2; ++k) \
;         acc[ai][bj][m][n] = __builtin_amdgcn_mfma_f32_16x16x32_bf16(Bt[n][k], At[m][k], acc[ai][bj][m][n], 0, 0, 0); __builtin_amdgcn_s_setprio(0); } while (0)
; #define PG8_WAIT_V(n) asm volatile("s_waitcnt vmcnt(" #n ")" ::: "memory")
; #define PG8_WAIT_L(n) asm volatile("s_waitcnt lgkmcnt(" #n ")" ::: "memory")
; #define PG8_BAR __builtin_amdgcn_s_barrier()
; #define PG8_SCHED __builtin_amdgcn_sched_barrier(0)
; template <class Epi>
; DI void gemm_phase(int wv, LAS unsigned char* lds, LAS unsigned char* scr, const Sched& S, const Epi& E) {
;     ...
;             PG8_WAIT_V(8); PG8_WAIT_L(0); PG8_BAR; PG8_MMA(1, 0, At, B0); PG8_MMA(1, 1, At, B1); PG8_BAR; PG8_SCHED;
;             PG8_LDB(B0, 1, 0); PG8_LDB(B1, 1, 1); PG8_SCHED; PG8_LDA(At, 1, 0); PG8_STAGE(PG8_SA(0, 1), a2 + hstepA, voffA);
;             PG8_WAIT_V(8); PG8_WAIT_L(0); PG8_BAR; PG8_MMA(0, 0, At, B0); PG8_MMA(0, 1, At, B1); PG8_BAR; PG8_SCHED;
	v_mfma_f32_16x16x32_bf16 v[60:63], v[146:149], v[178:181], v[60:63]
	v_mfma_f32_16x16x32_bf16 v[56:59], v[154:157], v[178:181], v[56:59]
	v_mfma_f32_16x16x32_bf16 v[52:55], v[146:149], v[186:189], v[52:55]
	v_mfma_f32_16x16x32_bf16 v[48:51], v[154:157], v[186:189], v[48:51]
	v_mfma_f32_16x16x32_bf16 v[36:39], v[146:149], v[198:201], v[36:39]
	v_mfma_f32_16x16x32_bf16 v[32:35], v[154:157], v[198:201], v[32:35]
	v_mfma_f32_16x16x32_bf16 v[20:23], v[146:149], v[206:209], v[20:23]
	v_mfma_f32_16x16x32_bf16 v[16:19], v[154:157], v[206:209], v[16:19]
	v_mfma_f32_16x16x32_bf16 v[60:63], v[150:153], v[182:185], v[60:63]
	v_mfma_f32_16x16x32_bf16 v[56:59], v[158:161], v[182:185], v[56:59]
	v_mfma_f32_16x16x32_bf16 v[52:55], v[150:153], v[194:197], v[52:55]
	v_mfma_f32_16x16x32_bf16 v[48:51], v[158:161], v[194:197], v[48:51]
	v_mfma_f32_16x16x32_bf16 v[36:39], v[150:153], v[202:205], v[36:39]
	v_mfma_f32_16x16x32_bf16 v[32:35], v[158:161], v[202:205], v[32:35]
	v_mfma_f32_16x16x32_bf16 v[20:23], v[150:153], v[210:213], v[20:23]
	v_mfma_f32_16x16x32_bf16 v[16:19], v[158:161], v[210:213], v[16:19]
	v_mfma_f32_16x16x32_bf16 v[44:47], v[162:165], v[178:181], v[44:47]
	v_mfma_f32_16x16x32_bf16 v[40:43], v[170:173], v[178:181], v[40:43]
	v_mfma_f32_16x16x32_bf16 v[28:31], v[162:165], v[186:189], v[28:31]
	v_mfma_f32_16x16x32_bf16 v[24:27], v[170:173], v[186:189], v[24:27]
	v_mfma_f32_16x16x32_bf16 v[12:15], v[162:165], v[198:201], v[12:15]
	v_mfma_f32_16x16x32_bf16 v[8:11], v[170:173], v[198:201], v[8:11]
	v_mfma_f32_16x16x32_bf16 v[4:7], v[162:165], v[206:209], v[4:7]
	v_mfma_f32_16x16x32_bf16 v[0:3], v[170:173], v[206:209], v[0:3]
	v_mfma_f32_16x16x32_bf16 v[44:47], v[166:169], v[182:185], v[44:47]
	v_mfma_f32_16x16x32_bf16 v[40:43], v[174:177], v[182:185], v[40:43]
	v_mfma_f32_16x16x32_bf16 v[28:31], v[166:169], v[194:197], v[28:31]
	v_mfma_f32_16x16x32_bf16 v[24:27], v[174:177], v[194:197], v[24:27]
	v_mfma_f32_16x16x32_bf16 v[12:15], v[166:169], v[202:205], v[12:15]
	v_mfma_f32_16x16x32_bf16 v[8:11], v[174:177], v[202:205], v[8:11]
	v_mfma_f32_16x16x32_bf16 v[4:7], v[166:169], v[210:213], v[4:7]
	v_mfma_f32_16x16x32_bf16 v[0:3], v[174:177], v[210:213], v[0:3]
	s_barrier
	s_add_i32 s48, 0, 0x18000
	v_add_u32_e32 v143, s48, v144
	s_add_i32 s49, 0, 0x1c000
	ds_read_b128 v[146:149], v143
	ds_read_b128 v[150:153], v143 offset:1024
	ds_read_b128 v[154:157], v143 offset:2048
	ds_read_b128 v[158:161], v143 offset:3072
	v_add_u32_e32 v143, s49, v144
	ds_read_b128 v[162:165], v143
	ds_read_b128 v[166:169], v143 offset:1024
	ds_read_b128 v[170:173], v143 offset:2048
	ds_read_b128 v[174:177], v143 offset:3072
	s_add_u32 s26, s26, 0x40000
	s_addc_u32 s27, s27, 0
	s_mov_b32 m0, s36
	v_lshl_add_u64 v[220:221], s[26:27], 0, v[134:135]
	ds_read_b128 v[178:181], v145 offset:32768
	ds_read_b128 v[182:185], v145 offset:33792
	ds_read_b128 v[186:189], v145 offset:34816
	ds_read_b128 v[194:197], v145 offset:35840
	ds_read_b128 v[198:201], v145 offset:36864
	ds_read_b128 v[202:205], v145 offset:37888
	ds_read_b128 v[206:209], v145 offset:38912
	ds_read_b128 v[210:213], v145 offset:39936
	global_load_lds_dwordx4 v[220:221], off
	v_lshl_add_u64 v[220:221], s[26:27], 0, v[130:131]
	s_mov_b32 m0, s37
	s_nop 0
	global_load_lds_dwordx4 v[220:221], off
	s_waitcnt vmcnt(8) lgkmcnt(0)
	s_barrier
	v_mfma_f32_16x16x32_bf16 v[124:127], v[146:149], v[178:181], v[124:127]
	v_mfma_f32_16x16x32_bf16 v[120:123], v[154:157], v[178:181], v[120:123]
	v_mfma_f32_16x16x32_bf16 v[116:119], v[146:149], v[186:189], v[116:119]
	v_mfma_f32_16x16x32_bf16 v[112:115], v[154:157], v[186:189], v[112:115]
	v_mfma_f32_16x16x32_bf16 v[100:103], v[146:149], v[198:201], v[100:103]
	v_mfma_f32_16x16x32_bf16 v[96:99], v[154:157], v[198:201], v[96:99]
	v_mfma_f32_16x16x32_bf16 v[84:87], v[146:149], v[206:209], v[84:87]
	v_mfma_f32_16x16x32_bf16 v[80:83], v[154:157], v[206:209], v[80:83]
	v_mfma_f32_16x16x32_bf16 v[124:127], v[150:153], v[182:185], v[124:127]
	v_mfma_f32_16x16x32_bf16 v[120:123], v[158:161], v[182:185], v[120:123]
	v_mfma_f32_16x16x32_bf16 v[116:119], v[150:153], v[194:197], v[116:119]
	v_mfma_f32_16x16x32_bf16 v[112:115], v[158:161], v[194:197], v[112:115]
	v_mfma_f32_16x16x32_bf16 v[100:103], v[150:153], v[202:205], v[100:103]
	v_mfma_f32_16x16x32_bf16 v[96:99], v[158:161], v[202:205], v[96:99]
	v_mfma_f32_16x16x32_bf16 v[84:87], v[150:153], v[210:213], v[84:87]
	v_mfma_f32_16x16x32_bf16 v[80:83], v[158:161], v[210:213], v[80:83]
	v_mfma_f32_16x16x32_bf16 v[108:111], v[162:165], v[178:181], v[108:111]
	v_mfma_f32_16x16x32_bf16 v[104:107], v[170:173], v[178:181], v[104:107]
	v_mfma_f32_16x16x32_bf16 v[92:95], v[162:165], v[186:189], v[92:95]
	v_mfma_f32_16x16x32_bf16 v[88:91], v[170:173], v[186:189], v[88:91]
	v_mfma_f32_16x16x32_bf16 v[76:79], v[162:165], v[198:201], v[76:79]
	v_mfma_f32_16x16x32_bf16 v[72:75], v[170:173], v[198:201], v[72:75]
	v_mfma_f32_16x16x32_bf16 v[68:71], v[162:165], v[206:209], v[68:71]
	v_mfma_f32_16x16x32_bf16 v[64:67], v[170:173], v[206:209], v[64:67]
	v_mfma_f32_16x16x32_bf16 v[108:111], v[166:169], v[182:185], v[108:111]
	v_mfma_f32_16x16x32_bf16 v[104:107], v[174:177], v[182:185], v[104:107]
	v_mfma_f32_16x16x32_bf16 v[92:95], v[166:169], v[194:197], v[92:95]
	v_mfma_f32_16x16x32_bf16 v[88:91], v[174:177], v[194:197], v[88:91]
	v_mfma_f32_16x16x32_bf16 v[76:79], v[166:169], v[202:205], v[76:79]
	v_mfma_f32_16x16x32_bf16 v[72:75], v[174:177], v[202:205], v[72:75]
	v_mfma_f32_16x16x32_bf16 v[68:71], v[166:169], v[210:213], v[68:71]
	v_mfma_f32_16x16x32_bf16 v[64:67], v[174:177], v[210:213], v[64:67]
	s_barrier
; #define PG8_STAGE(bufoff, gbase, voff) do { _Pragma("unroll") for (int _i = 0; _i < 2; ++_i) \
;         __builtin_amdgcn_global_load_lds((const unsigned*)((const char*)(gbase) + (voff)[_i]), (LAS unsigned*)(lds + (bufoff) + ldsw + _i * 8192), 16, 0, 0); } while (0)
; #define PG8_LDA(dst, b, h) do { _Pragma("unroll") for (int m = 0; m < 4; ++m) _Pragma("unroll") for (int k = 0; k < 2; ++k) dst[m][k] = *(const LAS bf16x8*)(lds + PG8_SA(b, h) + aoff + m * 2048 + k * 1024); } while (0)
; #define PG8_MMA(ai, bj, At, Bt) do { __builtin_amdgcn_s_setprio(1); _Pragma("unroll") for (int m = 0; m < 4; ++m) _Pragma("unroll") for (int n = 0; n < 2; ++n) _Pragma("unroll") for (int k = 0; k < 2; ++k) \
;         acc[ai][bj][m][n] = __builtin_amdgcn_mfma_f32_16x16x32_bf16(Bt[n][k], At[m][k], acc[ai][bj][m][n], 0, 0, 0); __builtin_amdgcn_s_setprio(0); } while (0)
; #define PG8_WAIT_V(n) asm volatile("s_waitcnt vmcnt(" #n ")" ::: "memory")
; #define PG8_WAIT_L(n) asm volatile("s_waitcnt lgkmcnt(" #n ")" ::: "memory")
; #define PG8_BAR __builtin_amdgcn_s_barrier()
; #define PG8_SCHED __builtin_amdgcn_sched_barrier(0)
; template <class Epi>
; DI void gemm_phase(int wv, LAS unsigned char* lds, LAS unsigned char* scr, const Sched& S, const Epi& E) {
;     ...
;             PG8_LDA(At, 1, 1); PG8_STAGE(PG8_SB(1, 0), b3, voffB); PG8_STAGE(PG8_SB(1, 1), b3 + hstepB, voffB); PG8_STAGE(PG8_SA(1, 0), a3, voffA);
;             PG8_WAIT_V(8); PG8_WAIT_L(0); PG8_BAR; PG8_MMA(1, 0, At, B0); PG8_MMA(1, 1, At, B1); PG8_BAR; PG8_SCHED;
;         }
	s_add_i32 s26, s48, s33
	v_lshl_add_u64 v[190:191], v[190:191], 0, s[2:3]
	s_mov_b32 m0, s26
	ds_read_b128 v[178:181], v145 offset:49152
	ds_read_b128 v[182:185], v145 offset:50176
	ds_read_b128 v[186:189], v145 offset:51200
	ds_read_b128 v[194:197], v145 offset:52224
	ds_read_b128 v[198:201], v145 offset:53248
	ds_read_b128 v[202:205], v145 offset:54272
	ds_read_b128 v[206:209], v145 offset:55296
	ds_read_b128 v[210:213], v145 offset:56320
	global_load_lds_dwordx4 v[190:191], off
	s_add_i32 m0, s26, 0x2000
	s_add_u32 s24, s24, 0x40080
	v_lshl_add_u64 v[190:191], v[214:215], 0, s[2:3]
	s_addc_u32 s25, s25, 0
	s_add_i32 s26, s49, s33
	global_load_lds_dwordx4 v[190:191], off
	v_lshl_add_u64 v[190:191], s[24:25], 0, v[132:133]
	s_mov_b32 m0, s26
	s_nop 0
	global_load_lds_dwordx4 v[190:191], off
	v_lshl_add_u64 v[190:191], s[24:25], 0, v[128:129]
	s_add_i32 m0, s26, 0x2000
	s_nop 0
	global_load_lds_dwordx4 v[190:191], off
	v_lshl_add_u64 v[190:191], v[216:217], 0, s[2:3]
	s_mov_b32 m0, s42
	s_nop 0
	global_load_lds_dwordx4 v[190:191], off
	v_lshl_add_u64 v[190:191], v[218:219], 0, s[2:3]
	s_mov_b32 m0, s43
	s_nop 0
	global_load_lds_dwordx4 v[190:191], off
	s_waitcnt vmcnt(8) lgkmcnt(0)
	s_barrier
	v_mfma_f32_16x16x32_bf16 v[60:63], v[146:149], v[178:181], v[60:63]
	v_mfma_f32_16x16x32_bf16 v[56:59], v[154:157], v[178:181], v[56:59]
	v_mfma_f32_16x16x32_bf16 v[52:55], v[146:149], v[186:189], v[52:55]
	v_mfma_f32_16x16x32_bf16 v[48:51], v[154:157], v[186:189], v[48:51]
	v_mfma_f32_16x16x32_bf16 v[36:39], v[146:149], v[198:201], v[36:39]
	v_mfma_f32_16x16x32_bf16 v[32:35], v[154:157], v[198:201], v[32:35]
	v_mfma_f32_16x16x32_bf16 v[20:23], v[146:149], v[206:209], v[20:23]
	v_mfma_f32_16x16x32_bf16 v[16:19], v[154:157], v[206:209], v[16:19]
	v_mfma_f32_16x16x32_bf16 v[60:63], v[150:153], v[182:185], v[60:63]
	v_mfma_f32_16x16x32_bf16 v[56:59], v[158:161], v[182:185], v[56:59]
	v_mfma_f32_16x16x32_bf16 v[52:55], v[150:153], v[194:197], v[52:55]
	v_mfma_f32_16x16x32_bf16 v[48:51], v[158:161], v[194:197], v[48:51]
	v_mfma_f32_16x16x32_bf16 v[36:39], v[150:153], v[202:205], v[36:39]
	v_mfma_f32_16x16x32_bf16 v[32:35], v[158:161], v[202:205], v[32:35]
	v_mfma_f32_16x16x32_bf16 v[20:23], v[150:153], v[210:213], v[20:23]
	v_mfma_f32_16x16x32_bf16 v[16:19], v[158:161], v[210:213], v[16:19]
	v_mfma_f32_16x16x32_bf16 v[44:47], v[162:165], v[178:181], v[44:47]
	v_mfma_f32_16x16x32_bf16 v[40:43], v[170:173], v[178:181], v[40:43]
	v_mfma_f32_16x16x32_bf16 v[28:31], v[162:165], v[186:189], v[28:31]
	v_mfma_f32_16x16x32_bf16 v[24:27], v[170:173], v[186:189], v[24:27]
	v_mfma_f32_16x16x32_bf16 v[12:15], v[162:165], v[198:201], v[12:15]
	v_mfma_f32_16x16x32_bf16 v[8:11], v[170:173], v[198:201], v[8:11]
	v_mfma_f32_16x16x32_bf16 v[4:7], v[162:165], v[206:209], v[4:7]
	v_mfma_f32_16x16x32_bf16 v[0:3], v[170:173], v[206:209], v[0:3]
	v_mfma_f32_16x16x32_bf16 v[44:47], v[166:169], v[182:185], v[44:47]
	v_mfma_f32_16x16x32_bf16 v[40:43], v[174:177], v[182:185], v[40:43]
	v_mfma_f32_16x16x32_bf16 v[28:31], v[166:169], v[194:197], v[28:31]
	v_mfma_f32_16x16x32_bf16 v[24:27], v[174:177], v[194:197], v[24:27]
	v_mfma_f32_16x16x32_bf16 v[12:15], v[166:169], v[202:205], v[12:15]
	v_mfma_f32_16x16x32_bf16 v[8:11], v[174:177], v[202:205], v[8:11]
	v_mfma_f32_16x16x32_bf16 v[4:7], v[166:169], v[210:213], v[4:7]
	v_mfma_f32_16x16x32_bf16 v[0:3], v[174:177], v[210:213], v[0:3]
	s_barrier
	s_add_i32 s47, s47, 2
	s_add_u32 s45, s45, 0x100
	s_addc_u32 s46, s46, 0
	s_add_u32 s22, s22, 0x100
	s_addc_u32 s23, s23, 0
	s_cmp_gt_u32 s47, 13
	s_cbranch_scc0 .LBB0_463
	s_and_b64 vcc, exec, s[8:9]
	s_cbranch_vccz .LBB0_466
	s_barrier

; #define PG8_STAGE(bufoff, gbase, voff) do { _Pragma("unroll") for (int _i = 0; _i < 2; ++_i) \
;         __builtin_amdgcn_global_load_lds((const unsigned*)((const char*)(gbase) + (voff)[_i]), (LAS unsigned*)(lds + (bufoff) + ldsw + _i * 8192), 16, 0, 0); } while (0)
; #define PG8_LDA(dst, b, h) do { _Pragma("unroll") for (int m = 0; m < 4; ++m) _Pragma("unroll") for (int k = 0; k < 2; ++k) dst[m][k] = *(const LAS bf16x8*)(lds + PG8_SA(b, h) + aoff + m * 2048 + k * 1024); } while (0)
; #define PG8_LDB(dst, b, h) do { _Pragma("unroll") for (int n = 0; n < 2; ++n) _Pragma("unroll") for (int k = 0; k < 2; ++k) dst[n][k] = *(const LAS bf16x8*)(lds + PG8_SB(b, h) + boff + n * 2048 + k * 1024); } while (0)
; #define PG8_MMA(ai, bj, At, Bt) do { __builtin_amdgcn_s_setprio(1); _Pragma("unroll") for (int m = 0; m < 4; ++m) _Pragma("unroll") for (int n = 0; n < 2; ++n) _Pragma("unroll") for (int k = 0; k < 2; ++k) \
;         acc[ai][bj][m][n] = __builtin_amdgcn_mfma_f32_16x16x32_bf16(Bt[n][k], At[m][k], acc[ai][bj][m][n], 0, 0, 0); __builtin_amdgcn_s_setprio(0); } while (0)
; #define PG8_WAIT_V(n) asm volatile("s_waitcnt vmcnt(" #n ")" ::: "memory")
; #define PG8_WAIT_L(n) asm volatile("s_waitcnt lgkmcnt(" #n ")" ::: "memory")
; #define PG8_BAR __builtin_amdgcn_s_barrier()
; #define PG8_SCHED __builtin_amdgcn_sched_barrier(0)
; template <class Epi>
; DI void gemm_phase(int wv, LAS unsigned char* lds, LAS unsigned char* scr, const Sched& S, const Epi& E) {
;     ...
;             const bool last = (t == nt - 2);
;             const char* a1 = cA + (size_t)(t + 1) * kstep;
;             const char* a2 = last ? nA : cA + (size_t)(t + 2) * kstep; const char* b2 = last ? nB : cB + (size_t)(t + 2) * kstep;
;             const char* a3 = a2 + kstep; const char* b3 = b2 + kstep;
;             PG8_LDB(B0, 0, 0); PG8_LDB(B1, 0, 1); PG8_SCHED; PG8_LDA(At, 0, 0); PG8_STAGE(PG8_SA(1, 1), a1 + hstepA, voffA);
;             PG8_WAIT_V(8); PG8_WAIT_L(0); PG8_BAR; PG8_MMA(0, 0, At, B0); PG8_MMA(0, 1, At, B1); PG8_BAR; PG8_SCHED;
;             PG8_LDA(At, 0, 1); PG8_STAGE(PG8_SB(0, 0), b2, voffB); PG8_STAGE(PG8_SB(0, 1), b2 + hstepB, voffB); PG8_STAGE(PG8_SA(0, 0), a2, voffA);
.LBB0_588:
	s_add_u32 s28, s12, 0xfffc0080
	s_addc_u32 s29, s13, -1
	s_add_i32 s49, 0, 0x10000
	s_cmp_eq_u32 s33, 12
	s_cselect_b32 s31, s17, s29
	s_cselect_b32 s30, s19, s28
	v_add_u32_e32 v143, s49, v146
	s_cselect_b32 s29, s21, s27
	s_cselect_b32 s28, s20, s25
	s_add_i32 s52, 0, 0x14000
	ds_read_b128 v[168:171], v143
	ds_read_b128 v[172:175], v143 offset:1024
	ds_read_b128 v[176:179], v143 offset:2048
	ds_read_b128 v[180:183], v143 offset:3072
	v_add_u32_e32 v143, s52, v146
	ds_read_b128 v[184:187], v143
	ds_read_b128 v[188:191], v143 offset:1024
	ds_read_b128 v[194:197], v143 offset:2048
	ds_read_b128 v[198:201], v143 offset:3072
	v_lshl_add_u64 v[144:145], s[12:13], 0, v[140:141]
	s_add_i32 m0, s39, 0xc000
	ds_read_b128 v[202:205], v166
	ds_read_b128 v[206:209], v166 offset:1024
	ds_read_b128 v[210:213], v166 offset:2048
	ds_read_b128 v[214:217], v166 offset:3072
	ds_read_b128 v[218:221], v166 offset:4096
	ds_read_b128 v[222:225], v166 offset:5120
	ds_read_b128 v[226:229], v166 offset:6144
	ds_read_b128 v[230:233], v166 offset:7168
	global_load_lds_dwordx4 v[144:145], off
	v_lshl_add_u64 v[144:145], s[12:13], 0, v[138:139]
	s_add_i32 m0, s39, 0xe000
	s_nop 0
	global_load_lds_dwordx4 v[144:145], off
	s_waitcnt vmcnt(8) lgkmcnt(0)
	s_barrier
	v_mfma_f32_16x16x32_bf16 v[124:127], v[168:171], v[202:205], v[124:127]
	v_mfma_f32_16x16x32_bf16 v[120:123], v[176:179], v[202:205], v[120:123]
	v_mfma_f32_16x16x32_bf16 v[108:111], v[168:171], v[210:213], v[108:111]
	v_mfma_f32_16x16x32_bf16 v[104:107], v[176:179], v[210:213], v[104:107]
	v_mfma_f32_16x16x32_bf16 v[92:95], v[168:171], v[218:221], v[92:95]
	v_mfma_f32_16x16x32_bf16 v[88:91], v[176:179], v[218:221], v[88:91]
	v_mfma_f32_16x16x32_bf16 v[76:79], v[168:171], v[226:229], v[76:79]
	v_mfma_f32_16x16x32_bf16 v[72:75], v[176:179], v[226:229], v[72:75]
	v_mfma_f32_16x16x32_bf16 v[124:127], v[172:175], v[206:209], v[124:127]
	v_mfma_f32_16x16x32_bf16 v[120:123], v[180:183], v[206:209], v[120:123]
	v_mfma_f32_16x16x32_bf16 v[108:111], v[172:175], v[214:217], v[108:111]
	v_mfma_f32_16x16x32_bf16 v[104:107], v[180:183], v[214:217], v[104:107]
	v_mfma_f32_16x16x32_bf16 v[92:95], v[172:175], v[222:225], v[92:95]
	v_mfma_f32_16x16x32_bf16 v[88:91], v[180:183], v[222:225], v[88:91]
	v_mfma_f32_16x16x32_bf16 v[76:79], v[172:175], v[230:233], v[76:79]
	v_mfma_f32_16x16x32_bf16 v[72:75], v[180:183], v[230:233], v[72:75]
	v_mfma_f32_16x16x32_bf16 v[116:119], v[184:187], v[202:205], v[116:119]
	v_mfma_f32_16x16x32_bf16 v[112:115], v[194:197], v[202:205], v[112:115]
	v_mfma_f32_16x16x32_bf16 v[100:103], v[184:187], v[210:213], v[100:103]
	v_mfma_f32_16x16x32_bf16 v[96:99], v[194:197], v[210:213], v[96:99]
	v_mfma_f32_16x16x32_bf16 v[84:87], v[184:187], v[218:221], v[84:87]
	v_mfma_f32_16x16x32_bf16 v[80:83], v[194:197], v[218:221], v[80:83]
	v_mfma_f32_16x16x32_bf16 v[68:71], v[184:187], v[226:229], v[68:71]
	v_mfma_f32_16x16x32_bf16 v[64:67], v[194:197], v[226:229], v[64:67]
	v_mfma_f32_16x16x32_bf16 v[116:119], v[188:191], v[206:209], v[116:119]
	v_mfma_f32_16x16x32_bf16 v[112:115], v[198:201], v[206:209], v[112:115]
	v_mfma_f32_16x16x32_bf16 v[100:103], v[188:191], v[214:217], v[100:103]
	v_mfma_f32_16x16x32_bf16 v[96:99], v[198:201], v[214:217], v[96:99]
	v_mfma_f32_16x16x32_bf16 v[84:87], v[188:191], v[222:225], v[84:87]
	v_mfma_f32_16x16x32_bf16 v[80:83], v[198:201], v[222:225], v[80:83]
	v_mfma_f32_16x16x32_bf16 v[68:71], v[188:191], v[230:233], v[68:71]
	v_mfma_f32_16x16x32_bf16 v[64:67], v[198:201], v[230:233], v[64:67]
	s_barrier
	s_add_i32 s49, s49, s38
	v_lshl_add_u64 v[144:145], s[28:29], 0, v[130:131]
	s_mov_b32 m0, s49
	ds_read_b128 v[202:205], v166 offset:16384
	ds_read_b128 v[206:209], v166 offset:17408
	ds_read_b128 v[210:213], v166 offset:18432
	ds_read_b128 v[214:217], v166 offset:19456
	ds_read_b128 v[218:221], v166 offset:20480
	ds_read_b128 v[222:225], v166 offset:21504
	ds_read_b128 v[226:229], v166 offset:22528
	ds_read_b128 v[230:233], v166 offset:23552
	global_load_lds_dwordx4 v[144:145], off
	s_add_i32 m0, s49, 0x2000
	s_add_u32 s50, s28, 0x40000
	v_lshl_add_u64 v[234:235], s[28:29], 0, v[134:135]
	s_addc_u32 s51, s29, 0
	s_add_i32 s49, s52, s38
	global_load_lds_dwordx4 v[234:235], off
	v_lshl_add_u64 v[236:237], s[50:51], 0, v[130:131]
	s_mov_b32 m0, s49
	v_lshl_add_u64 v[238:239], s[30:31], 0, v[132:133]
	global_load_lds_dwordx4 v[236:237], off
	v_lshl_add_u64 v[236:237], s[50:51], 0, v[134:135]
	s_add_i32 m0, s49, 0x2000
	s_nop 0
	global_load_lds_dwordx4 v[236:237], off
	v_lshl_add_u64 v[236:237], s[30:31], 0, v[128:129]
	s_mov_b32 m0, s39
	s_nop 0
	global_load_lds_dwordx4 v[236:237], off
	s_mov_b32 m0, s42
	s_nop 0
	global_load_lds_dwordx4 v[238:239], off
	s_waitcnt vmcnt(8) lgkmcnt(0)
	s_barrier
; #define PG8_STAGE(bufoff, gbase, voff) do { _Pragma("unroll") for (int _i = 0; _i < 2; ++_i) \
;         __builtin_amdgcn_global_load_lds((const unsigned*)((const char*)(gbase) + (voff)[_i]), (LAS unsigned*)(lds + (bufoff) + ldsw + _i * 8192), 16, 0, 0); } while (0)
; #define PG8_LDA(dst, b, h) do { _Pragma("unroll") for (int m = 0; m < 4; ++m) _Pragma("unroll") for (int k = 0; k < 2; ++k) dst[m][k] = *(const LAS bf16x8*)(lds + PG8_SA(b, h) + aoff + m * 2048 + k * 1024); } while (0)
; #define PG8_LDB(dst, b, h) do { _Pragma("unroll") for (int n = 0; n < 2; ++n) _Pragma("unroll") for (int k = 0; k < 2; ++k) dst[n][k] = *(const LAS bf16x8*)(lds + PG8_SB(b, h) + boff + n * 2048 + k * 1024); } while (0)
; #define PG8_MMA(ai, bj, At, Bt) do { __builtin_amdgcn_s_setprio(1); _Pragma("unroll") for (int m = 0; m < 4; ++m) _Pragma("unroll") for (int n = 0; n < 2; ++n) _Pragma("unroll") for (int k = 0; k < 2; ++k) \
;         acc[ai][bj][m][n] = __builtin_amdgcn_mfma_f32_16x16x32_bf16(Bt[n][k], At[m][k], acc[ai][bj][m][n], 0, 0, 0); __builtin_amdgcn_s_setprio(0); } while (0)
; #define PG8_WAIT_V(n) asm volatile("s_waitcnt vmcnt(" #n ")" ::: "memory")
; #define PG8_WAIT_L(n) asm volatile("s_waitcnt lgkmcnt(" #n ")" ::: "memory")
; #define PG8_BAR __builtin_amdgcn_s_barrier()
; #define PG8_SCHED __builtin_amdgcn_sched_barrier(0)
; template <class Epi>
; DI void gemm_phase(int wv, LAS unsigned char* lds, LAS unsigned char* scr, const Sched& S, const Epi& E) {
;     ...
;             PG8_WAIT_V(8); PG8_WAIT_L(0); PG8_BAR; PG8_MMA(1, 0, At, B0); PG8_MMA(1, 1, At, B1); PG8_BAR; PG8_SCHED;
;             PG8_LDB(B0, 1, 0); PG8_LDB(B1, 1, 1); PG8_SCHED; PG8_LDA(At, 1, 0); PG8_STAGE(PG8_SA(0, 1), a2 + hstepA, voffA);
;             PG8_WAIT_V(8); PG8_WAIT_L(0); PG8_BAR; PG8_MMA(0, 0, At, B0); PG8_MMA(0, 1, At, B1); PG8_BAR; PG8_SCHED;
	v_mfma_f32_16x16x32_bf16 v[60:63], v[168:171], v[202:205], v[60:63]
	v_mfma_f32_16x16x32_bf16 v[56:59], v[176:179], v[202:205], v[56:59]
	v_mfma_f32_16x16x32_bf16 v[44:47], v[168:171], v[210:213], v[44:47]
	v_mfma_f32_16x16x32_bf16 v[40:43], v[176:179], v[210:213], v[40:43]
	v_mfma_f32_16x16x32_bf16 v[28:31], v[168:171], v[218:221], v[28:31]
	v_mfma_f32_16x16x32_bf16 v[24:27], v[176:179], v[218:221], v[24:27]
	v_mfma_f32_16x16x32_bf16 v[12:15], v[168:171], v[226:229], v[12:15]
	v_mfma_f32_16x16x32_bf16 v[8:11], v[176:179], v[226:229], v[8:11]
	v_mfma_f32_16x16x32_bf16 v[60:63], v[172:175], v[206:209], v[60:63]
	v_mfma_f32_16x16x32_bf16 v[56:59], v[180:183], v[206:209], v[56:59]
	v_mfma_f32_16x16x32_bf16 v[44:47], v[172:175], v[214:217], v[44:47]
	v_mfma_f32_16x16x32_bf16 v[40:43], v[180:183], v[214:217], v[40:43]
	v_mfma_f32_16x16x32_bf16 v[28:31], v[172:175], v[222:225], v[28:31]
	v_mfma_f32_16x16x32_bf16 v[24:27], v[180:183], v[222:225], v[24:27]
	v_mfma_f32_16x16x32_bf16 v[12:15], v[172:175], v[230:233], v[12:15]
	v_mfma_f32_16x16x32_bf16 v[8:11], v[180:183], v[230:233], v[8:11]
	v_mfma_f32_16x16x32_bf16 v[52:55], v[184:187], v[202:205], v[52:55]
	v_mfma_f32_16x16x32_bf16 v[48:51], v[194:197], v[202:205], v[48:51]
	v_mfma_f32_16x16x32_bf16 v[36:39], v[184:187], v[210:213], v[36:39]
	v_mfma_f32_16x16x32_bf16 v[32:35], v[194:197], v[210:213], v[32:35]
	v_mfma_f32_16x16x32_bf16 v[20:23], v[184:187], v[218:221], v[20:23]
	v_mfma_f32_16x16x32_bf16 v[16:19], v[194:197], v[218:221], v[16:19]
	v_mfma_f32_16x16x32_bf16 v[4:7], v[184:187], v[226:229], v[4:7]
	v_mfma_f32_16x16x32_bf16 v[0:3], v[194:197], v[226:229], v[0:3]
	v_mfma_f32_16x16x32_bf16 v[52:55], v[188:191], v[206:209], v[52:55]
	v_mfma_f32_16x16x32_bf16 v[48:51], v[198:201], v[206:209], v[48:51]
	v_mfma_f32_16x16x32_bf16 v[36:39], v[188:191], v[214:217], v[36:39]
	v_mfma_f32_16x16x32_bf16 v[32:35], v[198:201], v[214:217], v[32:35]
	v_mfma_f32_16x16x32_bf16 v[20:23], v[188:191], v[222:225], v[20:23]
	v_mfma_f32_16x16x32_bf16 v[16:19], v[198:201], v[222:225], v[16:19]
	v_mfma_f32_16x16x32_bf16 v[4:7], v[188:191], v[230:233], v[4:7]
	v_mfma_f32_16x16x32_bf16 v[0:3], v[198:201], v[230:233], v[0:3]
	s_barrier
	s_add_i32 s49, 0, 0x18000
	v_add_u32_e32 v143, s49, v146
	s_add_i32 s50, 0, 0x1c000
	ds_read_b128 v[168:171], v143
	ds_read_b128 v[172:175], v143 offset:1024
	ds_read_b128 v[176:179], v143 offset:2048
	ds_read_b128 v[180:183], v143 offset:3072
	v_add_u32_e32 v143, s50, v146
	ds_read_b128 v[184:187], v143
	ds_read_b128 v[188:191], v143 offset:1024
	ds_read_b128 v[194:197], v143 offset:2048
	ds_read_b128 v[198:201], v143 offset:3072
	s_add_u32 s30, s30, 0x40000
	s_addc_u32 s31, s31, 0
	s_mov_b32 m0, s43
	v_lshl_add_u64 v[240:241], s[30:31], 0, v[128:129]
	ds_read_b128 v[202:205], v166 offset:32768
	ds_read_b128 v[206:209], v166 offset:33792
	ds_read_b128 v[210:213], v166 offset:34816
	ds_read_b128 v[214:217], v166 offset:35840
	ds_read_b128 v[218:221], v166 offset:36864
	ds_read_b128 v[222:225], v166 offset:37888
	ds_read_b128 v[226:229], v166 offset:38912
	ds_read_b128 v[230:233], v166 offset:39936
	global_load_lds_dwordx4 v[240:241], off
	v_lshl_add_u64 v[240:241], s[30:31], 0, v[132:133]
	s_mov_b32 m0, s44
	s_nop 0
	global_load_lds_dwordx4 v[240:241], off
	s_waitcnt vmcnt(8) lgkmcnt(0)
	s_barrier
	v_mfma_f32_16x16x32_bf16 v[124:127], v[168:171], v[202:205], v[124:127]
	v_mfma_f32_16x16x32_bf16 v[120:123], v[176:179], v[202:205], v[120:123]
	v_mfma_f32_16x16x32_bf16 v[108:111], v[168:171], v[210:213], v[108:111]
	v_mfma_f32_16x16x32_bf16 v[104:107], v[176:179], v[210:213], v[104:107]
	v_mfma_f32_16x16x32_bf16 v[92:95], v[168:171], v[218:221], v[92:95]
	v_mfma_f32_16x16x32_bf16 v[88:91], v[176:179], v[218:221], v[88:91]
	v_mfma_f32_16x16x32_bf16 v[76:79], v[168:171], v[226:229], v[76:79]
	v_mfma_f32_16x16x32_bf16 v[72:75], v[176:179], v[226:229], v[72:75]
	v_mfma_f32_16x16x32_bf16 v[124:127], v[172:175], v[206:209], v[124:127]
	v_mfma_f32_16x16x32_bf16 v[120:123], v[180:183], v[206:209], v[120:123]
	v_mfma_f32_16x16x32_bf16 v[108:111], v[172:175], v[214:217], v[108:111]
	v_mfma_f32_16x16x32_bf16 v[104:107], v[180:183], v[214:217], v[104:107]
	v_mfma_f32_16x16x32_bf16 v[92:95], v[172:175], v[222:225], v[92:95]
	v_mfma_f32_16x16x32_bf16 v[88:91], v[180:183], v[222:225], v[88:91]
	v_mfma_f32_16x16x32_bf16 v[76:79], v[172:175], v[230:233], v[76:79]
	v_mfma_f32_16x16x32_bf16 v[72:75], v[180:183], v[230:233], v[72:75]
	v_mfma_f32_16x16x32_bf16 v[116:119], v[184:187], v[202:205], v[116:119]
	v_mfma_f32_16x16x32_bf16 v[112:115], v[194:197], v[202:205], v[112:115]
	v_mfma_f32_16x16x32_bf16 v[100:103], v[184:187], v[210:213], v[100:103]
	v_mfma_f32_16x16x32_bf16 v[96:99], v[194:197], v[210:213], v[96:99]
	v_mfma_f32_16x16x32_bf16 v[84:87], v[184:187], v[218:221], v[84:87]
	v_mfma_f32_16x16x32_bf16 v[80:83], v[194:197], v[218:221], v[80:83]
	v_mfma_f32_16x16x32_bf16 v[68:71], v[184:187], v[226:229], v[68:71]
	v_mfma_f32_16x16x32_bf16 v[64:67], v[194:197], v[226:229], v[64:67]
	v_mfma_f32_16x16x32_bf16 v[116:119], v[188:191], v[206:209], v[116:119]
	v_mfma_f32_16x16x32_bf16 v[112:115], v[198:201], v[206:209], v[112:115]
	v_mfma_f32_16x16x32_bf16 v[100:103], v[188:191], v[214:217], v[100:103]
	v_mfma_f32_16x16x32_bf16 v[96:99], v[198:201], v[214:217], v[96:99]
	v_mfma_f32_16x16x32_bf16 v[84:87], v[188:191], v[222:225], v[84:87]
	v_mfma_f32_16x16x32_bf16 v[80:83], v[198:201], v[222:225], v[80:83]
	v_mfma_f32_16x16x32_bf16 v[68:71], v[188:191], v[230:233], v[68:71]
	v_mfma_f32_16x16x32_bf16 v[64:67], v[198:201], v[230:233], v[64:67]
	s_barrier
; #define PG8_STAGE(bufoff, gbase, voff) do { _Pragma("unroll") for (int _i = 0; _i < 2; ++_i) \
;         __builtin_amdgcn_global_load_lds((const unsigned*)((const char*)(gbase) + (voff)[_i]), (LAS unsigned*)(lds + (bufoff) + ldsw + _i * 8192), 16, 0, 0); } while (0)
; #define PG8_LDA(dst, b, h) do { _Pragma("unroll") for (int m = 0; m < 4; ++m) _Pragma("unroll") for (int k = 0; k < 2; ++k) dst[m][k] = *(const LAS bf16x8*)(lds + PG8_SA(b, h) + aoff + m * 2048 + k * 1024); } while (0)
; #define PG8_MMA(ai, bj, At, Bt) do { __builtin_amdgcn_s_setprio(1); _Pragma("unroll") for (int m = 0; m < 4; ++m) _Pragma("unroll") for (int n = 0; n < 2; ++n) _Pragma("unroll") for (int k = 0; k < 2; ++k) \
;         acc[ai][bj][m][n] = __builtin_amdgcn_mfma_f32_16x16x32_bf16(Bt[n][k], At[m][k], acc[ai][bj][m][n], 0, 0, 0); __builtin_amdgcn_s_setprio(0); } while (0)
; #define PG8_WAIT_V(n) asm volatile("s_waitcnt vmcnt(" #n ")" ::: "memory")
; #define PG8_WAIT_L(n) asm volatile("s_waitcnt lgkmcnt(" #n ")" ::: "memory")
; #define PG8_BAR __builtin_amdgcn_s_barrier()
; #define PG8_SCHED __builtin_amdgcn_sched_barrier(0)
; template <class Epi>
; DI void gemm_phase(int wv, LAS unsigned char* lds, LAS unsigned char* scr, const Sched& S, const Epi& E) {
;     ...
;             PG8_LDA(At, 1, 1); PG8_STAGE(PG8_SB(1, 0), b3, voffB); PG8_STAGE(PG8_SB(1, 1), b3 + hstepB, voffB); PG8_STAGE(PG8_SA(1, 0), a3, voffA);
;             PG8_WAIT_V(8); PG8_WAIT_L(0); PG8_BAR; PG8_MMA(1, 0, At, B0); PG8_MMA(1, 1, At, B1); PG8_BAR; PG8_SCHED;
;         }
	s_add_i32 s30, s49, s38
	v_lshl_add_u64 v[144:145], v[144:145], 0, s[2:3]
	s_mov_b32 m0, s30
	ds_read_b128 v[202:205], v166 offset:49152
	ds_read_b128 v[206:209], v166 offset:50176
	ds_read_b128 v[210:213], v166 offset:51200
	ds_read_b128 v[214:217], v166 offset:52224
	ds_read_b128 v[218:221], v166 offset:53248
	ds_read_b128 v[222:225], v166 offset:54272
	ds_read_b128 v[226:229], v166 offset:55296
	ds_read_b128 v[230:233], v166 offset:56320
	global_load_lds_dwordx4 v[144:145], off
	s_add_i32 m0, s30, 0x2000
	s_add_u32 s28, s28, 0x40080
	v_lshl_add_u64 v[144:145], v[234:235], 0, s[2:3]
	s_addc_u32 s29, s29, 0
	s_add_i32 s30, s50, s38
	global_load_lds_dwordx4 v[144:145], off
	v_lshl_add_u64 v[144:145], s[28:29], 0, v[130:131]
	s_mov_b32 m0, s30
	s_nop 0
	global_load_lds_dwordx4 v[144:145], off
	v_lshl_add_u64 v[144:145], s[28:29], 0, v[134:135]
	s_add_i32 m0, s30, 0x2000
	s_nop 0
	global_load_lds_dwordx4 v[144:145], off
	v_lshl_add_u64 v[144:145], v[236:237], 0, s[2:3]
	s_mov_b32 m0, s45
	s_nop 0
	global_load_lds_dwordx4 v[144:145], off
	v_lshl_add_u64 v[144:145], v[238:239], 0, s[2:3]
	s_mov_b32 m0, s46
	s_nop 0
	global_load_lds_dwordx4 v[144:145], off
	s_waitcnt vmcnt(8) lgkmcnt(0)
	s_barrier
	v_mfma_f32_16x16x32_bf16 v[60:63], v[168:171], v[202:205], v[60:63]
	v_mfma_f32_16x16x32_bf16 v[56:59], v[176:179], v[202:205], v[56:59]
	v_mfma_f32_16x16x32_bf16 v[44:47], v[168:171], v[210:213], v[44:47]
	v_mfma_f32_16x16x32_bf16 v[40:43], v[176:179], v[210:213], v[40:43]
	v_mfma_f32_16x16x32_bf16 v[28:31], v[168:171], v[218:221], v[28:31]
	v_mfma_f32_16x16x32_bf16 v[24:27], v[176:179], v[218:221], v[24:27]
	v_mfma_f32_16x16x32_bf16 v[12:15], v[168:171], v[226:229], v[12:15]
	v_mfma_f32_16x16x32_bf16 v[8:11], v[176:179], v[226:229], v[8:11]
	v_mfma_f32_16x16x32_bf16 v[60:63], v[172:175], v[206:209], v[60:63]
	v_mfma_f32_16x16x32_bf16 v[56:59], v[180:183], v[206:209], v[56:59]
	v_mfma_f32_16x16x32_bf16 v[44:47], v[172:175], v[214:217], v[44:47]
	v_mfma_f32_16x16x32_bf16 v[40:43], v[180:183], v[214:217], v[40:43]
	v_mfma_f32_16x16x32_bf16 v[28:31], v[172:175], v[222:225], v[28:31]
	v_mfma_f32_16x16x32_bf16 v[24:27], v[180:183], v[222:225], v[24:27]
	v_mfma_f32_16x16x32_bf16 v[12:15], v[172:175], v[230:233], v[12:15]
	v_mfma_f32_16x16x32_bf16 v[8:11], v[180:183], v[230:233], v[8:11]
	v_mfma_f32_16x16x32_bf16 v[52:55], v[184:187], v[202:205], v[52:55]
	v_mfma_f32_16x16x32_bf16 v[48:51], v[194:197], v[202:205], v[48:51]
	v_mfma_f32_16x16x32_bf16 v[36:39], v[184:187], v[210:213], v[36:39]
	v_mfma_f32_16x16x32_bf16 v[32:35], v[194:197], v[210:213], v[32:35]
	v_mfma_f32_16x16x32_bf16 v[20:23], v[184:187], v[218:221], v[20:23]
	v_mfma_f32_16x16x32_bf16 v[16:19], v[194:197], v[218:221], v[16:19]
	v_mfma_f32_16x16x32_bf16 v[4:7], v[184:187], v[226:229], v[4:7]
	v_mfma_f32_16x16x32_bf16 v[0:3], v[194:197], v[226:229], v[0:3]
	v_mfma_f32_16x16x32_bf16 v[52:55], v[188:191], v[206:209], v[52:55]
	v_mfma_f32_16x16x32_bf16 v[48:51], v[198:201], v[206:209], v[48:51]
	v_mfma_f32_16x16x32_bf16 v[36:39], v[188:191], v[214:217], v[36:39]
	v_mfma_f32_16x16x32_bf16 v[32:35], v[198:201], v[214:217], v[32:35]
	v_mfma_f32_16x16x32_bf16 v[20:23], v[188:191], v[222:225], v[20:23]
	v_mfma_f32_16x16x32_bf16 v[16:19], v[198:201], v[222:225], v[16:19]
	v_mfma_f32_16x16x32_bf16 v[4:7], v[188:191], v[230:233], v[4:7]
	v_mfma_f32_16x16x32_bf16 v[0:3], v[198:201], v[230:233], v[0:3]
	s_barrier
	s_add_i32 s33, s33, 2
	s_add_u32 s25, s25, 0x100
	s_addc_u32 s27, s27, 0
	s_add_u32 s12, s12, 0x100
	s_addc_u32 s13, s13, 0
	s_cmp_gt_u32 s33, 13
	s_cbranch_scc0 .LBB0_588
	s_and_b64 vcc, exec, s[14:15]
	s_cbranch_vccz .LBB0_591
	s_barrier

; #define PG8_STAGE(bufoff, gbase, voff) do { _Pragma("unroll") for (int _i = 0; _i < 2; ++_i) \
;         __builtin_amdgcn_global_load_lds((const unsigned*)((const char*)(gbase) + (voff)[_i]), (LAS unsigned*)(lds + (bufoff) + ldsw + _i * 8192), 16, 0, 0); } while (0)
; #define PG8_LDA(dst, b, h) do { _Pragma("unroll") for (int m = 0; m < 4; ++m) _Pragma("unroll") for (int k = 0; k < 2; ++k) dst[m][k] = *(const LAS bf16x8*)(lds + PG8_SA(b, h) + aoff + m * 2048 + k * 1024); } while (0)
; #define PG8_LDB(dst, b, h) do { _Pragma("unroll") for (int n = 0; n < 2; ++n) _Pragma("unroll") for (int k = 0; k < 2; ++k) dst[n][k] = *(const LAS bf16x8*)(lds + PG8_SB(b, h) + boff + n * 2048 + k * 1024); } while (0)
; #define PG8_MMA(ai, bj, At, Bt) do { __builtin_amdgcn_s_setprio(1); _Pragma("unroll") for (int m = 0; m < 4; ++m) _Pragma("unroll") for (int n = 0; n < 2; ++n) _Pragma("unroll") for (int k = 0; k < 2; ++k) \
;         acc[ai][bj][m][n] = __builtin_amdgcn_mfma_f32_16x16x32_bf16(Bt[n][k], At[m][k], acc[ai][bj][m][n], 0, 0, 0); __builtin_amdgcn_s_setprio(0); } while (0)
; #define PG8_WAIT_V(n) asm volatile("s_waitcnt vmcnt(" #n ")" ::: "memory")
; #define PG8_WAIT_L(n) asm volatile("s_waitcnt lgkmcnt(" #n ")" ::: "memory")
; #define PG8_BAR __builtin_amdgcn_s_barrier()
; #define PG8_SCHED __builtin_amdgcn_sched_barrier(0)
; template <class Epi>
; DI void gemm_phase(int wv, LAS unsigned char* lds, LAS unsigned char* scr, const Sched& S, const Epi& E) {
;     ...
;             const bool last = (t == nt - 2);
;             const char* a1 = cA + (size_t)(t + 1) * kstep;
;             const char* a2 = last ? nA : cA + (size_t)(t + 2) * kstep; const char* b2 = last ? nB : cB + (size_t)(t + 2) * kstep;
;             const char* a3 = a2 + kstep; const char* b3 = b2 + kstep;
;             PG8_LDB(B0, 0, 0); PG8_LDB(B1, 0, 1); PG8_SCHED; PG8_LDA(At, 0, 0); PG8_STAGE(PG8_SA(1, 1), a1 + hstepA, voffA);
;             PG8_WAIT_V(8); PG8_WAIT_L(0); PG8_BAR; PG8_MMA(0, 0, At, B0); PG8_MMA(0, 1, At, B1); PG8_BAR; PG8_SCHED;
;             PG8_LDA(At, 0, 1); PG8_STAGE(PG8_SB(0, 0), b2, voffB); PG8_STAGE(PG8_SB(0, 1), b2 + hstepB, voffB); PG8_STAGE(PG8_SA(0, 0), a2, voffA);
.LBB0_684:
	s_add_u32 s24, s8, 0xfffc0080
	s_addc_u32 s25, s9, -1
	s_add_i32 s46, 0, 0x10000
	s_cmp_eq_u32 s45, 12
	s_cselect_b32 s27, s11, s25
	s_cselect_b32 s26, s15, s24
	v_add_u32_e32 v143, s46, v144
	s_cselect_b32 s25, s21, s19
	s_cselect_b32 s24, s20, s17
	s_add_i32 s48, 0, 0x14000
	ds_read_b128 v[146:149], v143
	ds_read_b128 v[150:153], v143 offset:1024
	ds_read_b128 v[154:157], v143 offset:2048
	ds_read_b128 v[158:161], v143 offset:3072
	v_add_u32_e32 v143, s48, v144
	ds_read_b128 v[162:165], v143
	ds_read_b128 v[166:169], v143 offset:1024
	ds_read_b128 v[170:173], v143 offset:2048
	ds_read_b128 v[174:177], v143 offset:3072
	v_lshl_add_u64 v[190:191], s[8:9], 0, v[140:141]
	s_add_i32 m0, s34, 0xc000
	ds_read_b128 v[178:181], v145
	ds_read_b128 v[182:185], v145 offset:1024
	ds_read_b128 v[186:189], v145 offset:2048
	ds_read_b128 v[194:197], v145 offset:3072
	ds_read_b128 v[198:201], v145 offset:4096
	ds_read_b128 v[202:205], v145 offset:5120
	ds_read_b128 v[206:209], v145 offset:6144
	ds_read_b128 v[210:213], v145 offset:7168
	global_load_lds_dwordx4 v[190:191], off
	v_lshl_add_u64 v[190:191], s[8:9], 0, v[138:139]
	s_add_i32 m0, s34, 0xe000
	s_nop 0
	global_load_lds_dwordx4 v[190:191], off
	s_waitcnt vmcnt(8) lgkmcnt(0)
	s_barrier
	v_mfma_f32_16x16x32_bf16 v[124:127], v[146:149], v[178:181], v[124:127]
	v_mfma_f32_16x16x32_bf16 v[120:123], v[154:157], v[178:181], v[120:123]
	v_mfma_f32_16x16x32_bf16 v[116:119], v[146:149], v[186:189], v[116:119]
	v_mfma_f32_16x16x32_bf16 v[112:115], v[154:157], v[186:189], v[112:115]
	v_mfma_f32_16x16x32_bf16 v[100:103], v[146:149], v[198:201], v[100:103]
	v_mfma_f32_16x16x32_bf16 v[96:99], v[154:157], v[198:201], v[96:99]
	v_mfma_f32_16x16x32_bf16 v[84:87], v[146:149], v[206:209], v[84:87]
	v_mfma_f32_16x16x32_bf16 v[80:83], v[154:157], v[206:209], v[80:83]
	v_mfma_f32_16x16x32_bf16 v[124:127], v[150:153], v[182:185], v[124:127]
	v_mfma_f32_16x16x32_bf16 v[120:123], v[158:161], v[182:185], v[120:123]
	v_mfma_f32_16x16x32_bf16 v[116:119], v[150:153], v[194:197], v[116:119]
	v_mfma_f32_16x16x32_bf16 v[112:115], v[158:161], v[194:197], v[112:115]
	v_mfma_f32_16x16x32_bf16 v[100:103], v[150:153], v[202:205], v[100:103]
	v_mfma_f32_16x16x32_bf16 v[96:99], v[158:161], v[202:205], v[96:99]
	v_mfma_f32_16x16x32_bf16 v[84:87], v[150:153], v[210:213], v[84:87]
	v_mfma_f32_16x16x32_bf16 v[80:83], v[158:161], v[210:213], v[80:83]
	v_mfma_f32_16x16x32_bf16 v[108:111], v[162:165], v[178:181], v[108:111]
	v_mfma_f32_16x16x32_bf16 v[104:107], v[170:173], v[178:181], v[104:107]
	v_mfma_f32_16x16x32_bf16 v[92:95], v[162:165], v[186:189], v[92:95]
	v_mfma_f32_16x16x32_bf16 v[88:91], v[170:173], v[186:189], v[88:91]
	v_mfma_f32_16x16x32_bf16 v[76:79], v[162:165], v[198:201], v[76:79]
	v_mfma_f32_16x16x32_bf16 v[72:75], v[170:173], v[198:201], v[72:75]
	v_mfma_f32_16x16x32_bf16 v[68:71], v[162:165], v[206:209], v[68:71]
	v_mfma_f32_16x16x32_bf16 v[64:67], v[170:173], v[206:209], v[64:67]
	v_mfma_f32_16x16x32_bf16 v[108:111], v[166:169], v[182:185], v[108:111]
	v_mfma_f32_16x16x32_bf16 v[104:107], v[174:177], v[182:185], v[104:107]
	v_mfma_f32_16x16x32_bf16 v[92:95], v[166:169], v[194:197], v[92:95]
	v_mfma_f32_16x16x32_bf16 v[88:91], v[174:177], v[194:197], v[88:91]
	v_mfma_f32_16x16x32_bf16 v[76:79], v[166:169], v[202:205], v[76:79]
	v_mfma_f32_16x16x32_bf16 v[72:75], v[174:177], v[202:205], v[72:75]
	v_mfma_f32_16x16x32_bf16 v[68:71], v[166:169], v[210:213], v[68:71]
	v_mfma_f32_16x16x32_bf16 v[64:67], v[174:177], v[210:213], v[64:67]
	s_barrier
	s_add_i32 s46, s46, s33
	v_lshl_add_u64 v[190:191], s[24:25], 0, v[132:133]
	s_mov_b32 m0, s46
	ds_read_b128 v[178:181], v145 offset:16384
	ds_read_b128 v[182:185], v145 offset:17408
	ds_read_b128 v[186:189], v145 offset:18432
	ds_read_b128 v[194:197], v145 offset:19456
	ds_read_b128 v[198:201], v145 offset:20480
	ds_read_b128 v[202:205], v145 offset:21504
	ds_read_b128 v[206:209], v145 offset:22528
	ds_read_b128 v[210:213], v145 offset:23552
	global_load_lds_dwordx4 v[190:191], off
	s_add_i32 m0, s46, 0x2000
	s_add_u32 s46, s24, 0x40000
	v_lshl_add_u64 v[214:215], s[24:25], 0, v[128:129]
	s_addc_u32 s47, s25, 0
	s_add_i32 s48, s48, s33
	global_load_lds_dwordx4 v[214:215], off
	v_lshl_add_u64 v[216:217], s[46:47], 0, v[132:133]
	s_mov_b32 m0, s48
	v_lshl_add_u64 v[218:219], s[26:27], 0, v[130:131]
	global_load_lds_dwordx4 v[216:217], off
	v_lshl_add_u64 v[216:217], s[46:47], 0, v[128:129]
	s_add_i32 m0, s48, 0x2000
	s_nop 0
	global_load_lds_dwordx4 v[216:217], off
	v_lshl_add_u64 v[216:217], s[26:27], 0, v[134:135]
	s_mov_b32 m0, s34
	s_nop 0
	global_load_lds_dwordx4 v[216:217], off
	s_mov_b32 m0, s35
	s_nop 0
	global_load_lds_dwordx4 v[218:219], off
	s_waitcnt vmcnt(8) lgkmcnt(0)
	s_barrier
; #define PG8_STAGE(bufoff, gbase, voff) do { _Pragma("unroll") for (int _i = 0; _i < 2; ++_i) \
;         __builtin_amdgcn_global_load_lds((const unsigned*)((const char*)(gbase) + (voff)[_i]), (LAS unsigned*)(lds + (bufoff) + ldsw + _i * 8192), 16, 0, 0); } while (0)
; #define PG8_LDA(dst, b, h) do { _Pragma("unroll") for (int m = 0; m < 4; ++m) _Pragma("unroll") for (int k = 0; k < 2; ++k) dst[m][k] = *(const LAS bf16x8*)(lds + PG8_SA(b, h) + aoff + m * 2048 + k * 1024); } while (0)
; #define PG8_LDB(dst, b, h) do { _Pragma("unroll") for (int n = 0; n < 2; ++n) _Pragma("unroll") for (int k = 0; k < 2; ++k) dst[n][k] = *(const LAS bf16x8*)(lds + PG8_SB(b, h) + boff + n * 2048 + k * 1024); } while (0)
; #define PG8_MMA(ai, bj, At, Bt) do { __builtin_amdgcn_s_setprio(1); _Pragma("unroll") for (int m = 0; m < 4; ++m) _Pragma("unroll") for (int n = 0; n < 2; ++n) _Pragma("unroll") for (int k = 0; k < 2; ++k) \
;         acc[ai][bj][m][n] = __builtin_amdgcn_mfma_f32_16x16x32_bf16(Bt[n][k], At[m][k], acc[ai][bj][m][n], 0, 0, 0); __builtin_amdgcn_s_setprio(0); } while (0)
; #define PG8_WAIT_V(n) asm volatile("s_waitcnt vmcnt(" #n ")" ::: "memory")
; #define PG8_WAIT_L(n) asm volatile("s_waitcnt lgkmcnt(" #n ")" ::: "memory")
; #define PG8_BAR __builtin_amdgcn_s_barrier()
; #define PG8_SCHED __builtin_amdgcn_sched_barrier(0)
; template <class Epi>
; DI void gemm_phase(int wv, LAS unsigned char* lds, LAS unsigned char* scr, const Sched& S, const Epi& E) {
;     ...
;             PG8_WAIT_V(8); PG8_WAIT_L(0); PG8_BAR; PG8_MMA(1, 0, At, B0); PG8_MMA(1, 1, At, B1); PG8_BAR; PG8_SCHED;
;             PG8_LDB(B0, 1, 0); PG8_LDB(B1, 1, 1); PG8_SCHED; PG8_LDA(At, 1, 0); PG8_STAGE(PG8_SA(0, 1), a2 + hstepA, voffA);
;             PG8_WAIT_V(8); PG8_WAIT_L(0); PG8_BAR; PG8_MMA(0, 0, At, B0); PG8_MMA(0, 1, At, B1); PG8_BAR; PG8_SCHED;
	v_mfma_f32_16x16x32_bf16 v[60:63], v[146:149], v[178:181], v[60:63]
	v_mfma_f32_16x16x32_bf16 v[56:59], v[154:157], v[178:181], v[56:59]
	v_mfma_f32_16x16x32_bf16 v[52:55], v[146:149], v[186:189], v[52:55]
	v_mfma_f32_16x16x32_bf16 v[48:51], v[154:157], v[186:189], v[48:51]
	v_mfma_f32_16x16x32_bf16 v[36:39], v[146:149], v[198:201], v[36:39]
	v_mfma_f32_16x16x32_bf16 v[32:35], v[154:157], v[198:201], v[32:35]
	v_mfma_f32_16x16x32_bf16 v[20:23], v[146:149], v[206:209], v[20:23]
	v_mfma_f32_16x16x32_bf16 v[16:19], v[154:157], v[206:209], v[16:19]
	v_mfma_f32_16x16x32_bf16 v[60:63], v[150:153], v[182:185], v[60:63]
	v_mfma_f32_16x16x32_bf16 v[56:59], v[158:161], v[182:185], v[56:59]
	v_mfma_f32_16x16x32_bf16 v[52:55], v[150:153], v[194:197], v[52:55]
	v_mfma_f32_16x16x32_bf16 v[48:51], v[158:161], v[194:197], v[48:51]
	v_mfma_f32_16x16x32_bf16 v[36:39], v[150:153], v[202:205], v[36:39]
	v_mfma_f32_16x16x32_bf16 v[32:35], v[158:161], v[202:205], v[32:35]
	v_mfma_f32_16x16x32_bf16 v[20:23], v[150:153], v[210:213], v[20:23]
	v_mfma_f32_16x16x32_bf16 v[16:19], v[158:161], v[210:213], v[16:19]
	v_mfma_f32_16x16x32_bf16 v[44:47], v[162:165], v[178:181], v[44:47]
	v_mfma_f32_16x16x32_bf16 v[40:43], v[170:173], v[178:181], v[40:43]
	v_mfma_f32_16x16x32_bf16 v[28:31], v[162:165], v[186:189], v[28:31]
	v_mfma_f32_16x16x32_bf16 v[24:27], v[170:173], v[186:189], v[24:27]
	v_mfma_f32_16x16x32_bf16 v[12:15], v[162:165], v[198:201], v[12:15]
	v_mfma_f32_16x16x32_bf16 v[8:11], v[170:173], v[198:201], v[8:11]
	v_mfma_f32_16x16x32_bf16 v[4:7], v[162:165], v[206:209], v[4:7]
	v_mfma_f32_16x16x32_bf16 v[0:3], v[170:173], v[206:209], v[0:3]
	v_mfma_f32_16x16x32_bf16 v[44:47], v[166:169], v[182:185], v[44:47]
	v_mfma_f32_16x16x32_bf16 v[40:43], v[174:177], v[182:185], v[40:43]
	v_mfma_f32_16x16x32_bf16 v[28:31], v[166:169], v[194:197], v[28:31]
	v_mfma_f32_16x16x32_bf16 v[24:27], v[174:177], v[194:197], v[24:27]
	v_mfma_f32_16x16x32_bf16 v[12:15], v[166:169], v[202:205], v[12:15]
	v_mfma_f32_16x16x32_bf16 v[8:11], v[174:177], v[202:205], v[8:11]
	v_mfma_f32_16x16x32_bf16 v[4:7], v[166:169], v[210:213], v[4:7]
	v_mfma_f32_16x16x32_bf16 v[0:3], v[174:177], v[210:213], v[0:3]
	s_barrier
	s_add_i32 s46, 0, 0x18000
	v_add_u32_e32 v143, s46, v144
	s_add_i32 s47, 0, 0x1c000
	ds_read_b128 v[146:149], v143
	ds_read_b128 v[150:153], v143 offset:1024
	ds_read_b128 v[154:157], v143 offset:2048
	ds_read_b128 v[158:161], v143 offset:3072
	v_add_u32_e32 v143, s47, v144
	ds_read_b128 v[162:165], v143
	ds_read_b128 v[166:169], v143 offset:1024
	ds_read_b128 v[170:173], v143 offset:2048
	ds_read_b128 v[174:177], v143 offset:3072
	s_add_u32 s26, s26, 0x40000
	s_addc_u32 s27, s27, 0
	s_mov_b32 m0, s36
	v_lshl_add_u64 v[220:221], s[26:27], 0, v[134:135]
	ds_read_b128 v[178:181], v145 offset:32768
	ds_read_b128 v[182:185], v145 offset:33792
	ds_read_b128 v[186:189], v145 offset:34816
	ds_read_b128 v[194:197], v145 offset:35840
	ds_read_b128 v[198:201], v145 offset:36864
	ds_read_b128 v[202:205], v145 offset:37888
	ds_read_b128 v[206:209], v145 offset:38912
	ds_read_b128 v[210:213], v145 offset:39936
	global_load_lds_dwordx4 v[220:221], off
	v_lshl_add_u64 v[220:221], s[26:27], 0, v[130:131]
	s_mov_b32 m0, s37
	s_nop 0
	global_load_lds_dwordx4 v[220:221], off
	s_waitcnt vmcnt(8) lgkmcnt(0)
	s_barrier
	v_mfma_f32_16x16x32_bf16 v[124:127], v[146:149], v[178:181], v[124:127]
	v_mfma_f32_16x16x32_bf16 v[120:123], v[154:157], v[178:181], v[120:123]
	v_mfma_f32_16x16x32_bf16 v[116:119], v[146:149], v[186:189], v[116:119]
	v_mfma_f32_16x16x32_bf16 v[112:115], v[154:157], v[186:189], v[112:115]
	v_mfma_f32_16x16x32_bf16 v[100:103], v[146:149], v[198:201], v[100:103]
	v_mfma_f32_16x16x32_bf16 v[96:99], v[154:157], v[198:201], v[96:99]
	v_mfma_f32_16x16x32_bf16 v[84:87], v[146:149], v[206:209], v[84:87]
	v_mfma_f32_16x16x32_bf16 v[80:83], v[154:157], v[206:209], v[80:83]
	v_mfma_f32_16x16x32_bf16 v[124:127], v[150:153], v[182:185], v[124:127]
	v_mfma_f32_16x16x32_bf16 v[120:123], v[158:161], v[182:185], v[120:123]
	v_mfma_f32_16x16x32_bf16 v[116:119], v[150:153], v[194:197], v[116:119]
	v_mfma_f32_16x16x32_bf16 v[112:115], v[158:161], v[194:197], v[112:115]
	v_mfma_f32_16x16x32_bf16 v[100:103], v[150:153], v[202:205], v[100:103]
	v_mfma_f32_16x16x32_bf16 v[96:99], v[158:161], v[202:205], v[96:99]
	v_mfma_f32_16x16x32_bf16 v[84:87], v[150:153], v[210:213], v[84:87]
	v_mfma_f32_16x16x32_bf16 v[80:83], v[158:161], v[210:213], v[80:83]
	v_mfma_f32_16x16x32_bf16 v[108:111], v[162:165], v[178:181], v[108:111]
	v_mfma_f32_16x16x32_bf16 v[104:107], v[170:173], v[178:181], v[104:107]
	v_mfma_f32_16x16x32_bf16 v[92:95], v[162:165], v[186:189], v[92:95]
	v_mfma_f32_16x16x32_bf16 v[88:91], v[170:173], v[186:189], v[88:91]
	v_mfma_f32_16x16x32_bf16 v[76:79], v[162:165], v[198:201], v[76:79]
	v_mfma_f32_16x16x32_bf16 v[72:75], v[170:173], v[198:201], v[72:75]
	v_mfma_f32_16x16x32_bf16 v[68:71], v[162:165], v[206:209], v[68:71]
	v_mfma_f32_16x16x32_bf16 v[64:67], v[170:173], v[206:209], v[64:67]
	v_mfma_f32_16x16x32_bf16 v[108:111], v[166:169], v[182:185], v[108:111]
	v_mfma_f32_16x16x32_bf16 v[104:107], v[174:177], v[182:185], v[104:107]
	v_mfma_f32_16x16x32_bf16 v[92:95], v[166:169], v[194:197], v[92:95]
	v_mfma_f32_16x16x32_bf16 v[88:91], v[174:177], v[194:197], v[88:91]
	v_mfma_f32_16x16x32_bf16 v[76:79], v[166:169], v[202:205], v[76:79]
	v_mfma_f32_16x16x32_bf16 v[72:75], v[174:177], v[202:205], v[72:75]
	v_mfma_f32_16x16x32_bf16 v[68:71], v[166:169], v[210:213], v[68:71]
	v_mfma_f32_16x16x32_bf16 v[64:67], v[174:177], v[210:213], v[64:67]
	s_barrier
; #define PG8_STAGE(bufoff, gbase, voff) do { _Pragma("unroll") for (int _i = 0; _i < 2; ++_i) \
;         __builtin_amdgcn_global_load_lds((const unsigned*)((const char*)(gbase) + (voff)[_i]), (LAS unsigned*)(lds + (bufoff) + ldsw + _i * 8192), 16, 0, 0); } while (0)
; #define PG8_LDA(dst, b, h) do { _Pragma("unroll") for (int m = 0; m < 4; ++m) _Pragma("unroll") for (int k = 0; k < 2; ++k) dst[m][k] = *(const LAS bf16x8*)(lds + PG8_SA(b, h) + aoff + m * 2048 + k * 1024); } while (0)
; #define PG8_MMA(ai, bj, At, Bt) do { __builtin_amdgcn_s_setprio(1); _Pragma("unroll") for (int m = 0; m < 4; ++m) _Pragma("unroll") for (int n = 0; n < 2; ++n) _Pragma("unroll") for (int k = 0; k < 2; ++k) \
;         acc[ai][bj][m][n] = __builtin_amdgcn_mfma_f32_16x16x32_bf16(Bt[n][k], At[m][k], acc[ai][bj][m][n], 0, 0, 0); __builtin_amdgcn_s_setprio(0); } while (0)
; #define PG8_WAIT_V(n) asm volatile("s_waitcnt vmcnt(" #n ")" ::: "memory")
; #define PG8_WAIT_L(n) asm volatile("s_waitcnt lgkmcnt(" #n ")" ::: "memory")
; #define PG8_BAR __builtin_amdgcn_s_barrier()
; #define PG8_SCHED __builtin_amdgcn_sched_barrier(0)
; template <class Epi>
; DI void gemm_phase(int wv, LAS unsigned char* lds, LAS unsigned char* scr, const Sched& S, const Epi& E) {
;     ...
;             PG8_LDA(At, 1, 1); PG8_STAGE(PG8_SB(1, 0), b3, voffB); PG8_STAGE(PG8_SB(1, 1), b3 + hstepB, voffB); PG8_STAGE(PG8_SA(1, 0), a3, voffA);
;             PG8_WAIT_V(8); PG8_WAIT_L(0); PG8_BAR; PG8_MMA(1, 0, At, B0); PG8_MMA(1, 1, At, B1); PG8_BAR; PG8_SCHED;
;         }
	s_add_i32 s26, s46, s33
	v_lshl_add_u64 v[190:191], v[190:191], 0, s[2:3]
	s_mov_b32 m0, s26
	ds_read_b128 v[178:181], v145 offset:49152
	ds_read_b128 v[182:185], v145 offset:50176
	ds_read_b128 v[186:189], v145 offset:51200
	ds_read_b128 v[194:197], v145 offset:52224
	ds_read_b128 v[198:201], v145 offset:53248
	ds_read_b128 v[202:205], v145 offset:54272
	ds_read_b128 v[206:209], v145 offset:55296
	ds_read_b128 v[210:213], v145 offset:56320
	global_load_lds_dwordx4 v[190:191], off
	s_add_i32 m0, s26, 0x2000
	s_add_u32 s24, s24, 0x40080
	v_lshl_add_u64 v[190:191], v[214:215], 0, s[2:3]
	s_addc_u32 s25, s25, 0
	s_add_i32 s26, s47, s33
	global_load_lds_dwordx4 v[190:191], off
	v_lshl_add_u64 v[190:191], s[24:25], 0, v[132:133]
	s_mov_b32 m0, s26
	s_nop 0
	global_load_lds_dwordx4 v[190:191], off
	v_lshl_add_u64 v[190:191], s[24:25], 0, v[128:129]
	s_add_i32 m0, s26, 0x2000
	s_nop 0
	global_load_lds_dwordx4 v[190:191], off
	v_lshl_add_u64 v[190:191], v[216:217], 0, s[2:3]
	s_mov_b32 m0, s42
	s_nop 0
	global_load_lds_dwordx4 v[190:191], off
	v_lshl_add_u64 v[190:191], v[218:219], 0, s[2:3]
	s_mov_b32 m0, s43
	s_nop 0
	global_load_lds_dwordx4 v[190:191], off
	s_waitcnt vmcnt(8) lgkmcnt(0)
	s_barrier
	v_mfma_f32_16x16x32_bf16 v[60:63], v[146:149], v[178:181], v[60:63]
	v_mfma_f32_16x16x32_bf16 v[56:59], v[154:157], v[178:181], v[56:59]
	v_mfma_f32_16x16x32_bf16 v[52:55], v[146:149], v[186:189], v[52:55]
	v_mfma_f32_16x16x32_bf16 v[48:51], v[154:157], v[186:189], v[48:51]
	v_mfma_f32_16x16x32_bf16 v[36:39], v[146:149], v[198:201], v[36:39]
	v_mfma_f32_16x16x32_bf16 v[32:35], v[154:157], v[198:201], v[32:35]
	v_mfma_f32_16x16x32_bf16 v[20:23], v[146:149], v[206:209], v[20:23]
	v_mfma_f32_16x16x32_bf16 v[16:19], v[154:157], v[206:209], v[16:19]
	v_mfma_f32_16x16x32_bf16 v[60:63], v[150:153], v[182:185], v[60:63]
	v_mfma_f32_16x16x32_bf16 v[56:59], v[158:161], v[182:185], v[56:59]
	v_mfma_f32_16x16x32_bf16 v[52:55], v[150:153], v[194:197], v[52:55]
	v_mfma_f32_16x16x32_bf16 v[48:51], v[158:161], v[194:197], v[48:51]
	v_mfma_f32_16x16x32_bf16 v[36:39], v[150:153], v[202:205], v[36:39]
	v_mfma_f32_16x16x32_bf16 v[32:35], v[158:161], v[202:205], v[32:35]
	v_mfma_f32_16x16x32_bf16 v[20:23], v[150:153], v[210:213], v[20:23]
	v_mfma_f32_16x16x32_bf16 v[16:19], v[158:161], v[210:213], v[16:19]
	v_mfma_f32_16x16x32_bf16 v[44:47], v[162:165], v[178:181], v[44:47]
	v_mfma_f32_16x16x32_bf16 v[40:43], v[170:173], v[178:181], v[40:43]
	v_mfma_f32_16x16x32_bf16 v[28:31], v[162:165], v[186:189], v[28:31]
	v_mfma_f32_16x16x32_bf16 v[24:27], v[170:173], v[186:189], v[24:27]
	v_mfma_f32_16x16x32_bf16 v[12:15], v[162:165], v[198:201], v[12:15]
	v_mfma_f32_16x16x32_bf16 v[8:11], v[170:173], v[198:201], v[8:11]
	v_mfma_f32_16x16x32_bf16 v[4:7], v[162:165], v[206:209], v[4:7]
	v_mfma_f32_16x16x32_bf16 v[0:3], v[170:173], v[206:209], v[0:3]
	v_mfma_f32_16x16x32_bf16 v[44:47], v[166:169], v[182:185], v[44:47]
	v_mfma_f32_16x16x32_bf16 v[40:43], v[174:177], v[182:185], v[40:43]
	v_mfma_f32_16x16x32_bf16 v[28:31], v[166:169], v[194:197], v[28:31]
	v_mfma_f32_16x16x32_bf16 v[24:27], v[174:177], v[194:197], v[24:27]
	v_mfma_f32_16x16x32_bf16 v[12:15], v[166:169], v[202:205], v[12:15]
	v_mfma_f32_16x16x32_bf16 v[8:11], v[174:177], v[202:205], v[8:11]
	v_mfma_f32_16x16x32_bf16 v[4:7], v[166:169], v[210:213], v[4:7]
	v_mfma_f32_16x16x32_bf16 v[0:3], v[174:177], v[210:213], v[0:3]
	s_barrier
	s_add_i32 s45, s45, 2
	s_add_u32 s17, s17, 0x100
	s_addc_u32 s19, s19, 0
	s_add_u32 s8, s8, 0x100
	s_addc_u32 s9, s9, 0
	s_cmp_gt_u32 s45, 13
	s_cbranch_scc0 .LBB0_684
	s_and_b64 vcc, exec, s[12:13]
	s_cbranch_vccz .LBB0_687
	s_barrier

; #define PG8_STAGE(bufoff, gbase, voff) do { _Pragma("unroll") for (int _i = 0; _i < 2; ++_i) \
;         __builtin_amdgcn_global_load_lds((const unsigned*)((const char*)(gbase) + (voff)[_i]), (LAS unsigned*)(lds + (bufoff) + ldsw + _i * 8192), 16, 0, 0); } while (0)
; #define PG8_LDA(dst, b, h) do { _Pragma("unroll") for (int m = 0; m < 4; ++m) _Pragma("unroll") for (int k = 0; k < 2; ++k) dst[m][k] = *(const LAS bf16x8*)(lds + PG8_SA(b, h) + aoff + m * 2048 + k * 1024); } while (0)
; #define PG8_LDB(dst, b, h) do { _Pragma("unroll") for (int n = 0; n < 2; ++n) _Pragma("unroll") for (int k = 0; k < 2; ++k) dst[n][k] = *(const LAS bf16x8*)(lds + PG8_SB(b, h) + boff + n * 2048 + k * 1024); } while (0)
; #define PG8_MMA(ai, bj, At, Bt) do { __builtin_amdgcn_s_setprio(1); _Pragma("unroll") for (int m = 0; m < 4; ++m) _Pragma("unroll") for (int n = 0; n < 2; ++n) _Pragma("unroll") for (int k = 0; k < 2; ++k) \
;         acc[ai][bj][m][n] = __builtin_amdgcn_mfma_f32_16x16x32_bf16(Bt[n][k], At[m][k], acc[ai][bj][m][n], 0, 0, 0); __builtin_amdgcn_s_setprio(0); } while (0)
; #define PG8_WAIT_V(n) asm volatile("s_waitcnt vmcnt(" #n ")" ::: "memory")
; #define PG8_WAIT_L(n) asm volatile("s_waitcnt lgkmcnt(" #n ")" ::: "memory")
; #define PG8_BAR __builtin_amdgcn_s_barrier()
; #define PG8_SCHED __builtin_amdgcn_sched_barrier(0)
; template <class Epi>
; DI void gemm_phase(int wv, LAS unsigned char* lds, LAS unsigned char* scr, const Sched& S, const Epi& E) {
;     ...
;             const bool last = (t == nt - 2);
;             const char* a1 = cA + (size_t)(t + 1) * kstep;
;             const char* a2 = last ? nA : cA + (size_t)(t + 2) * kstep; const char* b2 = last ? nB : cB + (size_t)(t + 2) * kstep;
;             const char* a3 = a2 + kstep; const char* b3 = b2 + kstep;
;             PG8_LDB(B0, 0, 0); PG8_LDB(B1, 0, 1); PG8_SCHED; PG8_LDA(At, 0, 0); PG8_STAGE(PG8_SA(1, 1), a1 + hstepA, voffA);
;             PG8_WAIT_V(8); PG8_WAIT_L(0); PG8_BAR; PG8_MMA(0, 0, At, B0); PG8_MMA(0, 1, At, B1); PG8_BAR; PG8_SCHED;
;             PG8_LDA(At, 0, 1); PG8_STAGE(PG8_SB(0, 0), b2, voffB); PG8_STAGE(PG8_SB(0, 1), b2 + hstepB, voffB); PG8_STAGE(PG8_SA(0, 0), a2, voffA);
.LBB0_811:
	s_add_u32 s54, s28, 0xfffc0080
	s_addc_u32 s55, s29, -1
	s_add_i32 s61, 0, 0x10000
	s_cmp_eq_u32 s60, 12
	s_cselect_b32 s57, s49, s55
	s_cselect_b32 s56, s48, s54
	s_cselect_b32 s55, s47, s59
	s_cselect_b32 s54, s53, s58
	s_add_i32 s76, 0, 0x14000
	v_add_u32_e32 v140, s61, v199
	v_add_u32_e32 v156, s76, v199
	ds_read_b128 v[128:131], v140
	ds_read_b128 v[132:135], v140 offset:1024
	ds_read_b128 v[136:139], v140 offset:2048
	ds_read_b128 v[140:143], v140 offset:3072
	ds_read_b128 v[144:147], v156
	ds_read_b128 v[148:151], v156 offset:1024
	ds_read_b128 v[152:155], v156 offset:2048
	ds_read_b128 v[156:159], v156 offset:3072
	v_lshl_add_u64 v[204:205], s[28:29], 0, v[178:179]
	s_add_i32 m0, s66, 0xc000
	ds_read_b128 v[160:163], v220
	ds_read_b128 v[164:167], v220 offset:1024
	ds_read_b128 v[180:183], v220 offset:2048
	ds_read_b128 v[184:187], v220 offset:3072
	ds_read_b128 v[188:191], v220 offset:4096
	ds_read_b128 v[194:197], v220 offset:5120
	ds_read_b128 v[200:203], v220 offset:6144
	ds_read_b128 v[222:225], v220 offset:7168
	global_load_lds_dwordx4 v[204:205], off
	v_lshl_add_u64 v[204:205], s[28:29], 0, v[176:177]
	s_add_i32 m0, s66, 0xe000
	s_nop 0
	global_load_lds_dwordx4 v[204:205], off
	s_waitcnt vmcnt(8) lgkmcnt(0)
	s_barrier
	v_mfma_f32_16x16x32_bf16 v[124:127], v[128:131], v[160:163], v[124:127]
	v_mfma_f32_16x16x32_bf16 v[92:95], v[136:139], v[160:163], v[92:95]
	v_mfma_f32_16x16x32_bf16 v[116:119], v[128:131], v[180:183], v[116:119]
	v_mfma_f32_16x16x32_bf16 v[84:87], v[136:139], v[180:183], v[84:87]
	v_mfma_f32_16x16x32_bf16 v[108:111], v[128:131], v[188:191], v[108:111]
	v_mfma_f32_16x16x32_bf16 v[76:79], v[136:139], v[188:191], v[76:79]
	v_mfma_f32_16x16x32_bf16 v[100:103], v[128:131], v[200:203], v[100:103]
	v_mfma_f32_16x16x32_bf16 v[68:71], v[136:139], v[200:203], v[68:71]
	v_mfma_f32_16x16x32_bf16 v[124:127], v[132:135], v[164:167], v[124:127]
	v_mfma_f32_16x16x32_bf16 v[92:95], v[140:143], v[164:167], v[92:95]
	v_mfma_f32_16x16x32_bf16 v[116:119], v[132:135], v[184:187], v[116:119]
	v_mfma_f32_16x16x32_bf16 v[84:87], v[140:143], v[184:187], v[84:87]
	v_mfma_f32_16x16x32_bf16 v[108:111], v[132:135], v[194:197], v[108:111]
	v_mfma_f32_16x16x32_bf16 v[76:79], v[140:143], v[194:197], v[76:79]
	v_mfma_f32_16x16x32_bf16 v[100:103], v[132:135], v[222:225], v[100:103]
	v_mfma_f32_16x16x32_bf16 v[68:71], v[140:143], v[222:225], v[68:71]
	v_mfma_f32_16x16x32_bf16 v[120:123], v[144:147], v[160:163], v[120:123]
	v_mfma_f32_16x16x32_bf16 v[88:91], v[152:155], v[160:163], v[88:91]
	v_mfma_f32_16x16x32_bf16 v[112:115], v[144:147], v[180:183], v[112:115]
	v_mfma_f32_16x16x32_bf16 v[80:83], v[152:155], v[180:183], v[80:83]
	v_mfma_f32_16x16x32_bf16 v[104:107], v[144:147], v[188:191], v[104:107]
	v_mfma_f32_16x16x32_bf16 v[72:75], v[152:155], v[188:191], v[72:75]
	v_mfma_f32_16x16x32_bf16 v[96:99], v[144:147], v[200:203], v[96:99]
	v_mfma_f32_16x16x32_bf16 v[64:67], v[152:155], v[200:203], v[64:67]
	v_mfma_f32_16x16x32_bf16 v[120:123], v[148:151], v[164:167], v[120:123]
	v_mfma_f32_16x16x32_bf16 v[88:91], v[156:159], v[164:167], v[88:91]
	v_mfma_f32_16x16x32_bf16 v[112:115], v[148:151], v[184:187], v[112:115]
	v_mfma_f32_16x16x32_bf16 v[80:83], v[156:159], v[184:187], v[80:83]
	v_mfma_f32_16x16x32_bf16 v[104:107], v[148:151], v[194:197], v[104:107]
	v_mfma_f32_16x16x32_bf16 v[72:75], v[156:159], v[194:197], v[72:75]
	v_mfma_f32_16x16x32_bf16 v[96:99], v[148:151], v[222:225], v[96:99]
	v_mfma_f32_16x16x32_bf16 v[64:67], v[156:159], v[222:225], v[64:67]
	s_barrier
	s_add_i32 s61, s61, s65
	v_lshl_add_u64 v[204:205], s[54:55], 0, v[170:171]
	s_mov_b32 m0, s61
	ds_read_b128 v[160:163], v220 offset:16384
	ds_read_b128 v[164:167], v220 offset:17408
	ds_read_b128 v[180:183], v220 offset:18432
	ds_read_b128 v[184:187], v220 offset:19456
	ds_read_b128 v[188:191], v220 offset:20480
	ds_read_b128 v[194:197], v220 offset:21504
	ds_read_b128 v[200:203], v220 offset:22528
	ds_read_b128 v[222:225], v220 offset:23552
	global_load_lds_dwordx4 v[204:205], off
	s_add_i32 m0, s61, 0x2000
	s_add_u32 s74, s54, 0x40000
	v_lshl_add_u64 v[226:227], s[54:55], 0, v[174:175]
	s_addc_u32 s75, s55, 0
	s_add_i32 s61, s76, s65
	global_load_lds_dwordx4 v[226:227], off
	v_lshl_add_u64 v[228:229], s[74:75], 0, v[170:171]
	s_mov_b32 m0, s61
	v_lshl_add_u64 v[230:231], s[56:57], 0, v[172:173]
	global_load_lds_dwordx4 v[228:229], off
	v_lshl_add_u64 v[228:229], s[74:75], 0, v[174:175]
	s_add_i32 m0, s61, 0x2000
	s_nop 0
	global_load_lds_dwordx4 v[228:229], off
	v_lshl_add_u64 v[228:229], s[56:57], 0, v[168:169]
	s_mov_b32 m0, s66
	s_nop 0
	global_load_lds_dwordx4 v[228:229], off
	s_mov_b32 m0, s67
	s_nop 0
	global_load_lds_dwordx4 v[230:231], off
	s_waitcnt vmcnt(8) lgkmcnt(0)
	s_barrier
; #define PG8_STAGE(bufoff, gbase, voff) do { _Pragma("unroll") for (int _i = 0; _i < 2; ++_i) \
;         __builtin_amdgcn_global_load_lds((const unsigned*)((const char*)(gbase) + (voff)[_i]), (LAS unsigned*)(lds + (bufoff) + ldsw + _i * 8192), 16, 0, 0); } while (0)
; #define PG8_LDA(dst, b, h) do { _Pragma("unroll") for (int m = 0; m < 4; ++m) _Pragma("unroll") for (int k = 0; k < 2; ++k) dst[m][k] = *(const LAS bf16x8*)(lds + PG8_SA(b, h) + aoff + m * 2048 + k * 1024); } while (0)
; #define PG8_LDB(dst, b, h) do { _Pragma("unroll") for (int n = 0; n < 2; ++n) _Pragma("unroll") for (int k = 0; k < 2; ++k) dst[n][k] = *(const LAS bf16x8*)(lds + PG8_SB(b, h) + boff + n * 2048 + k * 1024); } while (0)
; #define PG8_MMA(ai, bj, At, Bt) do { __builtin_amdgcn_s_setprio(1); _Pragma("unroll") for (int m = 0; m < 4; ++m) _Pragma("unroll") for (int n = 0; n < 2; ++n) _Pragma("unroll") for (int k = 0; k < 2; ++k) \
;         acc[ai][bj][m][n] = __builtin_amdgcn_mfma_f32_16x16x32_bf16(Bt[n][k], At[m][k], acc[ai][bj][m][n], 0, 0, 0); __builtin_amdgcn_s_setprio(0); } while (0)
; #define PG8_WAIT_V(n) asm volatile("s_waitcnt vmcnt(" #n ")" ::: "memory")
; #define PG8_WAIT_L(n) asm volatile("s_waitcnt lgkmcnt(" #n ")" ::: "memory")
; #define PG8_BAR __builtin_amdgcn_s_barrier()
; #define PG8_SCHED __builtin_amdgcn_sched_barrier(0)
; template <class Epi>
; DI void gemm_phase(int wv, LAS unsigned char* lds, LAS unsigned char* scr, const Sched& S, const Epi& E) {
;     ...
;             PG8_WAIT_V(8); PG8_WAIT_L(0); PG8_BAR; PG8_MMA(1, 0, At, B0); PG8_MMA(1, 1, At, B1); PG8_BAR; PG8_SCHED;
;             PG8_LDB(B0, 1, 0); PG8_LDB(B1, 1, 1); PG8_SCHED; PG8_LDA(At, 1, 0); PG8_STAGE(PG8_SA(0, 1), a2 + hstepA, voffA);
;             PG8_WAIT_V(8); PG8_WAIT_L(0); PG8_BAR; PG8_MMA(0, 0, At, B0); PG8_MMA(0, 1, At, B1); PG8_BAR; PG8_SCHED;
	v_mfma_f32_16x16x32_bf16 v[60:63], v[128:131], v[160:163], v[60:63]
	v_mfma_f32_16x16x32_bf16 v[28:31], v[136:139], v[160:163], v[28:31]
	v_mfma_f32_16x16x32_bf16 v[52:55], v[128:131], v[180:183], v[52:55]
	v_mfma_f32_16x16x32_bf16 v[20:23], v[136:139], v[180:183], v[20:23]
	v_mfma_f32_16x16x32_bf16 v[44:47], v[128:131], v[188:191], v[44:47]
	v_mfma_f32_16x16x32_bf16 v[12:15], v[136:139], v[188:191], v[12:15]
	v_mfma_f32_16x16x32_bf16 v[36:39], v[128:131], v[200:203], v[36:39]
	v_mfma_f32_16x16x32_bf16 v[4:7], v[136:139], v[200:203], v[4:7]
	v_mfma_f32_16x16x32_bf16 v[60:63], v[132:135], v[164:167], v[60:63]
	v_mfma_f32_16x16x32_bf16 v[28:31], v[140:143], v[164:167], v[28:31]
	v_mfma_f32_16x16x32_bf16 v[52:55], v[132:135], v[184:187], v[52:55]
	v_mfma_f32_16x16x32_bf16 v[20:23], v[140:143], v[184:187], v[20:23]
	v_mfma_f32_16x16x32_bf16 v[44:47], v[132:135], v[194:197], v[44:47]
	v_mfma_f32_16x16x32_bf16 v[12:15], v[140:143], v[194:197], v[12:15]
	v_mfma_f32_16x16x32_bf16 v[36:39], v[132:135], v[222:225], v[36:39]
	v_mfma_f32_16x16x32_bf16 v[4:7], v[140:143], v[222:225], v[4:7]
	v_mfma_f32_16x16x32_bf16 v[56:59], v[144:147], v[160:163], v[56:59]
	v_mfma_f32_16x16x32_bf16 v[24:27], v[152:155], v[160:163], v[24:27]
	v_mfma_f32_16x16x32_bf16 v[48:51], v[144:147], v[180:183], v[48:51]
	v_mfma_f32_16x16x32_bf16 v[16:19], v[152:155], v[180:183], v[16:19]
	v_mfma_f32_16x16x32_bf16 v[40:43], v[144:147], v[188:191], v[40:43]
	v_mfma_f32_16x16x32_bf16 v[8:11], v[152:155], v[188:191], v[8:11]
	v_mfma_f32_16x16x32_bf16 v[32:35], v[144:147], v[200:203], v[32:35]
	v_mfma_f32_16x16x32_bf16 v[0:3], v[152:155], v[200:203], v[0:3]
	v_mfma_f32_16x16x32_bf16 v[56:59], v[148:151], v[164:167], v[56:59]
	v_mfma_f32_16x16x32_bf16 v[24:27], v[156:159], v[164:167], v[24:27]
	v_mfma_f32_16x16x32_bf16 v[48:51], v[148:151], v[184:187], v[48:51]
	v_mfma_f32_16x16x32_bf16 v[16:19], v[156:159], v[184:187], v[16:19]
	v_mfma_f32_16x16x32_bf16 v[40:43], v[148:151], v[194:197], v[40:43]
	v_mfma_f32_16x16x32_bf16 v[8:11], v[156:159], v[194:197], v[8:11]
	v_mfma_f32_16x16x32_bf16 v[32:35], v[148:151], v[222:225], v[32:35]
	v_mfma_f32_16x16x32_bf16 v[0:3], v[156:159], v[222:225], v[0:3]
	s_barrier
	s_add_i32 s61, 0, 0x18000
	s_add_i32 s74, 0, 0x1c000
	v_add_u32_e32 v140, s61, v199
	v_add_u32_e32 v156, s74, v199
	ds_read_b128 v[128:131], v140
	ds_read_b128 v[132:135], v140 offset:1024
	ds_read_b128 v[136:139], v140 offset:2048
	ds_read_b128 v[140:143], v140 offset:3072
	ds_read_b128 v[144:147], v156
	ds_read_b128 v[148:151], v156 offset:1024
	ds_read_b128 v[152:155], v156 offset:2048
	ds_read_b128 v[156:159], v156 offset:3072
	s_add_u32 s56, s56, 0x40000
	s_addc_u32 s57, s57, 0
	s_mov_b32 m0, s68
	v_lshl_add_u64 v[232:233], s[56:57], 0, v[168:169]
	ds_read_b128 v[160:163], v220 offset:32768
	ds_read_b128 v[164:167], v220 offset:33792
	ds_read_b128 v[180:183], v220 offset:34816
	ds_read_b128 v[184:187], v220 offset:35840
	ds_read_b128 v[188:191], v220 offset:36864
	ds_read_b128 v[194:197], v220 offset:37888
	ds_read_b128 v[200:203], v220 offset:38912
	ds_read_b128 v[222:225], v220 offset:39936
	global_load_lds_dwordx4 v[232:233], off
	v_lshl_add_u64 v[232:233], s[56:57], 0, v[172:173]
	s_mov_b32 m0, s69
	s_nop 0
	global_load_lds_dwordx4 v[232:233], off
	s_waitcnt vmcnt(8) lgkmcnt(0)
	s_barrier
	v_mfma_f32_16x16x32_bf16 v[124:127], v[128:131], v[160:163], v[124:127]
	v_mfma_f32_16x16x32_bf16 v[92:95], v[136:139], v[160:163], v[92:95]
	v_mfma_f32_16x16x32_bf16 v[116:119], v[128:131], v[180:183], v[116:119]
	v_mfma_f32_16x16x32_bf16 v[84:87], v[136:139], v[180:183], v[84:87]
	v_mfma_f32_16x16x32_bf16 v[108:111], v[128:131], v[188:191], v[108:111]
	v_mfma_f32_16x16x32_bf16 v[76:79], v[136:139], v[188:191], v[76:79]
	v_mfma_f32_16x16x32_bf16 v[100:103], v[128:131], v[200:203], v[100:103]
	v_mfma_f32_16x16x32_bf16 v[68:71], v[136:139], v[200:203], v[68:71]
	v_mfma_f32_16x16x32_bf16 v[124:127], v[132:135], v[164:167], v[124:127]
	v_mfma_f32_16x16x32_bf16 v[92:95], v[140:143], v[164:167], v[92:95]
	v_mfma_f32_16x16x32_bf16 v[116:119], v[132:135], v[184:187], v[116:119]
	v_mfma_f32_16x16x32_bf16 v[84:87], v[140:143], v[184:187], v[84:87]
	v_mfma_f32_16x16x32_bf16 v[108:111], v[132:135], v[194:197], v[108:111]
	v_mfma_f32_16x16x32_bf16 v[76:79], v[140:143], v[194:197], v[76:79]
	v_mfma_f32_16x16x32_bf16 v[100:103], v[132:135], v[222:225], v[100:103]
	v_mfma_f32_16x16x32_bf16 v[68:71], v[140:143], v[222:225], v[68:71]
	v_mfma_f32_16x16x32_bf16 v[120:123], v[144:147], v[160:163], v[120:123]
	v_mfma_f32_16x16x32_bf16 v[88:91], v[152:155], v[160:163], v[88:91]
	v_mfma_f32_16x16x32_bf16 v[112:115], v[144:147], v[180:183], v[112:115]
	v_mfma_f32_16x16x32_bf16 v[80:83], v[152:155], v[180:183], v[80:83]
	v_mfma_f32_16x16x32_bf16 v[104:107], v[144:147], v[188:191], v[104:107]
	v_mfma_f32_16x16x32_bf16 v[72:75], v[152:155], v[188:191], v[72:75]
	v_mfma_f32_16x16x32_bf16 v[96:99], v[144:147], v[200:203], v[96:99]
	v_mfma_f32_16x16x32_bf16 v[64:67], v[152:155], v[200:203], v[64:67]
	v_mfma_f32_16x16x32_bf16 v[120:123], v[148:151], v[164:167], v[120:123]
	v_mfma_f32_16x16x32_bf16 v[88:91], v[156:159], v[164:167], v[88:91]
	v_mfma_f32_16x16x32_bf16 v[112:115], v[148:151], v[184:187], v[112:115]
	v_mfma_f32_16x16x32_bf16 v[80:83], v[156:159], v[184:187], v[80:83]
	v_mfma_f32_16x16x32_bf16 v[104:107], v[148:151], v[194:197], v[104:107]
	v_mfma_f32_16x16x32_bf16 v[72:75], v[156:159], v[194:197], v[72:75]
	v_mfma_f32_16x16x32_bf16 v[96:99], v[148:151], v[222:225], v[96:99]
	v_mfma_f32_16x16x32_bf16 v[64:67], v[156:159], v[222:225], v[64:67]
	s_barrier
; #define PG8_STAGE(bufoff, gbase, voff) do { _Pragma("unroll") for (int _i = 0; _i < 2; ++_i) \
;         __builtin_amdgcn_global_load_lds((const unsigned*)((const char*)(gbase) + (voff)[_i]), (LAS unsigned*)(lds + (bufoff) + ldsw + _i * 8192), 16, 0, 0); } while (0)
; #define PG8_LDA(dst, b, h) do { _Pragma("unroll") for (int m = 0; m < 4; ++m) _Pragma("unroll") for (int k = 0; k < 2; ++k) dst[m][k] = *(const LAS bf16x8*)(lds + PG8_SA(b, h) + aoff + m * 2048 + k * 1024); } while (0)
; #define PG8_MMA(ai, bj, At, Bt) do { __builtin_amdgcn_s_setprio(1); _Pragma("unroll") for (int m = 0; m < 4; ++m) _Pragma("unroll") for (int n = 0; n < 2; ++n) _Pragma("unroll") for (int k = 0; k < 2; ++k) \
;         acc[ai][bj][m][n] = __builtin_amdgcn_mfma_f32_16x16x32_bf16(Bt[n][k], At[m][k], acc[ai][bj][m][n], 0, 0, 0); __builtin_amdgcn_s_setprio(0); } while (0)
; #define PG8_WAIT_V(n) asm volatile("s_waitcnt vmcnt(" #n ")" ::: "memory")
; #define PG8_WAIT_L(n) asm volatile("s_waitcnt lgkmcnt(" #n ")" ::: "memory")
; #define PG8_BAR __builtin_amdgcn_s_barrier()
; #define PG8_SCHED __builtin_amdgcn_sched_barrier(0)
; template <class Epi>
; DI void gemm_phase(int wv, LAS unsigned char* lds, LAS unsigned char* scr, const Sched& S, const Epi& E) {
;     ...
;             PG8_LDA(At, 1, 1); PG8_STAGE(PG8_SB(1, 0), b3, voffB); PG8_STAGE(PG8_SB(1, 1), b3 + hstepB, voffB); PG8_STAGE(PG8_SA(1, 0), a3, voffA);
;             PG8_WAIT_V(8); PG8_WAIT_L(0); PG8_BAR; PG8_MMA(1, 0, At, B0); PG8_MMA(1, 1, At, B1); PG8_BAR; PG8_SCHED;
;         }
	s_add_i32 s56, s61, s65
	v_lshl_add_u64 v[204:205], v[204:205], 0, s[2:3]
	s_mov_b32 m0, s56
	ds_read_b128 v[160:163], v220 offset:49152
	ds_read_b128 v[164:167], v220 offset:50176
	ds_read_b128 v[180:183], v220 offset:51200
	ds_read_b128 v[184:187], v220 offset:52224
	ds_read_b128 v[188:191], v220 offset:53248
	ds_read_b128 v[194:197], v220 offset:54272
	ds_read_b128 v[200:203], v220 offset:55296
	ds_read_b128 v[222:225], v220 offset:56320
	global_load_lds_dwordx4 v[204:205], off
	s_add_i32 m0, s56, 0x2000
	s_add_u32 s54, s54, 0x40080
	v_lshl_add_u64 v[204:205], v[226:227], 0, s[2:3]
	s_addc_u32 s55, s55, 0
	s_add_i32 s56, s74, s65
	global_load_lds_dwordx4 v[204:205], off
	v_lshl_add_u64 v[204:205], s[54:55], 0, v[170:171]
	s_mov_b32 m0, s56
	s_nop 0
	global_load_lds_dwordx4 v[204:205], off
	v_lshl_add_u64 v[204:205], s[54:55], 0, v[174:175]
	s_add_i32 m0, s56, 0x2000
	s_nop 0
	global_load_lds_dwordx4 v[204:205], off
	v_lshl_add_u64 v[204:205], v[228:229], 0, s[2:3]
	s_mov_b32 m0, s70
	s_nop 0
	global_load_lds_dwordx4 v[204:205], off
	v_lshl_add_u64 v[204:205], v[230:231], 0, s[2:3]
	s_mov_b32 m0, s71
	s_nop 0
	global_load_lds_dwordx4 v[204:205], off
	s_waitcnt vmcnt(8) lgkmcnt(0)
	s_barrier
	v_mfma_f32_16x16x32_bf16 v[60:63], v[128:131], v[160:163], v[60:63]
	v_mfma_f32_16x16x32_bf16 v[28:31], v[136:139], v[160:163], v[28:31]
	v_mfma_f32_16x16x32_bf16 v[52:55], v[128:131], v[180:183], v[52:55]
	v_mfma_f32_16x16x32_bf16 v[20:23], v[136:139], v[180:183], v[20:23]
	v_mfma_f32_16x16x32_bf16 v[44:47], v[128:131], v[188:191], v[44:47]
	v_mfma_f32_16x16x32_bf16 v[12:15], v[136:139], v[188:191], v[12:15]
	v_mfma_f32_16x16x32_bf16 v[36:39], v[128:131], v[200:203], v[36:39]
	v_mfma_f32_16x16x32_bf16 v[4:7], v[136:139], v[200:203], v[4:7]
	v_mfma_f32_16x16x32_bf16 v[60:63], v[132:135], v[164:167], v[60:63]
	v_mfma_f32_16x16x32_bf16 v[28:31], v[140:143], v[164:167], v[28:31]
	v_mfma_f32_16x16x32_bf16 v[52:55], v[132:135], v[184:187], v[52:55]
	v_mfma_f32_16x16x32_bf16 v[20:23], v[140:143], v[184:187], v[20:23]
	v_mfma_f32_16x16x32_bf16 v[44:47], v[132:135], v[194:197], v[44:47]
	v_mfma_f32_16x16x32_bf16 v[12:15], v[140:143], v[194:197], v[12:15]
	v_mfma_f32_16x16x32_bf16 v[36:39], v[132:135], v[222:225], v[36:39]
	v_mfma_f32_16x16x32_bf16 v[4:7], v[140:143], v[222:225], v[4:7]
	v_mfma_f32_16x16x32_bf16 v[56:59], v[144:147], v[160:163], v[56:59]
	v_mfma_f32_16x16x32_bf16 v[24:27], v[152:155], v[160:163], v[24:27]
	v_mfma_f32_16x16x32_bf16 v[48:51], v[144:147], v[180:183], v[48:51]
	v_mfma_f32_16x16x32_bf16 v[16:19], v[152:155], v[180:183], v[16:19]
	v_mfma_f32_16x16x32_bf16 v[40:43], v[144:147], v[188:191], v[40:43]
	v_mfma_f32_16x16x32_bf16 v[8:11], v[152:155], v[188:191], v[8:11]
	v_mfma_f32_16x16x32_bf16 v[32:35], v[144:147], v[200:203], v[32:35]
	v_mfma_f32_16x16x32_bf16 v[0:3], v[152:155], v[200:203], v[0:3]
	v_mfma_f32_16x16x32_bf16 v[56:59], v[148:151], v[164:167], v[56:59]
	v_mfma_f32_16x16x32_bf16 v[24:27], v[156:159], v[164:167], v[24:27]
	v_mfma_f32_16x16x32_bf16 v[48:51], v[148:151], v[184:187], v[48:51]
	v_mfma_f32_16x16x32_bf16 v[16:19], v[156:159], v[184:187], v[16:19]
	v_mfma_f32_16x16x32_bf16 v[40:43], v[148:151], v[194:197], v[40:43]
	v_mfma_f32_16x16x32_bf16 v[8:11], v[156:159], v[194:197], v[8:11]
	v_mfma_f32_16x16x32_bf16 v[32:35], v[148:151], v[222:225], v[32:35]
	v_mfma_f32_16x16x32_bf16 v[0:3], v[156:159], v[222:225], v[0:3]
	s_barrier
	s_add_i32 s60, s60, 2
	s_add_u32 s58, s58, 0x100
	s_addc_u32 s59, s59, 0
	s_add_u32 s28, s28, 0x100
	s_addc_u32 s29, s29, 0
	s_cmp_gt_u32 s60, 13
	s_cbranch_scc0 .LBB0_811
	s_and_b64 vcc, exec, s[42:43]
	s_cbranch_vccz .LBB0_814
	s_barrier

; #define PG8_STAGE(bufoff, gbase, voff) do { _Pragma("unroll") for (int _i = 0; _i < 2; ++_i) \
;         __builtin_amdgcn_global_load_lds((const unsigned*)((const char*)(gbase) + (voff)[_i]), (LAS unsigned*)(lds + (bufoff) + ldsw + _i * 8192), 16, 0, 0); } while (0)
; #define PG8_LDA(dst, b, h) do { _Pragma("unroll") for (int m = 0; m < 4; ++m) _Pragma("unroll") for (int k = 0; k < 2; ++k) dst[m][k] = *(const LAS bf16x8*)(lds + PG8_SA(b, h) + aoff + m * 2048 + k * 1024); } while (0)
; #define PG8_LDB(dst, b, h) do { _Pragma("unroll") for (int n = 0; n < 2; ++n) _Pragma("unroll") for (int k = 0; k < 2; ++k) dst[n][k] = *(const LAS bf16x8*)(lds + PG8_SB(b, h) + boff + n * 2048 + k * 1024); } while (0)
; #define PG8_MMA(ai, bj, At, Bt) do { __builtin_amdgcn_s_setprio(1); _Pragma("unroll") for (int m = 0; m < 4; ++m) _Pragma("unroll") for (int n = 0; n < 2; ++n) _Pragma("unroll") for (int k = 0; k < 2; ++k) \
;         acc[ai][bj][m][n] = __builtin_amdgcn_mfma_f32_16x16x32_bf16(Bt[n][k], At[m][k], acc[ai][bj][m][n], 0, 0, 0); __builtin_amdgcn_s_setprio(0); } while (0)
; #define PG8_WAIT_V(n) asm volatile("s_waitcnt vmcnt(" #n ")" ::: "memory")
; #define PG8_WAIT_L(n) asm volatile("s_waitcnt lgkmcnt(" #n ")" ::: "memory")
; #define PG8_BAR __builtin_amdgcn_s_barrier()
; #define PG8_SCHED __builtin_amdgcn_sched_barrier(0)
; template <class Epi>
; DI void gemm_phase(int wv, LAS unsigned char* lds, LAS unsigned char* scr, const Sched& S, const Epi& E) {
;     ...
;             const bool last = (t == nt - 2);
;             const char* a1 = cA + (size_t)(t + 1) * kstep;
;             const char* a2 = last ? nA : cA + (size_t)(t + 2) * kstep; const char* b2 = last ? nB : cB + (size_t)(t + 2) * kstep;
;             const char* a3 = a2 + kstep; const char* b3 = b2 + kstep;
;             PG8_LDB(B0, 0, 0); PG8_LDB(B1, 0, 1); PG8_SCHED; PG8_LDA(At, 0, 0); PG8_STAGE(PG8_SA(1, 1), a1 + hstepA, voffA);
;             PG8_WAIT_V(8); PG8_WAIT_L(0); PG8_BAR; PG8_MMA(0, 0, At, B0); PG8_MMA(0, 1, At, B1); PG8_BAR; PG8_SCHED;
;             PG8_LDA(At, 0, 1); PG8_STAGE(PG8_SB(0, 0), b2, voffB); PG8_STAGE(PG8_SB(0, 1), b2 + hstepB, voffB); PG8_STAGE(PG8_SA(0, 0), a2, voffA);
.LBB0_936:
	s_add_u32 s30, s28, 0x100
	s_addc_u32 s31, s29, 0
	s_add_i32 s69, 0, 0x10000
	s_cmp_eq_u32 s68, 40
	s_cselect_b32 s37, s9, s31
	s_cselect_b32 s36, s8, s30
	s_cselect_b32 s35, s23, s27
	s_cselect_b32 s34, s22, s25
	s_add_i32 s70, 0, 0x14000
	v_add_u32_e32 v156, s69, v142
	v_add_u32_e32 v172, s70, v142
	ds_read_b128 v[144:147], v156
	ds_read_b128 v[148:151], v156 offset:1024
	ds_read_b128 v[152:155], v156 offset:2048
	ds_read_b128 v[156:159], v156 offset:3072
	ds_read_b128 v[160:163], v172
	ds_read_b128 v[164:167], v172 offset:1024
	ds_read_b128 v[168:171], v172 offset:2048
	ds_read_b128 v[172:175], v172 offset:3072
	v_lshl_add_u64 v[210:211], s[28:29], 0, v[140:141]
	s_add_i32 m0, s57, 0xc000
	ds_read_b128 v[176:179], v143
	ds_read_b128 v[180:183], v143 offset:1024
	ds_read_b128 v[184:187], v143 offset:2048
	ds_read_b128 v[188:191], v143 offset:3072
	ds_read_b128 v[194:197], v143 offset:4096
	ds_read_b128 v[198:201], v143 offset:5120
	ds_read_b128 v[202:205], v143 offset:6144
	ds_read_b128 v[206:209], v143 offset:7168
	global_load_lds_dwordx4 v[210:211], off
	v_lshl_add_u64 v[210:211], s[28:29], 0, v[138:139]
	s_add_i32 m0, s57, 0xe000
	s_nop 0
	global_load_lds_dwordx4 v[210:211], off
	s_waitcnt vmcnt(8) lgkmcnt(0)
	s_barrier
	v_mfma_f32_16x16x32_bf16 v[124:127], v[144:147], v[176:179], v[124:127]
	v_mfma_f32_16x16x32_bf16 v[120:123], v[152:155], v[176:179], v[120:123]
	v_mfma_f32_16x16x32_bf16 v[116:119], v[144:147], v[184:187], v[116:119]
	v_mfma_f32_16x16x32_bf16 v[112:115], v[152:155], v[184:187], v[112:115]
	v_mfma_f32_16x16x32_bf16 v[100:103], v[144:147], v[194:197], v[100:103]
	v_mfma_f32_16x16x32_bf16 v[96:99], v[152:155], v[194:197], v[96:99]
	v_mfma_f32_16x16x32_bf16 v[84:87], v[144:147], v[202:205], v[84:87]
	v_mfma_f32_16x16x32_bf16 v[80:83], v[152:155], v[202:205], v[80:83]
	v_mfma_f32_16x16x32_bf16 v[124:127], v[148:151], v[180:183], v[124:127]
	v_mfma_f32_16x16x32_bf16 v[120:123], v[156:159], v[180:183], v[120:123]
	v_mfma_f32_16x16x32_bf16 v[116:119], v[148:151], v[188:191], v[116:119]
	v_mfma_f32_16x16x32_bf16 v[112:115], v[156:159], v[188:191], v[112:115]
	v_mfma_f32_16x16x32_bf16 v[100:103], v[148:151], v[198:201], v[100:103]
	v_mfma_f32_16x16x32_bf16 v[96:99], v[156:159], v[198:201], v[96:99]
	v_mfma_f32_16x16x32_bf16 v[84:87], v[148:151], v[206:209], v[84:87]
	v_mfma_f32_16x16x32_bf16 v[80:83], v[156:159], v[206:209], v[80:83]
	v_mfma_f32_16x16x32_bf16 v[108:111], v[160:163], v[176:179], v[108:111]
	v_mfma_f32_16x16x32_bf16 v[104:107], v[168:171], v[176:179], v[104:107]
	v_mfma_f32_16x16x32_bf16 v[92:95], v[160:163], v[184:187], v[92:95]
	v_mfma_f32_16x16x32_bf16 v[88:91], v[168:171], v[184:187], v[88:91]
	v_mfma_f32_16x16x32_bf16 v[76:79], v[160:163], v[194:197], v[76:79]
	v_mfma_f32_16x16x32_bf16 v[72:75], v[168:171], v[194:197], v[72:75]
	v_mfma_f32_16x16x32_bf16 v[68:71], v[160:163], v[202:205], v[68:71]
	v_mfma_f32_16x16x32_bf16 v[64:67], v[168:171], v[202:205], v[64:67]
	v_mfma_f32_16x16x32_bf16 v[108:111], v[164:167], v[180:183], v[108:111]
	v_mfma_f32_16x16x32_bf16 v[104:107], v[172:175], v[180:183], v[104:107]
	v_mfma_f32_16x16x32_bf16 v[92:95], v[164:167], v[188:191], v[92:95]
	v_mfma_f32_16x16x32_bf16 v[88:91], v[172:175], v[188:191], v[88:91]
	v_mfma_f32_16x16x32_bf16 v[76:79], v[164:167], v[198:201], v[76:79]
	v_mfma_f32_16x16x32_bf16 v[72:75], v[172:175], v[198:201], v[72:75]
	v_mfma_f32_16x16x32_bf16 v[68:71], v[164:167], v[206:209], v[68:71]
	v_mfma_f32_16x16x32_bf16 v[64:67], v[172:175], v[206:209], v[64:67]
	s_barrier
	s_add_i32 s28, s69, s56
	v_lshl_add_u64 v[210:211], s[34:35], 0, v[132:133]
	s_mov_b32 m0, s28
	ds_read_b128 v[176:179], v143 offset:16384
	ds_read_b128 v[180:183], v143 offset:17408
	ds_read_b128 v[184:187], v143 offset:18432
	ds_read_b128 v[188:191], v143 offset:19456
	ds_read_b128 v[194:197], v143 offset:20480
	ds_read_b128 v[198:201], v143 offset:21504
	ds_read_b128 v[202:205], v143 offset:22528
	ds_read_b128 v[206:209], v143 offset:23552
	global_load_lds_dwordx4 v[210:211], off
	s_add_i32 m0, s28, 0x2000
	s_add_u32 s28, s34, 0xb0000
	v_lshl_add_u64 v[212:213], s[34:35], 0, v[128:129]
	s_addc_u32 s29, s35, 0
	s_add_i32 s69, s70, s56
	global_load_lds_dwordx4 v[212:213], off
	v_lshl_add_u64 v[214:215], s[28:29], 0, v[132:133]
	s_mov_b32 m0, s69
	v_lshl_add_u64 v[216:217], s[36:37], 0, v[130:131]
	global_load_lds_dwordx4 v[214:215], off
	v_lshl_add_u64 v[214:215], s[28:29], 0, v[128:129]
	s_add_i32 m0, s69, 0x2000
	s_nop 0
	global_load_lds_dwordx4 v[214:215], off
	v_lshl_add_u64 v[214:215], s[36:37], 0, v[134:135]
	s_mov_b32 m0, s57
	s_nop 0
	global_load_lds_dwordx4 v[214:215], off
	s_mov_b32 m0, s58
	s_nop 0
	global_load_lds_dwordx4 v[216:217], off
	s_waitcnt vmcnt(8) lgkmcnt(0)
	s_barrier
; #define PG8_STAGE(bufoff, gbase, voff) do { _Pragma("unroll") for (int _i = 0; _i < 2; ++_i) \
;         __builtin_amdgcn_global_load_lds((const unsigned*)((const char*)(gbase) + (voff)[_i]), (LAS unsigned*)(lds + (bufoff) + ldsw + _i * 8192), 16, 0, 0); } while (0)
; #define PG8_LDA(dst, b, h) do { _Pragma("unroll") for (int m = 0; m < 4; ++m) _Pragma("unroll") for (int k = 0; k < 2; ++k) dst[m][k] = *(const LAS bf16x8*)(lds + PG8_SA(b, h) + aoff + m * 2048 + k * 1024); } while (0)
; #define PG8_LDB(dst, b, h) do { _Pragma("unroll") for (int n = 0; n < 2; ++n) _Pragma("unroll") for (int k = 0; k < 2; ++k) dst[n][k] = *(const LAS bf16x8*)(lds + PG8_SB(b, h) + boff + n * 2048 + k * 1024); } while (0)
; #define PG8_MMA(ai, bj, At, Bt) do { __builtin_amdgcn_s_setprio(1); _Pragma("unroll") for (int m = 0; m < 4; ++m) _Pragma("unroll") for (int n = 0; n < 2; ++n) _Pragma("unroll") for (int k = 0; k < 2; ++k) \
;         acc[ai][bj][m][n] = __builtin_amdgcn_mfma_f32_16x16x32_bf16(Bt[n][k], At[m][k], acc[ai][bj][m][n], 0, 0, 0); __builtin_amdgcn_s_setprio(0); } while (0)
; #define PG8_WAIT_V(n) asm volatile("s_waitcnt vmcnt(" #n ")" ::: "memory")
; #define PG8_WAIT_L(n) asm volatile("s_waitcnt lgkmcnt(" #n ")" ::: "memory")
; #define PG8_BAR __builtin_amdgcn_s_barrier()
; #define PG8_SCHED __builtin_amdgcn_sched_barrier(0)
; template <class Epi>
; DI void gemm_phase(int wv, LAS unsigned char* lds, LAS unsigned char* scr, const Sched& S, const Epi& E) {
;     ...
;             PG8_WAIT_V(8); PG8_WAIT_L(0); PG8_BAR; PG8_MMA(1, 0, At, B0); PG8_MMA(1, 1, At, B1); PG8_BAR; PG8_SCHED;
;             PG8_LDB(B0, 1, 0); PG8_LDB(B1, 1, 1); PG8_SCHED; PG8_LDA(At, 1, 0); PG8_STAGE(PG8_SA(0, 1), a2 + hstepA, voffA);
;             PG8_WAIT_V(8); PG8_WAIT_L(0); PG8_BAR; PG8_MMA(0, 0, At, B0); PG8_MMA(0, 1, At, B1); PG8_BAR; PG8_SCHED;
	v_mfma_f32_16x16x32_bf16 v[60:63], v[144:147], v[176:179], v[60:63]
	v_mfma_f32_16x16x32_bf16 v[56:59], v[152:155], v[176:179], v[56:59]
	v_mfma_f32_16x16x32_bf16 v[52:55], v[144:147], v[184:187], v[52:55]
	v_mfma_f32_16x16x32_bf16 v[48:51], v[152:155], v[184:187], v[48:51]
	v_mfma_f32_16x16x32_bf16 v[36:39], v[144:147], v[194:197], v[36:39]
	v_mfma_f32_16x16x32_bf16 v[32:35], v[152:155], v[194:197], v[32:35]
	v_mfma_f32_16x16x32_bf16 v[20:23], v[144:147], v[202:205], v[20:23]
	v_mfma_f32_16x16x32_bf16 v[16:19], v[152:155], v[202:205], v[16:19]
	v_mfma_f32_16x16x32_bf16 v[60:63], v[148:151], v[180:183], v[60:63]
	v_mfma_f32_16x16x32_bf16 v[56:59], v[156:159], v[180:183], v[56:59]
	v_mfma_f32_16x16x32_bf16 v[52:55], v[148:151], v[188:191], v[52:55]
	v_mfma_f32_16x16x32_bf16 v[48:51], v[156:159], v[188:191], v[48:51]
	v_mfma_f32_16x16x32_bf16 v[36:39], v[148:151], v[198:201], v[36:39]
	v_mfma_f32_16x16x32_bf16 v[32:35], v[156:159], v[198:201], v[32:35]
	v_mfma_f32_16x16x32_bf16 v[20:23], v[148:151], v[206:209], v[20:23]
	v_mfma_f32_16x16x32_bf16 v[16:19], v[156:159], v[206:209], v[16:19]
	v_mfma_f32_16x16x32_bf16 v[44:47], v[160:163], v[176:179], v[44:47]
	v_mfma_f32_16x16x32_bf16 v[40:43], v[168:171], v[176:179], v[40:43]
	v_mfma_f32_16x16x32_bf16 v[28:31], v[160:163], v[184:187], v[28:31]
	v_mfma_f32_16x16x32_bf16 v[24:27], v[168:171], v[184:187], v[24:27]
	v_mfma_f32_16x16x32_bf16 v[12:15], v[160:163], v[194:197], v[12:15]
	v_mfma_f32_16x16x32_bf16 v[8:11], v[168:171], v[194:197], v[8:11]
	v_mfma_f32_16x16x32_bf16 v[4:7], v[160:163], v[202:205], v[4:7]
	v_mfma_f32_16x16x32_bf16 v[0:3], v[168:171], v[202:205], v[0:3]
	v_mfma_f32_16x16x32_bf16 v[44:47], v[164:167], v[180:183], v[44:47]
	v_mfma_f32_16x16x32_bf16 v[40:43], v[172:175], v[180:183], v[40:43]
	v_mfma_f32_16x16x32_bf16 v[28:31], v[164:167], v[188:191], v[28:31]
	v_mfma_f32_16x16x32_bf16 v[24:27], v[172:175], v[188:191], v[24:27]
	v_mfma_f32_16x16x32_bf16 v[12:15], v[164:167], v[198:201], v[12:15]
	v_mfma_f32_16x16x32_bf16 v[8:11], v[172:175], v[198:201], v[8:11]
	v_mfma_f32_16x16x32_bf16 v[4:7], v[164:167], v[206:209], v[4:7]
	v_mfma_f32_16x16x32_bf16 v[0:3], v[172:175], v[206:209], v[0:3]
	s_barrier
	s_add_i32 s69, 0, 0x18000
	s_add_i32 s70, 0, 0x1c000
	v_add_u32_e32 v156, s69, v142
	v_add_u32_e32 v172, s70, v142
	ds_read_b128 v[144:147], v156
	ds_read_b128 v[148:151], v156 offset:1024
	ds_read_b128 v[152:155], v156 offset:2048
	ds_read_b128 v[156:159], v156 offset:3072
	ds_read_b128 v[160:163], v172
	ds_read_b128 v[164:167], v172 offset:1024
	ds_read_b128 v[168:171], v172 offset:2048
	ds_read_b128 v[172:175], v172 offset:3072
	s_add_u32 s28, s36, 0xb0000
	s_addc_u32 s29, s37, 0
	s_mov_b32 m0, s59
	v_lshl_add_u64 v[218:219], s[28:29], 0, v[134:135]
	ds_read_b128 v[176:179], v143 offset:32768
	ds_read_b128 v[180:183], v143 offset:33792
	ds_read_b128 v[184:187], v143 offset:34816
	ds_read_b128 v[188:191], v143 offset:35840
	ds_read_b128 v[194:197], v143 offset:36864
	ds_read_b128 v[198:201], v143 offset:37888
	ds_read_b128 v[202:205], v143 offset:38912
	ds_read_b128 v[206:209], v143 offset:39936
	global_load_lds_dwordx4 v[218:219], off
	v_lshl_add_u64 v[218:219], s[28:29], 0, v[130:131]
	s_mov_b32 m0, s60
	s_nop 0
	global_load_lds_dwordx4 v[218:219], off
	s_waitcnt vmcnt(8) lgkmcnt(0)
	s_barrier
	v_mfma_f32_16x16x32_bf16 v[124:127], v[144:147], v[176:179], v[124:127]
	v_mfma_f32_16x16x32_bf16 v[120:123], v[152:155], v[176:179], v[120:123]
	v_mfma_f32_16x16x32_bf16 v[116:119], v[144:147], v[184:187], v[116:119]
	v_mfma_f32_16x16x32_bf16 v[112:115], v[152:155], v[184:187], v[112:115]
	v_mfma_f32_16x16x32_bf16 v[100:103], v[144:147], v[194:197], v[100:103]
	v_mfma_f32_16x16x32_bf16 v[96:99], v[152:155], v[194:197], v[96:99]
	v_mfma_f32_16x16x32_bf16 v[84:87], v[144:147], v[202:205], v[84:87]
	v_mfma_f32_16x16x32_bf16 v[80:83], v[152:155], v[202:205], v[80:83]
	v_mfma_f32_16x16x32_bf16 v[124:127], v[148:151], v[180:183], v[124:127]
	v_mfma_f32_16x16x32_bf16 v[120:123], v[156:159], v[180:183], v[120:123]
	v_mfma_f32_16x16x32_bf16 v[116:119], v[148:151], v[188:191], v[116:119]
	v_mfma_f32_16x16x32_bf16 v[112:115], v[156:159], v[188:191], v[112:115]
	v_mfma_f32_16x16x32_bf16 v[100:103], v[148:151], v[198:201], v[100:103]
	v_mfma_f32_16x16x32_bf16 v[96:99], v[156:159], v[198:201], v[96:99]
	v_mfma_f32_16x16x32_bf16 v[84:87], v[148:151], v[206:209], v[84:87]
	v_mfma_f32_16x16x32_bf16 v[80:83], v[156:159], v[206:209], v[80:83]
	v_mfma_f32_16x16x32_bf16 v[108:111], v[160:163], v[176:179], v[108:111]
	v_mfma_f32_16x16x32_bf16 v[104:107], v[168:171], v[176:179], v[104:107]
	v_mfma_f32_16x16x32_bf16 v[92:95], v[160:163], v[184:187], v[92:95]
	v_mfma_f32_16x16x32_bf16 v[88:91], v[168:171], v[184:187], v[88:91]
	v_mfma_f32_16x16x32_bf16 v[76:79], v[160:163], v[194:197], v[76:79]
	v_mfma_f32_16x16x32_bf16 v[72:75], v[168:171], v[194:197], v[72:75]
	v_mfma_f32_16x16x32_bf16 v[68:71], v[160:163], v[202:205], v[68:71]
	v_mfma_f32_16x16x32_bf16 v[64:67], v[168:171], v[202:205], v[64:67]
	v_mfma_f32_16x16x32_bf16 v[108:111], v[164:167], v[180:183], v[108:111]
	v_mfma_f32_16x16x32_bf16 v[104:107], v[172:175], v[180:183], v[104:107]
	v_mfma_f32_16x16x32_bf16 v[92:95], v[164:167], v[188:191], v[92:95]
	v_mfma_f32_16x16x32_bf16 v[88:91], v[172:175], v[188:191], v[88:91]
	v_mfma_f32_16x16x32_bf16 v[76:79], v[164:167], v[198:201], v[76:79]
	v_mfma_f32_16x16x32_bf16 v[72:75], v[172:175], v[198:201], v[72:75]
	v_mfma_f32_16x16x32_bf16 v[68:71], v[164:167], v[206:209], v[68:71]
	v_mfma_f32_16x16x32_bf16 v[64:67], v[172:175], v[206:209], v[64:67]
	s_barrier
; #define PG8_STAGE(bufoff, gbase, voff) do { _Pragma("unroll") for (int _i = 0; _i < 2; ++_i) \
;         __builtin_amdgcn_global_load_lds((const unsigned*)((const char*)(gbase) + (voff)[_i]), (LAS unsigned*)(lds + (bufoff) + ldsw + _i * 8192), 16, 0, 0); } while (0)
; #define PG8_LDA(dst, b, h) do { _Pragma("unroll") for (int m = 0; m < 4; ++m) _Pragma("unroll") for (int k = 0; k < 2; ++k) dst[m][k] = *(const LAS bf16x8*)(lds + PG8_SA(b, h) + aoff + m * 2048 + k * 1024); } while (0)
; #define PG8_MMA(ai, bj, At, Bt) do { __builtin_amdgcn_s_setprio(1); _Pragma("unroll") for (int m = 0; m < 4; ++m) _Pragma("unroll") for (int n = 0; n < 2; ++n) _Pragma("unroll") for (int k = 0; k < 2; ++k) \
;         acc[ai][bj][m][n] = __builtin_amdgcn_mfma_f32_16x16x32_bf16(Bt[n][k], At[m][k], acc[ai][bj][m][n], 0, 0, 0); __builtin_amdgcn_s_setprio(0); } while (0)
; #define PG8_WAIT_V(n) asm volatile("s_waitcnt vmcnt(" #n ")" ::: "memory")
; #define PG8_WAIT_L(n) asm volatile("s_waitcnt lgkmcnt(" #n ")" ::: "memory")
; #define PG8_BAR __builtin_amdgcn_s_barrier()
; #define PG8_SCHED __builtin_amdgcn_sched_barrier(0)
; template <class Epi>
; DI void gemm_phase(int wv, LAS unsigned char* lds, LAS unsigned char* scr, const Sched& S, const Epi& E) {
;     ...
;             PG8_LDA(At, 1, 1); PG8_STAGE(PG8_SB(1, 0), b3, voffB); PG8_STAGE(PG8_SB(1, 1), b3 + hstepB, voffB); PG8_STAGE(PG8_SA(1, 0), a3, voffA);
;             PG8_WAIT_V(8); PG8_WAIT_L(0); PG8_BAR; PG8_MMA(1, 0, At, B0); PG8_MMA(1, 1, At, B1); PG8_BAR; PG8_SCHED;
;         }
	s_add_i32 s28, s69, s56
	v_lshl_add_u64 v[210:211], v[210:211], 0, s[2:3]
	s_mov_b32 m0, s28
	ds_read_b128 v[176:179], v143 offset:49152
	ds_read_b128 v[180:183], v143 offset:50176
	ds_read_b128 v[184:187], v143 offset:51200
	ds_read_b128 v[188:191], v143 offset:52224
	ds_read_b128 v[194:197], v143 offset:53248
	ds_read_b128 v[198:201], v143 offset:54272
	ds_read_b128 v[202:205], v143 offset:55296
	ds_read_b128 v[206:209], v143 offset:56320
	global_load_lds_dwordx4 v[210:211], off
	s_add_i32 m0, s28, 0x2000
	s_add_u32 s28, s34, 0xb0080
	v_lshl_add_u64 v[210:211], v[212:213], 0, s[2:3]
	s_addc_u32 s29, s35, 0
	s_add_i32 s34, s70, s56
	global_load_lds_dwordx4 v[210:211], off
	v_lshl_add_u64 v[210:211], s[28:29], 0, v[132:133]
	s_mov_b32 m0, s34
	s_nop 0
	global_load_lds_dwordx4 v[210:211], off
	v_lshl_add_u64 v[210:211], s[28:29], 0, v[128:129]
	s_add_i32 m0, s34, 0x2000
	s_nop 0
	global_load_lds_dwordx4 v[210:211], off
	v_lshl_add_u64 v[210:211], v[214:215], 0, s[2:3]
	s_mov_b32 m0, s63
	s_nop 0
	global_load_lds_dwordx4 v[210:211], off
	v_lshl_add_u64 v[210:211], v[216:217], 0, s[2:3]
	s_mov_b32 m0, s64
	s_nop 0
	global_load_lds_dwordx4 v[210:211], off
	s_waitcnt vmcnt(8) lgkmcnt(0)
	s_barrier
	v_mfma_f32_16x16x32_bf16 v[60:63], v[144:147], v[176:179], v[60:63]
	v_mfma_f32_16x16x32_bf16 v[56:59], v[152:155], v[176:179], v[56:59]
	v_mfma_f32_16x16x32_bf16 v[52:55], v[144:147], v[184:187], v[52:55]
	v_mfma_f32_16x16x32_bf16 v[48:51], v[152:155], v[184:187], v[48:51]
	v_mfma_f32_16x16x32_bf16 v[36:39], v[144:147], v[194:197], v[36:39]
	v_mfma_f32_16x16x32_bf16 v[32:35], v[152:155], v[194:197], v[32:35]
	v_mfma_f32_16x16x32_bf16 v[20:23], v[144:147], v[202:205], v[20:23]
	v_mfma_f32_16x16x32_bf16 v[16:19], v[152:155], v[202:205], v[16:19]
	v_mfma_f32_16x16x32_bf16 v[60:63], v[148:151], v[180:183], v[60:63]
	v_mfma_f32_16x16x32_bf16 v[56:59], v[156:159], v[180:183], v[56:59]
	v_mfma_f32_16x16x32_bf16 v[52:55], v[148:151], v[188:191], v[52:55]
	v_mfma_f32_16x16x32_bf16 v[48:51], v[156:159], v[188:191], v[48:51]
	v_mfma_f32_16x16x32_bf16 v[36:39], v[148:151], v[198:201], v[36:39]
	v_mfma_f32_16x16x32_bf16 v[32:35], v[156:159], v[198:201], v[32:35]
	v_mfma_f32_16x16x32_bf16 v[20:23], v[148:151], v[206:209], v[20:23]
	v_mfma_f32_16x16x32_bf16 v[16:19], v[156:159], v[206:209], v[16:19]
	v_mfma_f32_16x16x32_bf16 v[44:47], v[160:163], v[176:179], v[44:47]
	v_mfma_f32_16x16x32_bf16 v[40:43], v[168:171], v[176:179], v[40:43]
	v_mfma_f32_16x16x32_bf16 v[28:31], v[160:163], v[184:187], v[28:31]
	v_mfma_f32_16x16x32_bf16 v[24:27], v[168:171], v[184:187], v[24:27]
	v_mfma_f32_16x16x32_bf16 v[12:15], v[160:163], v[194:197], v[12:15]
	v_mfma_f32_16x16x32_bf16 v[8:11], v[168:171], v[194:197], v[8:11]
	v_mfma_f32_16x16x32_bf16 v[4:7], v[160:163], v[202:205], v[4:7]
	v_mfma_f32_16x16x32_bf16 v[0:3], v[168:171], v[202:205], v[0:3]
	v_mfma_f32_16x16x32_bf16 v[44:47], v[164:167], v[180:183], v[44:47]
	v_mfma_f32_16x16x32_bf16 v[40:43], v[172:175], v[180:183], v[40:43]
	v_mfma_f32_16x16x32_bf16 v[28:31], v[164:167], v[188:191], v[28:31]
	v_mfma_f32_16x16x32_bf16 v[24:27], v[172:175], v[188:191], v[24:27]
	v_mfma_f32_16x16x32_bf16 v[12:15], v[164:167], v[198:201], v[12:15]
	v_mfma_f32_16x16x32_bf16 v[8:11], v[172:175], v[198:201], v[8:11]
	v_mfma_f32_16x16x32_bf16 v[4:7], v[164:167], v[206:209], v[4:7]
	v_mfma_f32_16x16x32_bf16 v[0:3], v[172:175], v[206:209], v[0:3]
	s_barrier
	s_add_i32 s68, s68, 2
	s_add_u32 s25, s25, 0x100
	s_addc_u32 s27, s27, 0
	s_cmp_gt_u32 s68, 41
	s_mov_b64 s[28:29], s[30:31]
	s_cbranch_scc0 .LBB0_936
	s_and_b64 vcc, exec, s[20:21]
	s_cbranch_vccz .LBB0_939
	s_barrier
